# second combination: previous combination + GEMM1 scale loads at the unit head, out-GEMM stat-load hoist with counted waits, direct barrier polling, gate cross-unit wait relaxation
# speedup vs baseline: 1.0124x; 1.0043x over previous
; __device__ __forceinline__ unsigned xb_ld(unsigned* p)              { return __hip_atomic_load(p, __ATOMIC_RELAXED, __HIP_MEMORY_SCOPE_AGENT); }
; __device__ __forceinline__ unsigned xb_add(unsigned* p, unsigned v) { return __hip_atomic_fetch_add(p, v, __ATOMIC_RELAXED, __HIP_MEMORY_SCOPE_AGENT); }
; #define XB_SPIN(cond, bar) do { unsigned _sp = 0; while (cond) { __builtin_amdgcn_s_sleep(1); \
;     if ((++_sp & 255u) == 0u) { if (xb_ld(&(bar)[XB_TMO])) break; if (_sp > XB_SPIN_CAP) { atomicAdd(&(bar)[XB_TMO], 1u); break; } } } } while (0)
; __device__ __forceinline__ void xcd_barrier(const XcdBarrier& b) {
;     asm volatile("s_waitcnt vmcnt(0)" ::: "memory");
;     __syncthreads();
;     if (threadIdx.x == 0) {
;         unsigned* bar = b.bar;
;         __builtin_amdgcn_s_waitcnt(0);
;         unsigned nloc = b.st[0], nx = b.st[1];
;         if (nloc == 0u) { xcd_barrier_complete(bar, b.x, nloc, nx); b.st[0] = nloc; b.st[1] = nx; }
;         const unsigned old = xb_add(&bar[XB_XSUB(b.x)], 1u);
;         const unsigned gen = old / nloc;
;         if (old + 1u == (gen + 1u) * nloc) {
;             __builtin_amdgcn_fence(__ATOMIC_RELEASE, "agent");
;             asm volatile("s_waitcnt vmcnt(0)" ::: "memory");
;             const unsigned og = xb_add(&bar[XB_TOP], 1u);
;             const unsigned tg = og / nx;
;             if (og + 1u == (tg + 1u) * nx) xb_add(&bar[XB_TOPGEN], 1u);
;             else XB_SPIN(xb_ld(&bar[XB_TOPGEN]) == tg, bar);
;             __builtin_amdgcn_fence(__ATOMIC_ACQUIRE, "agent");
;             xb_add(&bar[XB_XGEN(b.x)], 1u);
;             asm volatile("s_waitcnt vmcnt(0)" ::: "memory");
;         } else {
;             XB_SPIN(xb_ld(&bar[XB_XGEN(b.x)]) == gen, bar);
;             __builtin_amdgcn_fence(__ATOMIC_ACQUIRE, "agent");
;             asm volatile("s_waitcnt vmcnt(0)" ::: "memory");
;         }
.LBB0_88:
	s_or_b64 exec, exec, s[6:7]
	v_cvt_f32_u32_e32 v5, v3
	s_waitcnt vmcnt(0)
	v_readfirstlane_b32 s2, v4
	v_sub_u32_e32 v4, 0, v3
	v_rcp_iflag_f32_e32 v5, v5
	v_add_u32_e32 v6, s2, v2
	v_mul_f32_e32 v5, 0x4f7ffffe, v5
	v_cvt_u32_f32_e32 v5, v5
	v_mul_lo_u32 v2, v4, v5
	v_mul_hi_u32 v2, v5, v2
	v_add_u32_e32 v2, v5, v2
	v_mul_hi_u32 v2, v6, v2
	v_mul_lo_u32 v4, v2, v3
	v_sub_u32_e32 v4, v6, v4
	v_add_u32_e32 v5, 1, v2
	v_cmp_ge_u32_e32 vcc, v4, v3
	s_nop 1
	v_cndmask_b32_e32 v2, v2, v5, vcc
	v_sub_u32_e32 v5, v4, v3
	v_cndmask_b32_e32 v4, v4, v5, vcc
	v_add_u32_e32 v5, 1, v2
	v_cmp_ge_u32_e32 vcc, v4, v3
	v_add_u32_e32 v4, 1, v6
	s_nop 0
	v_cndmask_b32_e32 v2, v2, v5, vcc
	v_mul_lo_u32 v5, v3, v2
	v_add_u32_e32 v3, v5, v3
	v_cmp_ne_u32_e32 vcc, v4, v3
	s_and_saveexec_b64 s[2:3], vcc
	s_xor_b64 s[2:3], exec, s[2:3]
	s_cbranch_execz .LBB0_102
	s_waitcnt lgkmcnt(0)
	v_mov_b32_e32 v1, 0x3100
	global_load_dword v1, v1, s[84:85] offset:1024 sc1
	s_add_u32 s8, s84, 0x3500
	s_addc_u32 s9, s85, 0
	s_waitcnt vmcnt(0)
	v_cmp_eq_u32_e32 vcc, v1, v2
	s_and_saveexec_b64 s[6:7], vcc
	s_cbranch_execz .LBB0_101
	s_mov_b32 s20, 1
	s_mov_b64 s[10:11], 0
	v_mov_b32_e32 v1, 0
	s_branch .LBB0_92

;     __device__ __forceinline__ void pre(Pre& p, const Unit& u, int wr, int wc, int lane) const {
;         const int fr = lane & 15, fq = lane >> 4, row0 = u.pm * BM + wr * 64 + fr, col0 = u.pn * BM + wc * 32 + 8 * fq;
; #pragma unroll
;         for (int bj = 0; bj < 2; ++bj)
; #pragma unroll
;             for (int n = 0; n < 2; ++n) p.wv[bj][n] = *(const f32x4*)(SW + col0 + bj * HALF + 4 * n);
; #pragma unroll
;         for (int i = 0; i < 8; ++i) p.rs[i] = SH[row0 + (i >> 2) * HALF + (i & 3) * 16];
;     }
; template <class Epi, class Sched, class Gemm, bool ALIGN_EPI = false, bool SP2 = false>
; __device__ __forceinline__ void gemm_phase(PG8_LAS unsigned char* lds, const Gemm g, const Sched& S, const Epi& E) {
;     ...
;         if constexpr (!epi_chain<Epi>::value) {
; #pragma unroll
;         for (int a = 0; a < 2; ++a)
; #pragma unroll
;             for (int b = 0; b < 2; ++b)
; #pragma unroll
;                 for (int m = 0; m < 4; ++m)
; #pragma unroll
;                     for (int n = 0; n < 2; ++n) acc[a][b][m][n] = (f32x4){0.f, 0.f, 0.f, 0.f};
;         }
;         cur = nxt; cA = nA; cB = nB; ++ui;
.LBB0_134:
	s_ashr_i32 s43, s42, 31
	s_lshl_b64 s[44:45], s[42:43], 18
	s_add_u32 s44, s60, s44
	s_addc_u32 s45, s61, s45
	s_and_b64 s[46:47], s[4:5], exec
	s_cselect_b32 s7, s45, s3
	s_cselect_b32 s43, s44, s2
	s_ashr_i32 s41, s40, 31
	s_lshl_b64 s[46:47], s[40:41], 18
	s_add_u32 s46, s62, s46
	s_addc_u32 s47, s63, s47
	s_and_b64 s[50:51], s[4:5], exec
	s_cselect_b32 s79, s47, s49
	s_cselect_b32 s80, s46, s48
	s_lshl_b32 s33, s0, 8
	s_lshl_b32 s41, s6, 8
	v_or_b32_e32 v18, s41, v252
	v_or_b32_e32 v20, s70, v1
	s_add_u32 s81, s48, 0x100
	v_ashrrev_i32_e32 v19, 31, v18
	v_add_u32_e32 v20, s33, v20
	s_addc_u32 s82, s49, 0
	v_ashrrev_i32_e32 v21, 31, v20
	v_lshl_add_u64 v[238:239], v[18:19], 2, s[34:35]
	s_add_u32 s48, s2, 0x20080
	v_mov_b32_e32 v18, 0
	v_lshl_add_u64 v[240:241], v[20:21], 2, s[30:31]
	global_load_dwordx4 v[2:5], v[238:239], off offset:16
	global_load_dwordx4 v[6:9], v[238:239], off
	global_load_dwordx4 v[10:13], v[238:239], off offset:528
	global_load_dwordx4 v[14:17], v[238:239], off offset:512
	global_load_dword v226, v[240:241], off
	global_load_dword v228, v[240:241], off offset:64
	global_load_dword v230, v[240:241], off offset:128
	global_load_dword v232, v[240:241], off offset:192
	global_load_dword v234, v[240:241], off offset:512
	global_load_dword v235, v[240:241], off offset:576
	global_load_dword v236, v[240:241], off offset:640
	global_load_dword v237, v[240:241], off offset:704
	s_addc_u32 s49, s3, 0
	s_mov_b32 s2, -2
	v_mov_b32_e32 v19, v18
	v_mov_b64_e32 v[20:21], 0
	v_mov_b64_e32 v[22:23], 0
	v_mov_b64_e32 v[24:25], 0
	v_mov_b64_e32 v[34:35], 0
	v_mov_b64_e32 v[36:37], 0
	v_mov_b64_e32 v[38:39], 0
	v_mov_b64_e32 v[40:41], 0
	v_mov_b64_e32 v[50:51], 0
	v_mov_b64_e32 v[52:53], 0
	v_mov_b64_e32 v[54:55], 0
	v_mov_b64_e32 v[56:57], 0
	v_mov_b64_e32 v[66:67], 0
	v_mov_b64_e32 v[68:69], 0
	v_mov_b64_e32 v[70:71], 0
	v_mov_b64_e32 v[72:73], 0
	v_mov_b64_e32 v[26:27], 0
	v_mov_b64_e32 v[28:29], 0
	v_mov_b64_e32 v[30:31], 0
	v_mov_b64_e32 v[32:33], 0
	v_mov_b64_e32 v[42:43], 0
	v_mov_b64_e32 v[44:45], 0
	v_mov_b64_e32 v[46:47], 0
	v_mov_b64_e32 v[48:49], 0
	v_mov_b64_e32 v[58:59], 0
	v_mov_b64_e32 v[60:61], 0
	v_mov_b64_e32 v[62:63], 0
	v_mov_b64_e32 v[64:65], 0
	v_mov_b64_e32 v[74:75], 0
	v_mov_b64_e32 v[76:77], 0
	v_mov_b64_e32 v[78:79], 0
	v_mov_b64_e32 v[80:81], 0
	v_mov_b64_e32 v[82:83], 0
	v_mov_b64_e32 v[84:85], 0
	v_mov_b64_e32 v[86:87], 0
	v_mov_b64_e32 v[88:89], 0
	v_mov_b64_e32 v[98:99], 0
	v_mov_b64_e32 v[100:101], 0
	v_mov_b64_e32 v[102:103], 0
	v_mov_b64_e32 v[104:105], 0
	v_mov_b64_e32 v[114:115], 0
	v_mov_b64_e32 v[116:117], 0
	v_mov_b64_e32 v[118:119], 0
	v_mov_b64_e32 v[120:121], 0
	v_mov_b64_e32 v[130:131], 0
	v_mov_b64_e32 v[132:133], 0
	v_mov_b64_e32 v[134:135], 0
	v_mov_b64_e32 v[136:137], 0
	v_mov_b64_e32 v[90:91], 0
	v_mov_b64_e32 v[92:93], 0
	v_mov_b64_e32 v[94:95], 0
	v_mov_b64_e32 v[96:97], 0
	v_mov_b64_e32 v[106:107], 0
	v_mov_b64_e32 v[108:109], 0
	v_mov_b64_e32 v[110:111], 0
	v_mov_b64_e32 v[112:113], 0
	v_mov_b64_e32 v[122:123], 0
	v_mov_b64_e32 v[124:125], 0
	v_mov_b64_e32 v[126:127], 0
	v_mov_b64_e32 v[128:129], 0
	v_mov_b64_e32 v[138:139], 0
	v_mov_b64_e32 v[140:141], 0
	v_mov_b64_e32 v[142:143], 0
	v_mov_b64_e32 v[144:145], 0
	s_nop 0
	s_branch .LBB0_136

; __device__ __forceinline__ unsigned cvt_pk_bf16(float lo, float hi) { return ::pk2(lo, hi); }
;     __device__ __forceinline__ void operator()(const f32x4 (&acc)[2][2][4][2], const Pre& p, const Unit& u, int wr, int wc, int fr, int fq) const {
;         asm volatile("" : "+v"(fr), "+v"(fq));
;         const int row0 = u.pm * BM + wr * 64 + fr, col0 = u.pn * BM + wc * 32 + 8 * fq;
;         const bool glu = (u.pn * BM >= ZB) && (u.pn * BM < ZQ);
; #pragma unroll
;         for (int ai = 0; ai < 2; ++ai)
; #pragma unroll
;             for (int m = 0; m < 4; ++m) { bf16_t* rowp = O + (size_t)(row0 + ai * HALF + m * 16) * ldc;
;                 const float rs = p.rs[ai * 4 + m];
; #pragma unroll
;                 for (int bj = 0; bj < 2; ++bj) {
;                     const f32x4 v0 = (__builtin_convertvector(__builtin_bit_cast(i32x4, acc[ai][bj][m][0]), f32x4) * p.wv[bj][0]) * rs, v1 = (__builtin_convertvector(__builtin_bit_cast(i32x4, acc[ai][bj][m][1]), f32x4) * p.wv[bj][1]) * rs;
;                     if (glu) {
;                         const float o0 = v0[0] * __builtin_amdgcn_rcpf(1.f + __builtin_amdgcn_exp2f(v0[1] * -1.44269504f)), o1 = v0[2] * __builtin_amdgcn_rcpf(1.f + __builtin_amdgcn_exp2f(v0[3] * -1.44269504f));
;                         const float o2 = v1[0] * __builtin_amdgcn_rcpf(1.f + __builtin_amdgcn_exp2f(v1[1] * -1.44269504f)), o3 = v1[2] * __builtin_amdgcn_rcpf(1.f + __builtin_amdgcn_exp2f(v1[3] * -1.44269504f));
;                         u32x2 w; w.x = cvt_pk_bf16(o0, o1); w.y = cvt_pk_bf16(o2, o3);
;                         *(u32x2*)(rowp + ZB + ((col0 + bj * HALF - ZB) >> 1)) = w;
;                     } else {
;                         u32x4 w; w.x = cvt_pk_bf16(v0[0], v0[1]); w.y = cvt_pk_bf16(v0[2], v0[3]); w.z = cvt_pk_bf16(v1[0], v1[1]); w.w = cvt_pk_bf16(v1[2], v1[3]);
;                         *(u32x4*)(rowp + col0 + bj * HALF) = w; } } }
.LBB0_140:
	v_mov_b32_e32 v147, v1
	v_mov_b32_e32 v146, v250
	s_or_b32 s0, s41, s71
	v_lshl_add_u32 v146, v146, 3, s0
	s_add_i32 s0, s6, -1
	v_cvt_f32_i32_e32 v153, v145
	v_cvt_f32_i32_e32 v152, v144
	s_cmp_gt_u32 s0, 1
	s_cselect_b64 s[0:1], -1, 0
	s_add_i32 s33, s33, s70
	v_add_u32_e32 v154, s33, v147
	v_mov_b64_e32 v[148:149], s[28:29]
	v_cvt_f32_i32_e32 v151, v143
	v_cvt_f32_i32_e32 v150, v142
	v_mad_i64_i32 v[142:143], s[2:3], v154, s78, v[148:149]
	s_waitcnt vmcnt(8)
	v_pk_mul_f32 v[148:149], v[8:9], v[152:153]
	v_cvt_f32_i32_e32 v139, v139
	v_cvt_f32_i32_e32 v153, v141
	v_cvt_f32_i32_e32 v152, v140
	v_cvt_f32_i32_e32 v138, v138
	v_pk_mul_f32 v[150:151], v[6:7], v[150:151]
	v_ashrrev_i32_e32 v147, 31, v146
	v_pk_mul_f32 v[140:141], v[148:149], v[226:227] op_sel_hi:[1,0]
	v_pk_mul_f32 v[148:149], v[150:151], v[226:227] op_sel_hi:[1,0]
	v_pk_mul_f32 v[150:151], v[4:5], v[152:153]
	v_pk_mul_f32 v[138:139], v[2:3], v[138:139]
	v_lshl_add_u64 v[144:145], v[146:147], 1, v[142:143]
	v_pk_mul_f32 v[152:153], v[150:151], v[226:227] op_sel_hi:[1,0]
	v_pk_mul_f32 v[150:151], v[138:139], v[226:227] op_sel_hi:[1,0]
	s_mov_b64 s[2:3], -1
	s_and_b64 vcc, exec, s[0:1]
	v_readlane_b32 s88, v255, 5
	s_cbranch_vccnz .Lg1plain_0
	s_nop 0
	s_cbranch_vccz .LBB0_142
	v_cvt_pk_bf16_f32 v156, v148, v149
	v_cvt_pk_bf16_f32 v157, v140, v141
	v_cvt_pk_bf16_f32 v158, v150, v151
	v_cvt_pk_bf16_f32 v159, v152, v153
	global_store_dwordx4 v[144:145], v[156:159], off
	s_mov_b64 s[2:3], 0

; #define TIDX opq((int)threadIdx.x)
; #define PG8_STAGE(bufoff, gbase, voff) do { _Pragma("unroll") for (int _i = 0; _i < 2; ++_i) \
;         __builtin_amdgcn_global_load_lds((const unsigned*)((const char*)(gbase) + (voff)[_i]), (PG8_LAS unsigned*)(lds + (bufoff) + ldsw + _i * 8192), 16, 0, 0); } while (0)
; #define PG8_WAIT_V(n) asm volatile("s_waitcnt vmcnt(" #n ")" ::: "memory")
; #define PG8_BAR __builtin_amdgcn_s_barrier()
; template <class Epi, class Sched, class Gemm, bool ALIGN_EPI = false, bool SP2 = false>
; __device__ __forceinline__ void gemm_phase(PG8_LAS unsigned char* lds, const Gemm g, const Sched& S, const Epi& E) {
;     const int tid = TIDX, wid = __builtin_amdgcn_readfirstlane(tid >> 6), lane = tid & 63, wr = wid >> 2, wc = wid & 3, fr = lane & 15, fq = lane >> 4;
;     constexpr int K = Gemm::K, nt = K / BK, lda = Gemm::lda, ldb = Gemm::ldb;
;     constexpr int BP = epi_bperm<Epi>::value;
;     unsigned voffA[2], voffB[2], voffB1[2];
; #pragma unroll
;     for (int i = 0; i < 2; ++i) { int R, C; stage_rc(tid * 16 + i * 8192, R, C);
;         voffA[i] = (unsigned)(R * lda + C) * 2u;
;         if constexpr (BP == 2) { const int w_ = R >> 5, n_ = (R >> 4) & 1, j_ = R & 15, cb_ = w_ * 64 + 16 * (j_ >> 2) + 4 * n_ + (j_ & 3);
;             voffB[i] = (unsigned)(cb_ * ldb + C) * 2u; voffB1[i] = voffB[i]; }
;         else { const int Rb = (BP == 1) ? ((R & ~31) + perm32(R & 31)) : R; voffB[i] = (unsigned)(Rb * ldb + C) * 2u; voffB1[i] = voffB[i]; } }
;     const size_t kstep = (size_t)(BK * 2);
;     const size_t hstepA = (size_t)HALF * lda * 2, hstepB = (size_t)HALF * ldb * 2, hB1 = (BP == 2) ? (size_t)8 * ldb * 2 : hstepB;
;     const size_t tstepA = 2 * hstepA, tstepB = 2 * hstepB;
;     const unsigned ldsw = (unsigned)wid * 1024u;
;     const int aoff = lds_byte(wr * 64 + fr, fq * 8), boff = lds_byte(wc * 32 + fr, fq * 8);
;     ...
;     if constexpr (SP2) {
;         PG8_STAGE(PG8_SB(0, 0), cB, voffB); PG8_STAGE(PG8_SB(0, 1), cB + hB1, voffB1); PG8_STAGE(PG8_SA(0, 0), cA, voffA); PG8_STAGE(PG8_SA(0, 1), cA + hstepA, voffA);
;         if (wr == 1) PG8_BAR;
;         PG8_WAIT_V(2); PG8_BAR;
;         PG8_STAGE(PG8_SB(1, 0), cB + kstep, voffB); PG8_STAGE(PG8_SA(1, 0), cA + kstep, voffA); PG8_STAGE(PG8_SB(1, 1), cB + hB1 + kstep, voffB1);
;         PG8_WAIT_V(6); PG8_BAR;
.LBB0_1182:
	s_and_b32 s22, s16, 3
	s_lshl_b32 s50, s17, 6
	s_lshl_b32 s24, s17, 13
	s_lshl_b32 s26, s22, 12
	s_add_u32 s16, s14, 0x1dd08000
	s_addc_u32 s17, s15, 0
	s_add_u32 s14, s14, 0x1dd28000
	s_mov_b64 s[18:19], 0x80
	s_addc_u32 s15, s15, 0
	s_add_i32 m0, s39, 0x18000
	v_lshl_add_u64 v[8:9], v[8:9], 0, s[18:19]
	s_waitcnt vmcnt(2)
	s_barrier
	global_load_lds_dwordx4 v[8:9], off
	v_lshl_add_u64 v[6:7], v[6:7], 0, s[18:19]
	s_add_i32 m0, s39, 0x1a000
	s_add_i32 s51, s39, 0x8000
	s_add_i32 s52, s39, 0xa000
	global_load_lds_dwordx4 v[6:7], off
	v_lshl_add_u64 v[2:3], v[2:3], 0, s[18:19]
	s_mov_b32 m0, s51
	s_add_u32 s20, s0, 0x2080
	global_load_lds_dwordx4 v[2:3], off
	v_lshl_add_u64 v[2:3], v[4:5], 0, s[18:19]
	s_mov_b32 m0, s52
	s_addc_u32 s21, s1, 0
	global_load_lds_dwordx4 v[2:3], off
	s_add_i32 m0, s39, 0x1c000
	v_lshl_add_u64 v[2:3], s[20:21], 0, v[148:149]
	global_load_lds_dwordx4 v[2:3], off
	v_lshl_add_u64 v[2:3], s[20:21], 0, v[152:153]
	s_add_i32 m0, s39, 0x1e000
	v_bfe_u32 v179, v10, 4, 2
	global_load_lds_dwordx4 v[2:3], off
	v_and_b32_e32 v1, 15, v10
	v_lshlrev_b32_e32 v2, 4, v179
	v_lshlrev_b32_e32 v3, 2, v10
	v_lshl_or_b32 v2, v1, 6, v2
	v_and_b32_e32 v3, 32, v3
	v_bitop3_b32 v4, v2, s24, v3 bitop3:0xde
	v_bitop3_b32 v181, v2, s26, v3 bitop3:0xde
	v_lshlrev_b32_e32 v2, 13, v14
	v_and_b32_e32 v2, 0xffffc000, v2
	v_lshl_add_u32 v2, v15, 10, v2
	v_and_b32_e32 v3, 1, v14
	v_lshl_or_b32 v2, v3, 6, v2
	v_lshl_add_u32 v156, v16, 1, v2
	v_lshlrev_b32_e32 v2, 13, v11
	v_and_b32_e32 v2, 0xffffc000, v2
	s_waitcnt vmcnt(6)
	s_cmpk_lt_u32 s5, 0x100
	v_lshl_add_u32 v2, v12, 10, v2
	v_and_b32_e32 v3, 1, v11
	s_cselect_b64 s[20:21], -1, 0
	v_lshl_or_b32 v2, v3, 6, v2
	s_add_i32 s55, 0, 0x10000
	s_add_i32 s56, 0, 0x14000
	s_sext_i32_i8 s59, s4
	s_lshl_b32 s53, s22, 6
	s_ashr_i32 s54, s23, 31
	v_mov_b32_e32 v157, v155
	v_lshl_add_u32 v158, v13, 1, v2
	v_mov_b32_e32 v159, v155
	v_mov_b64_e32 v[252:253], 0x800
	v_add_u32_e32 v183, s55, v181
	v_add_u32_e32 v185, s56, v181
	v_add_u32_e32 v187, 0, v4
	s_mov_b32 s22, 0xbfb8aa3b
	s_movk_i32 s57, 0x2200
	s_mov_b32 s24, 0x4b000000
	s_mov_b32 s26, 0x437f0000
	s_mov_b32 s58, 0xc0c0400
	s_barrier
	s_waitcnt vmcnt(0)
	s_nop 0
	s_branch .LBB0_1185

;     __device__ bool next(int i, Unit& u) const { const bool ok = StaticOrder::next(i >> 2, u); u.sub = i & 3; return ok; }
; #define PG8_STAGE(bufoff, gbase, voff) do { _Pragma("unroll") for (int _i = 0; _i < 2; ++_i) \
;         __builtin_amdgcn_global_load_lds((const unsigned*)((const char*)(gbase) + (voff)[_i]), (PG8_LAS unsigned*)(lds + (bufoff) + ldsw + _i * 8192), 16, 0, 0); } while (0)
; #define PG8_LDA(dst, b, h) do { _Pragma("unroll") for (int m = 0; m < 4; ++m) _Pragma("unroll") for (int k = 0; k < 2; ++k) dst[m][k] = *(const PG8_LAS bf16x8*)(lds + PG8_SA(b, h) + aoff + m * 2048 + k * 1024); } while (0)
; #define PG8_WAIT_V(n) asm volatile("s_waitcnt vmcnt(" #n ")" ::: "memory")
; #define PG8_WAIT_L(n) asm volatile("s_waitcnt lgkmcnt(" #n ")" ::: "memory")
; #define PG8_BAR __builtin_amdgcn_s_barrier()
; template <class Epi, class Sched, class Gemm, bool ALIGN_EPI = false, bool SP2 = false>
; __device__ __forceinline__ void gemm_phase(PG8_LAS unsigned char* lds, const Gemm g, const Sched& S, const Epi& E) {
;     ...
;         const bool has_next = S.next(ui + 1, nxt);
;         const char* nA = has_next ? (const char*)g.A + (size_t)nxt.pm * tstepA + (size_t)nxt.sub * g.a_sub : cA; const char* nB = has_next ? (const char*)g.Bt + (size_t)nxt.pn * tstepB + (size_t)nxt.sub * g.b_sub : cB;
;         for (int t = 0; t < nt; t += 2) {
;             const bool last = (t == nt - 2);
;             const char* a1 = cA + (size_t)(t + 1) * kstep;
;             const char* a2 = last ? nA : cA + (size_t)(t + 2) * kstep; const char* b2 = last ? nB : cB + (size_t)(t + 2) * kstep;
;             const char* a3 = a2 + kstep; const char* b3 = b2 + kstep;
;             if (last && has_next) S.a_ready(nxt);
;             if constexpr (SP2) {
;             PG8_LDB(B0, 0, 0); PG8_LDB(B1, 0, 1); PG8_SCHED; PG8_LDA(At, 0, 0); PG8_STAGE(PG8_SA(1, 1), a1 + hstepA, voffA);
;             PG8_WAIT_V(8); PG8_WAIT_L(0); PG8_BAR; PG8_MMA(0, 0, At, B0); PG8_MMA(0, 1, At, B1); PG8_BAR; PG8_SCHED;
;     ...
;         if constexpr (!epi_chain<Epi>::value) {
; #pragma unroll
;         for (int a = 0; a < 2; ++a)
; #pragma unroll
;             for (int b = 0; b < 2; ++b)
; #pragma unroll
;                 for (int m = 0; m < 4; ++m)
; #pragma unroll
;                     for (int n = 0; n < 2; ++n) acc[a][b][m][n] = (f32x4){0.f, 0.f, 0.f, 0.f};
;         }
;         cur = nxt; cA = nA; cB = nB; ++ui;
.LBB0_1191:
	s_ashr_i32 s31, s30, 31
	s_lshl_b64 s[34:35], s[30:31], 18
	s_add_u32 s34, s44, s34
	s_addc_u32 s35, s45, s35
	s_and_b64 s[36:37], s[4:5], exec
	s_cselect_b32 s31, s35, s3
	s_cselect_b32 s60, s34, s2
	s_ashr_i32 s29, s28, 31
	s_lshl_b64 s[36:37], s[28:29], 18
	s_add_u32 s36, s42, s36
	s_addc_u32 s37, s43, s37
	s_and_b64 s[40:41], s[4:5], exec
	s_cselect_b32 s29, s37, s1
	s_cselect_b32 s61, s36, s0
	s_add_u32 s62, s0, 0x100
	s_addc_u32 s63, s1, 0
	s_add_u32 s0, s2, 0x20080
	v_mov_b32_e32 v2, 0
	s_addc_u32 s1, s3, 0
	s_mov_b32 s64, -2
	v_mov_b32_e32 v3, v2
	v_mov_b32_e32 v4, v2
	v_mov_b32_e32 v5, v2
	v_mov_b32_e32 v6, v2
	v_mov_b32_e32 v7, v2
	v_mov_b32_e32 v8, v2
	v_mov_b32_e32 v9, v2
	s_nop 0
	v_mov_b64_e32 v[18:19], 0
	v_mov_b64_e32 v[20:21], 0
	v_mov_b64_e32 v[22:23], 0
	v_mov_b64_e32 v[24:25], 0
	v_mov_b64_e32 v[34:35], 0
	v_mov_b64_e32 v[36:37], 0
	v_mov_b64_e32 v[38:39], 0
	v_mov_b64_e32 v[40:41], 0
	v_mov_b64_e32 v[50:51], 0
	v_mov_b64_e32 v[52:53], 0
	v_mov_b64_e32 v[54:55], 0
	v_mov_b64_e32 v[56:57], 0
	v_mov_b64_e32 v[10:11], 0
	v_mov_b64_e32 v[12:13], 0
	v_mov_b64_e32 v[14:15], 0
	v_mov_b64_e32 v[16:17], 0
	v_mov_b64_e32 v[26:27], 0
	v_mov_b64_e32 v[28:29], 0
	v_mov_b64_e32 v[30:31], 0
	v_mov_b64_e32 v[32:33], 0
	v_mov_b64_e32 v[42:43], 0
	v_mov_b64_e32 v[44:45], 0
	v_mov_b64_e32 v[46:47], 0
	v_mov_b64_e32 v[48:49], 0
	v_mov_b64_e32 v[58:59], 0
	v_mov_b64_e32 v[60:61], 0
	v_mov_b64_e32 v[62:63], 0
	v_mov_b64_e32 v[64:65], 0
	v_mov_b64_e32 v[66:67], 0
	v_mov_b64_e32 v[68:69], 0
	v_mov_b64_e32 v[70:71], 0
	v_mov_b64_e32 v[72:73], 0
	v_mov_b64_e32 v[82:83], 0
	v_mov_b64_e32 v[84:85], 0
	v_mov_b64_e32 v[86:87], 0
	v_mov_b64_e32 v[88:89], 0
	v_mov_b64_e32 v[98:99], 0
	v_mov_b64_e32 v[100:101], 0
	v_mov_b64_e32 v[102:103], 0
	v_mov_b64_e32 v[104:105], 0
	v_mov_b64_e32 v[114:115], 0
	v_mov_b64_e32 v[116:117], 0
	v_mov_b64_e32 v[118:119], 0
	v_mov_b64_e32 v[120:121], 0
	v_mov_b64_e32 v[74:75], 0
	v_mov_b64_e32 v[76:77], 0
	v_mov_b64_e32 v[78:79], 0
	v_mov_b64_e32 v[80:81], 0
	v_mov_b64_e32 v[90:91], 0
	v_mov_b64_e32 v[92:93], 0
	v_mov_b64_e32 v[94:95], 0
	v_mov_b64_e32 v[96:97], 0
	v_mov_b64_e32 v[106:107], 0
	v_mov_b64_e32 v[108:109], 0
	v_mov_b64_e32 v[110:111], 0
	v_mov_b64_e32 v[112:113], 0
	v_mov_b64_e32 v[122:123], 0
	v_mov_b64_e32 v[124:125], 0
	v_mov_b64_e32 v[126:127], 0
	v_mov_b64_e32 v[128:129], 0
	s_mov_b64 vcc, -1
.LBB0_1192:
	ds_read_b128 v[172:175], v183
	ds_read_b128 v[188:191], v183 offset:1024
	ds_read_b128 v[192:195], v183 offset:2048
	ds_read_b128 v[196:199], v183 offset:3072
	ds_read_b128 v[134:137], v185
	ds_read_b128 v[138:141], v185 offset:1024
	ds_read_b128 v[142:145], v185 offset:2048
	ds_read_b128 v[130:133], v185 offset:3072
	s_add_u32 s2, s0, 0xfffe0080
	s_addc_u32 s3, s1, -1
	s_cmp_eq_u32 s64, 4
	s_cselect_b32 s3, s31, s3
	s_cselect_b32 s2, s60, s2
	s_cselect_b32 s41, s29, s63
	s_cselect_b32 s40, s61, s62
	v_lshl_add_u64 v[160:161], s[0:1], 0, v[158:159]
	s_add_i32 m0, s39, 0xc000
	ds_read_b128 v[164:167], v187
	ds_read_b128 v[168:171], v187 offset:1024
	ds_read_b128 v[200:203], v187 offset:2048
	ds_read_b128 v[204:207], v187 offset:3072
	ds_read_b128 v[208:211], v187 offset:4096
	ds_read_b128 v[212:215], v187 offset:5120
	ds_read_b128 v[216:219], v187 offset:6144
	ds_read_b128 v[220:223], v187 offset:7168
	global_load_lds_dwordx4 v[160:161], off
	v_lshl_add_u64 v[160:161], s[0:1], 0, v[156:157]
	s_add_i32 m0, s39, 0xe000
	s_nop 0
	global_load_lds_dwordx4 v[160:161], off
	s_cbranch_vccnz .Lfw_0
	s_waitcnt vmcnt(8)
.Lfw_0:
	s_waitcnt lgkmcnt(0)
	s_barrier
	s_setprio 1
	s_waitcnt lgkmcnt(0)
	v_mfma_i32_16x16x64_i8 v[224:227], v[172:175], v[164:167], v[126:129]
	v_mfma_i32_16x16x64_i8 v[126:129], v[188:191], v[168:171], v[224:227]
	v_mfma_i32_16x16x64_i8 v[228:231], v[192:195], v[164:167], v[122:125]
	v_mfma_i32_16x16x64_i8 v[232:235], v[172:175], v[200:203], v[110:113]
	v_mfma_i32_16x16x64_i8 v[236:239], v[192:195], v[200:203], v[106:109]
	v_mfma_i32_16x16x64_i8 v[240:243], v[172:175], v[208:211], v[94:97]
	v_mfma_i32_16x16x64_i8 v[244:247], v[192:195], v[208:211], v[90:93]
	v_mfma_i32_16x16x64_i8 v[224:227], v[172:175], v[216:219], v[78:81]
	v_mfma_i32_16x16x64_i8 v[74:77], v[192:195], v[216:219], v[74:77]
	v_mfma_i32_16x16x64_i8 v[122:125], v[196:199], v[168:171], v[228:231]
	v_mfma_i32_16x16x64_i8 v[110:113], v[188:191], v[204:207], v[232:235]
	v_mfma_i32_16x16x64_i8 v[106:109], v[196:199], v[204:207], v[236:239]
	v_mfma_i32_16x16x64_i8 v[94:97], v[188:191], v[212:215], v[240:243]
	v_mfma_i32_16x16x64_i8 v[90:93], v[196:199], v[212:215], v[244:247]
	v_mfma_i32_16x16x64_i8 v[78:81], v[188:191], v[220:223], v[224:227]
	v_mfma_i32_16x16x64_i8 v[74:77], v[196:199], v[220:223], v[74:77]
	s_setprio 0
	s_setprio 1
	v_mfma_i32_16x16x64_i8 v[224:227], v[134:137], v[164:167], v[118:121]
	v_mfma_i32_16x16x64_i8 v[118:121], v[138:141], v[168:171], v[224:227]
	v_mfma_i32_16x16x64_i8 v[228:231], v[142:145], v[164:167], v[114:117]
	v_mfma_i32_16x16x64_i8 v[232:235], v[134:137], v[200:203], v[102:105]
	v_mfma_i32_16x16x64_i8 v[236:239], v[142:145], v[200:203], v[98:101]
	v_mfma_i32_16x16x64_i8 v[240:243], v[134:137], v[208:211], v[86:89]
	v_mfma_i32_16x16x64_i8 v[244:247], v[142:145], v[208:211], v[82:85]
	v_mfma_i32_16x16x64_i8 v[164:167], v[134:137], v[216:219], v[70:73]
	v_mfma_i32_16x16x64_i8 v[66:69], v[142:145], v[216:219], v[66:69]
	v_mfma_i32_16x16x64_i8 v[114:117], v[130:133], v[168:171], v[228:231]
	v_mfma_i32_16x16x64_i8 v[102:105], v[138:141], v[204:207], v[232:235]
	v_mfma_i32_16x16x64_i8 v[98:101], v[130:133], v[204:207], v[236:239]
	v_mfma_i32_16x16x64_i8 v[86:89], v[138:141], v[212:215], v[240:243]
	v_mfma_i32_16x16x64_i8 v[82:85], v[130:133], v[212:215], v[244:247]
	v_mfma_i32_16x16x64_i8 v[70:73], v[138:141], v[220:223], v[164:167]
	v_mfma_i32_16x16x64_i8 v[66:69], v[130:133], v[220:223], v[66:69]
	s_setprio 0
	s_barrier
; #define PG8_STAGE(bufoff, gbase, voff) do { _Pragma("unroll") for (int _i = 0; _i < 2; ++_i) \
;         __builtin_amdgcn_global_load_lds((const unsigned*)((const char*)(gbase) + (voff)[_i]), (PG8_LAS unsigned*)(lds + (bufoff) + ldsw + _i * 8192), 16, 0, 0); } while (0)
; #define PG8_LDA(dst, b, h) do { _Pragma("unroll") for (int m = 0; m < 4; ++m) _Pragma("unroll") for (int k = 0; k < 2; ++k) dst[m][k] = *(const PG8_LAS bf16x8*)(lds + PG8_SA(b, h) + aoff + m * 2048 + k * 1024); } while (0)
; #define PG8_LDB(dst, b, h) do { _Pragma("unroll") for (int n = 0; n < 2; ++n) _Pragma("unroll") for (int k = 0; k < 2; ++k) dst[n][k] = *(const PG8_LAS bf16x8*)(lds + PG8_SB(b, h) + boff + n * 2048 + k * 1024); } while (0)
; #define PG8_MMA(ai, bj, At, Bt) do { __builtin_amdgcn_s_setprio(1); _Pragma("unroll") for (int m = 0; m < 4; ++m) _Pragma("unroll") for (int n = 0; n < 2; ++n) _Pragma("unroll") for (int k = 0; k < 2; ++k) \
;         acc[ai][bj][m][n] = Gemm::i8 ? ::mfma16i8_g(Bt[n][k], At[m][k], acc[ai][bj][m][n]) : ::mfma16_g(Bt[n][k], At[m][k], acc[ai][bj][m][n]); __builtin_amdgcn_s_setprio(0); } while (0)
; #define PG8_WAIT_V(n) asm volatile("s_waitcnt vmcnt(" #n ")" ::: "memory")
; #define PG8_WAIT_L(n) asm volatile("s_waitcnt lgkmcnt(" #n ")" ::: "memory")
; #define PG8_BAR __builtin_amdgcn_s_barrier()
; #define PG8_SCHED __builtin_amdgcn_sched_barrier(0)
; template <class Epi, class Sched, class Gemm, bool ALIGN_EPI = false, bool SP2 = false>
; __device__ __forceinline__ void gemm_phase(PG8_LAS unsigned char* lds, const Gemm g, const Sched& S, const Epi& E) {
;     ...
;             PG8_LDA(At, 0, 1); PG8_STAGE(PG8_SB(0, 0), b2, voffB); PG8_STAGE(PG8_SB(0, 1), b2 + hB1, voffB1); PG8_STAGE(PG8_SA(0, 0), a2, voffA);
;             PG8_WAIT_V(8); PG8_WAIT_L(0); PG8_BAR; PG8_MMA(1, 0, At, B0); PG8_MMA(1, 1, At, B1); PG8_BAR; PG8_SCHED;
;             PG8_LDB(B0, 1, 0); PG8_LDB(B1, 1, 1); PG8_SCHED; PG8_LDA(At, 1, 0); PG8_STAGE(PG8_SA(0, 1), a2 + hstepA, voffA);
;             PG8_WAIT_V(8); PG8_WAIT_L(0); PG8_BAR; PG8_MMA(0, 0, At, B0); PG8_MMA(0, 1, At, B1); PG8_BAR; PG8_SCHED;
	s_add_i32 s65, s55, s33
	v_lshl_add_u64 v[164:165], s[40:41], 0, v[148:149]
	s_mov_b32 m0, s65
	ds_read_b128 v[200:203], v187 offset:16384
	ds_read_b128 v[204:207], v187 offset:17408
	ds_read_b128 v[208:211], v187 offset:18432
	ds_read_b128 v[212:215], v187 offset:19456
	ds_read_b128 v[216:219], v187 offset:20480
	ds_read_b128 v[220:223], v187 offset:21504
	ds_read_b128 v[224:227], v187 offset:22528
	ds_read_b128 v[228:231], v187 offset:23552
	global_load_lds_dwordx4 v[164:165], off
	s_add_i32 m0, s65, 0x2000
	s_add_u32 s66, s40, 0x2000
	v_lshl_add_u64 v[166:167], s[40:41], 0, v[152:153]
	s_addc_u32 s67, s41, 0
	s_add_i32 s65, s56, s33
	global_load_lds_dwordx4 v[166:167], off
	v_lshl_add_u64 v[160:161], s[66:67], 0, v[148:149]
	s_mov_b32 m0, s65
	v_lshl_add_u64 v[168:169], s[2:3], 0, v[146:147]
	global_load_lds_dwordx4 v[160:161], off
	v_lshl_add_u64 v[160:161], s[66:67], 0, v[152:153]
	s_add_i32 m0, s65, 0x2000
	v_lshl_add_u64 v[170:171], s[2:3], 0, v[150:151]
	global_load_lds_dwordx4 v[160:161], off
	s_mov_b32 m0, s39
	s_nop 0
	global_load_lds_dwordx4 v[168:169], off
	s_mov_b32 m0, s46
	s_nop 0
	global_load_lds_dwordx4 v[170:171], off
	s_cbranch_vccnz .Lfw_1
	s_waitcnt vmcnt(8)
.Lfw_1:
	s_waitcnt lgkmcnt(0)
	s_barrier
	s_setprio 1
	s_waitcnt lgkmcnt(0)
	v_mfma_i32_16x16x64_i8 v[232:235], v[172:175], v[200:203], v[62:65]
	v_mfma_i32_16x16x64_i8 v[62:65], v[188:191], v[204:207], v[232:235]
	v_mfma_i32_16x16x64_i8 v[236:239], v[192:195], v[200:203], v[58:61]
	v_mfma_i32_16x16x64_i8 v[240:243], v[172:175], v[208:211], v[46:49]
	v_mfma_i32_16x16x64_i8 v[244:247], v[192:195], v[208:211], v[42:45]
	v_mfma_i32_16x16x64_i8 v[248:251], v[172:175], v[216:219], v[30:33]
	v_mfma_i32_16x16x64_i8 v[160:163], v[192:195], v[216:219], v[26:29]
	v_mfma_i32_16x16x64_i8 v[232:235], v[172:175], v[224:227], v[14:17]
	v_mfma_i32_16x16x64_i8 v[10:13], v[192:195], v[224:227], v[10:13]
	v_mfma_i32_16x16x64_i8 v[58:61], v[196:199], v[204:207], v[236:239]
	v_mfma_i32_16x16x64_i8 v[46:49], v[188:191], v[212:215], v[240:243]
	v_mfma_i32_16x16x64_i8 v[42:45], v[196:199], v[212:215], v[244:247]
	v_mfma_i32_16x16x64_i8 v[30:33], v[188:191], v[220:223], v[248:251]
	v_mfma_i32_16x16x64_i8 v[26:29], v[196:199], v[220:223], v[160:163]
	v_mfma_i32_16x16x64_i8 v[14:17], v[188:191], v[228:231], v[232:235]
	v_mfma_i32_16x16x64_i8 v[10:13], v[196:199], v[228:231], v[10:13]
	s_setprio 0
	s_setprio 1
	v_mfma_i32_16x16x64_i8 v[160:163], v[134:137], v[200:203], v[54:57]
	v_mfma_i32_16x16x64_i8 v[54:57], v[138:141], v[204:207], v[160:163]
	v_mfma_i32_16x16x64_i8 v[172:175], v[142:145], v[200:203], v[50:53]
	v_mfma_i32_16x16x64_i8 v[188:191], v[134:137], v[208:211], v[38:41]
	v_mfma_i32_16x16x64_i8 v[192:195], v[142:145], v[208:211], v[34:37]
	v_mfma_i32_16x16x64_i8 v[196:199], v[134:137], v[216:219], v[22:25]
	v_mfma_i32_16x16x64_i8 v[232:235], v[142:145], v[216:219], v[18:21]
	v_mfma_i32_16x16x64_i8 v[160:163], v[134:137], v[224:227], v[6:9]
	v_mfma_i32_16x16x64_i8 v[2:5], v[142:145], v[224:227], v[2:5]
	v_mfma_i32_16x16x64_i8 v[50:53], v[130:133], v[204:207], v[172:175]
	v_mfma_i32_16x16x64_i8 v[38:41], v[138:141], v[212:215], v[188:191]
	v_mfma_i32_16x16x64_i8 v[34:37], v[130:133], v[212:215], v[192:195]
	v_mfma_i32_16x16x64_i8 v[22:25], v[138:141], v[220:223], v[196:199]
	v_mfma_i32_16x16x64_i8 v[18:21], v[130:133], v[220:223], v[232:235]
	v_mfma_i32_16x16x64_i8 v[6:9], v[138:141], v[228:231], v[160:163]
	v_mfma_i32_16x16x64_i8 v[2:5], v[130:133], v[228:231], v[2:5]
	s_setprio 0
	s_barrier
	s_add_i32 s65, 0, 0x18000
	s_add_i32 s66, 0, 0x1c000
	v_add_u32_e32 v130, s65, v181
	v_add_u32_e32 v131, s66, v181
	ds_read_b128 v[160:163], v130
	ds_read_b128 v[172:175], v130 offset:1024
	ds_read_b128 v[188:191], v130 offset:2048
	ds_read_b128 v[192:195], v130 offset:3072
	ds_read_b128 v[134:137], v131
	ds_read_b128 v[138:141], v131 offset:1024
	ds_read_b128 v[142:145], v131 offset:2048
	ds_read_b128 v[130:133], v131 offset:3072
	s_add_u32 s2, s2, 0x20000
	s_addc_u32 s3, s3, 0
	s_mov_b32 m0, s47
	v_lshl_add_u64 v[176:177], s[2:3], 0, v[146:147]
	ds_read_b128 v[196:199], v187 offset:32768
	ds_read_b128 v[200:203], v187 offset:33792
	ds_read_b128 v[204:207], v187 offset:34816
	ds_read_b128 v[208:211], v187 offset:35840
	ds_read_b128 v[212:215], v187 offset:36864
	ds_read_b128 v[216:219], v187 offset:37888
	ds_read_b128 v[220:223], v187 offset:38912
	ds_read_b128 v[224:227], v187 offset:39936
	global_load_lds_dwordx4 v[176:177], off
	v_lshl_add_u64 v[176:177], s[2:3], 0, v[150:151]
	s_mov_b32 m0, s48
	s_nop 0
	global_load_lds_dwordx4 v[176:177], off
	s_waitcnt vmcnt(8)
	s_waitcnt lgkmcnt(0)
	s_barrier
; #define PG8_STAGE(bufoff, gbase, voff) do { _Pragma("unroll") for (int _i = 0; _i < 2; ++_i) \
;         __builtin_amdgcn_global_load_lds((const unsigned*)((const char*)(gbase) + (voff)[_i]), (PG8_LAS unsigned*)(lds + (bufoff) + ldsw + _i * 8192), 16, 0, 0); } while (0)
; #define PG8_LDA(dst, b, h) do { _Pragma("unroll") for (int m = 0; m < 4; ++m) _Pragma("unroll") for (int k = 0; k < 2; ++k) dst[m][k] = *(const PG8_LAS bf16x8*)(lds + PG8_SA(b, h) + aoff + m * 2048 + k * 1024); } while (0)
; #define PG8_MMA(ai, bj, At, Bt) do { __builtin_amdgcn_s_setprio(1); _Pragma("unroll") for (int m = 0; m < 4; ++m) _Pragma("unroll") for (int n = 0; n < 2; ++n) _Pragma("unroll") for (int k = 0; k < 2; ++k) \
;         acc[ai][bj][m][n] = Gemm::i8 ? ::mfma16i8_g(Bt[n][k], At[m][k], acc[ai][bj][m][n]) : ::mfma16_g(Bt[n][k], At[m][k], acc[ai][bj][m][n]); __builtin_amdgcn_s_setprio(0); } while (0)
; #define PG8_WAIT_V(n) asm volatile("s_waitcnt vmcnt(" #n ")" ::: "memory")
; #define PG8_WAIT_L(n) asm volatile("s_waitcnt lgkmcnt(" #n ")" ::: "memory")
; #define PG8_BAR __builtin_amdgcn_s_barrier()
; #define PG8_SCHED __builtin_amdgcn_sched_barrier(0)
; template <class Epi, class Sched, class Gemm, bool ALIGN_EPI = false, bool SP2 = false>
; __device__ __forceinline__ void gemm_phase(PG8_LAS unsigned char* lds, const Gemm g, const Sched& S, const Epi& E) {
;     ...
;             PG8_WAIT_V(8); PG8_WAIT_L(0); PG8_BAR; PG8_MMA(0, 0, At, B0); PG8_MMA(0, 1, At, B1); PG8_BAR; PG8_SCHED;
;             PG8_LDA(At, 1, 1); PG8_STAGE(PG8_SB(1, 0), b3, voffB); PG8_STAGE(PG8_SB(1, 1), b3 + hB1, voffB1); PG8_STAGE(PG8_SA(1, 0), a3, voffA);
;             PG8_WAIT_V(8);
;             if constexpr (epi_pre<Epi>::value) { if (last) E.pre(pre, cur, wr, wc, lane); }
;             PG8_WAIT_L(0); PG8_BAR; PG8_MMA(1, 0, At, B0); PG8_MMA(1, 1, At, B1); PG8_BAR; PG8_SCHED;
	s_setprio 1
	s_waitcnt lgkmcnt(0)
	v_mfma_i32_16x16x64_i8 v[228:231], v[160:163], v[196:199], v[126:129]
	v_mfma_i32_16x16x64_i8 v[126:129], v[172:175], v[200:203], v[228:231]
	v_mfma_i32_16x16x64_i8 v[232:235], v[188:191], v[196:199], v[122:125]
	v_mfma_i32_16x16x64_i8 v[236:239], v[160:163], v[204:207], v[110:113]
	v_mfma_i32_16x16x64_i8 v[240:243], v[188:191], v[204:207], v[106:109]
	v_mfma_i32_16x16x64_i8 v[244:247], v[160:163], v[212:215], v[94:97]
	v_mfma_i32_16x16x64_i8 v[248:251], v[188:191], v[212:215], v[90:93]
	v_mfma_i32_16x16x64_i8 v[228:231], v[160:163], v[220:223], v[78:81]
	v_mfma_i32_16x16x64_i8 v[74:77], v[188:191], v[220:223], v[74:77]
	v_mfma_i32_16x16x64_i8 v[122:125], v[192:195], v[200:203], v[232:235]
	v_mfma_i32_16x16x64_i8 v[110:113], v[172:175], v[208:211], v[236:239]
	v_mfma_i32_16x16x64_i8 v[106:109], v[192:195], v[208:211], v[240:243]
	v_mfma_i32_16x16x64_i8 v[94:97], v[172:175], v[216:219], v[244:247]
	v_mfma_i32_16x16x64_i8 v[90:93], v[192:195], v[216:219], v[248:251]
	v_mfma_i32_16x16x64_i8 v[78:81], v[172:175], v[224:227], v[228:231]
	v_mfma_i32_16x16x64_i8 v[74:77], v[192:195], v[224:227], v[74:77]
	s_setprio 0
	s_setprio 1
	v_mfma_i32_16x16x64_i8 v[228:231], v[134:137], v[196:199], v[118:121]
	v_mfma_i32_16x16x64_i8 v[118:121], v[138:141], v[200:203], v[228:231]
	v_mfma_i32_16x16x64_i8 v[232:235], v[142:145], v[196:199], v[114:117]
	v_mfma_i32_16x16x64_i8 v[236:239], v[134:137], v[204:207], v[102:105]
	v_mfma_i32_16x16x64_i8 v[240:243], v[142:145], v[204:207], v[98:101]
	v_mfma_i32_16x16x64_i8 v[244:247], v[134:137], v[212:215], v[86:89]
	v_mfma_i32_16x16x64_i8 v[248:251], v[142:145], v[212:215], v[82:85]
	v_mfma_i32_16x16x64_i8 v[196:199], v[134:137], v[220:223], v[70:73]
	v_mfma_i32_16x16x64_i8 v[66:69], v[142:145], v[220:223], v[66:69]
	v_mfma_i32_16x16x64_i8 v[114:117], v[130:133], v[200:203], v[232:235]
	v_mfma_i32_16x16x64_i8 v[102:105], v[138:141], v[208:211], v[236:239]
	v_mfma_i32_16x16x64_i8 v[98:101], v[130:133], v[208:211], v[240:243]
	v_mfma_i32_16x16x64_i8 v[86:89], v[138:141], v[216:219], v[244:247]
	v_mfma_i32_16x16x64_i8 v[82:85], v[130:133], v[216:219], v[248:251]
	v_mfma_i32_16x16x64_i8 v[70:73], v[138:141], v[224:227], v[196:199]
	v_mfma_i32_16x16x64_i8 v[66:69], v[130:133], v[224:227], v[66:69]
	s_setprio 0
	s_barrier
	s_add_i32 s2, s65, s33
	v_lshl_add_u64 v[164:165], v[164:165], 0, s[18:19]
	s_mov_b32 m0, s2
	ds_read_b128 v[196:199], v187 offset:49152
	ds_read_b128 v[200:203], v187 offset:50176
	ds_read_b128 v[204:207], v187 offset:51200
	ds_read_b128 v[208:211], v187 offset:52224
	ds_read_b128 v[212:215], v187 offset:53248
	ds_read_b128 v[216:219], v187 offset:54272
	ds_read_b128 v[220:223], v187 offset:55296
	ds_read_b128 v[224:227], v187 offset:56320
	global_load_lds_dwordx4 v[164:165], off
	s_add_i32 m0, s2, 0x2000
	s_add_u32 s2, s40, 0x2080
	v_lshl_add_u64 v[164:165], v[166:167], 0, s[18:19]
	s_addc_u32 s3, s41, 0
	s_add_i32 s40, s66, s33
	global_load_lds_dwordx4 v[164:165], off
	v_lshl_add_u64 v[164:165], s[2:3], 0, v[148:149]
	s_mov_b32 m0, s40
	s_nop 0
	global_load_lds_dwordx4 v[164:165], off
	v_lshl_add_u64 v[164:165], s[2:3], 0, v[152:153]
	s_add_i32 m0, s40, 0x2000
	s_nop 0
	global_load_lds_dwordx4 v[164:165], off
	v_lshl_add_u64 v[164:165], v[168:169], 0, s[18:19]
	s_mov_b32 m0, s51
	s_nop 0
	global_load_lds_dwordx4 v[164:165], off
	v_lshl_add_u64 v[164:165], v[170:171], 0, s[18:19]
	s_mov_b32 m0, s52
	s_nop 0
	global_load_lds_dwordx4 v[164:165], off
	s_waitcnt vmcnt(8)
	s_waitcnt lgkmcnt(0)
	s_barrier
	s_setprio 1
	s_waitcnt lgkmcnt(0)
	v_mfma_i32_16x16x64_i8 v[164:167], v[160:163], v[196:199], v[62:65]
	v_mfma_i32_16x16x64_i8 v[62:65], v[172:175], v[200:203], v[164:167]
	v_mfma_i32_16x16x64_i8 v[168:171], v[188:191], v[196:199], v[58:61]
	v_mfma_i32_16x16x64_i8 v[228:231], v[160:163], v[204:207], v[46:49]
	v_mfma_i32_16x16x64_i8 v[232:235], v[188:191], v[204:207], v[42:45]
	v_mfma_i32_16x16x64_i8 v[236:239], v[160:163], v[212:215], v[30:33]
	v_mfma_i32_16x16x64_i8 v[240:243], v[188:191], v[212:215], v[26:29]
	v_mfma_i32_16x16x64_i8 v[164:167], v[160:163], v[220:223], v[14:17]
	v_mfma_i32_16x16x64_i8 v[10:13], v[188:191], v[220:223], v[10:13]
	v_mfma_i32_16x16x64_i8 v[58:61], v[192:195], v[200:203], v[168:171]
	v_mfma_i32_16x16x64_i8 v[46:49], v[172:175], v[208:211], v[228:231]
	v_mfma_i32_16x16x64_i8 v[42:45], v[192:195], v[208:211], v[232:235]
	v_mfma_i32_16x16x64_i8 v[30:33], v[172:175], v[216:219], v[236:239]
	v_mfma_i32_16x16x64_i8 v[26:29], v[192:195], v[216:219], v[240:243]
	v_mfma_i32_16x16x64_i8 v[14:17], v[172:175], v[224:227], v[164:167]
	v_mfma_i32_16x16x64_i8 v[10:13], v[192:195], v[224:227], v[10:13]
	s_setprio 0
	s_setprio 1
	v_mfma_i32_16x16x64_i8 v[160:163], v[134:137], v[196:199], v[54:57]
	v_mfma_i32_16x16x64_i8 v[54:57], v[138:141], v[200:203], v[160:163]
	v_mfma_i32_16x16x64_i8 v[164:167], v[142:145], v[196:199], v[50:53]
	v_mfma_i32_16x16x64_i8 v[168:171], v[134:137], v[204:207], v[38:41]
	v_mfma_i32_16x16x64_i8 v[172:175], v[142:145], v[204:207], v[34:37]
	v_mfma_i32_16x16x64_i8 v[188:191], v[134:137], v[212:215], v[22:25]
	v_mfma_i32_16x16x64_i8 v[192:195], v[142:145], v[212:215], v[18:21]
	v_mfma_i32_16x16x64_i8 v[160:163], v[134:137], v[220:223], v[6:9]
	v_mfma_i32_16x16x64_i8 v[2:5], v[142:145], v[220:223], v[2:5]
	v_mfma_i32_16x16x64_i8 v[50:53], v[130:133], v[200:203], v[164:167]
	v_mfma_i32_16x16x64_i8 v[38:41], v[138:141], v[208:211], v[168:171]
	v_mfma_i32_16x16x64_i8 v[34:37], v[130:133], v[208:211], v[172:175]
	v_mfma_i32_16x16x64_i8 v[22:25], v[138:141], v[216:219], v[188:191]
	v_mfma_i32_16x16x64_i8 v[18:21], v[130:133], v[216:219], v[192:195]
	v_mfma_i32_16x16x64_i8 v[6:9], v[138:141], v[224:227], v[160:163]
	v_mfma_i32_16x16x64_i8 v[2:5], v[130:133], v[224:227], v[2:5]
	s_setprio 0
	s_barrier
; #define PG8_BAR __builtin_amdgcn_s_barrier()
;     __device__ __forceinline__ void operator()(const f32x4 (&acc)[2][2][4][2], const Unit& u, int wr, int wc, int fr, int fq) const {
;         asm volatile("" : "+v"(fr), "+v"(fq));
;         const int row0 = u.pm * BM + wr * 64 + fr, col0 = u.pn * BM + wc * 64 + 16 * fq;
;         const int gn = u.pn >> 2, gbase = (gn < 3) ? 3072 + 1024 * gn : 0;
;         f32x4 bv[2][2];
; #pragma unroll
;         for (int bj = 0; bj < 2; ++bj)
; #pragma unroll
;             for (int n = 0; n < 2; ++n) bv[bj][n] = *(const f32x4*)(bias + col0 + 8 * bj + 4 * n) * -1.44269504f;
;         f32x4 wv[2][2];
; #pragma unroll
;         for (int bj = 0; bj < 2; ++bj)
; #pragma unroll
;             for (int n = 0; n < 2; ++n) wv[bj][n] = *(const f32x4*)(SW + col0 + 8 * bj + 4 * n) * -1.44269504f;
;         float rsv[8];
; #pragma unroll
;         for (int i = 0; i < 8; ++i) rsv[i] = SH[row0 + (i >> 2) * HALF + (i & 3) * 16];
; template <class Epi, class Sched, class Gemm, bool ALIGN_EPI = false, bool SP2 = false>
; __device__ __forceinline__ void gemm_phase(PG8_LAS unsigned char* lds, const Gemm g, const Sched& S, const Epi& E) {
;     ...
;         if constexpr (ALIGN_EPI) { if (wr == 0) PG8_BAR; }
	s_add_i32 s64, s64, 2
	s_add_u32 s62, s62, 0x100
	s_addc_u32 s63, s63, 0
	s_add_u32 s0, s0, 0x100
	s_addc_u32 s1, s1, 0
	s_cmp_gt_u32 s64, 5
	s_mov_b64 vcc, 0
	s_cbranch_scc0 .LBB0_1192
	s_lshl_b32 s0, s59, 8
	v_mov_b32_e32 v130, v179
	v_mov_b32_e32 v154, v1
	s_or_b32 s0, s0, s53
	v_cvt_f32_i32_e32 v212, v122
	v_lshl_add_u32 v144, v130, 4, s0
	s_lshl_b32 s0, s38, 8
	v_ashrrev_i32_e32 v145, 31, v144
	s_add_i32 s0, s0, s50
	v_lshlrev_b64 v[142:143], 2, v[144:145]
	v_add_u32_e32 v164, s0, v154
	v_lshl_add_u64 v[160:161], s[10:11], 0, v[142:143]
	v_ashrrev_i32_e32 v165, 31, v164
	global_load_dwordx4 v[130:133], v[160:161], off
	global_load_dwordx4 v[134:137], v[160:161], off offset:16
	global_load_dwordx4 v[138:141], v[160:161], off offset:32
	s_nop 0
	global_load_dwordx4 v[160:163], v[160:161], off offset:48
	v_lshl_add_u64 v[142:143], s[14:15], 0, v[142:143]
	v_lshl_add_u64 v[170:171], v[164:165], 2, s[16:17]
	global_load_dwordx4 v[166:169], v[142:143], off
	global_load_dwordx4 v[194:197], v[142:143], off offset:16
	global_load_dwordx4 v[198:201], v[142:143], off offset:32
	global_load_dwordx4 v[202:205], v[142:143], off offset:48
	global_load_dword v206, v[170:171], off
	global_load_dword v188, v[170:171], off offset:64
	global_load_dword v186, v[170:171], off offset:128
	global_load_dword v184, v[170:171], off offset:192
	global_load_dword v182, v[170:171], off offset:512
	global_load_dword v180, v[170:171], off offset:576
	global_load_dword v178, v[170:171], off offset:640
	global_load_dword v122, v[170:171], off offset:704
	s_ashr_i32 s0, s59, 2
	s_lshl_b32 s1, s0, 10
	v_mov_b64_e32 v[142:143], s[12:13]
	s_add_i32 s2, s1, 0xc00
	v_cvt_f32_i32_e32 v209, v127
	v_cvt_f32_i32_e32 v208, v126
	v_cvt_f32_i32_e32 v215, v125
	v_cvt_f32_i32_e32 v214, v124
	s_cmp_lt_i32 s0, 3
	v_mad_i64_i32 v[124:125], s[0:1], v164, s57, v[142:143]
	s_cselect_b32 s0, s2, 0
	v_cvt_f32_i32_e32 v211, v129
	v_cvt_f32_i32_e32 v210, v128
	s_ashr_i32 s1, s0, 31
	v_cvt_f32_i32_e32 v115, v115
	v_cvt_f32_i32_e32 v114, v114
	v_cvt_f32_i32_e32 v99, v99
	v_cvt_f32_i32_e32 v98, v98
	v_cvt_f32_i32_e32 v83, v83
	v_cvt_f32_i32_e32 v82, v82
	v_cvt_f32_i32_e32 v67, v67
	v_cvt_f32_i32_e32 v66, v66
	v_cvt_f32_i32_e32 v51, v51
	v_cvt_f32_i32_e32 v50, v50
	v_cvt_f32_i32_e32 v35, v35
	v_cvt_f32_i32_e32 v34, v34
	v_cvt_f32_i32_e32 v19, v19
	v_cvt_f32_i32_e32 v18, v18
	v_and_b32_e32 v154, 0x3f0, v144
	v_lshl_add_u64 v[124:125], v[124:125], 0, s[0:1]
	v_cvt_f32_i32_e32 v117, v117
	v_cvt_f32_i32_e32 v116, v116
	v_cvt_f32_i32_e32 v111, v111
	v_cvt_f32_i32_e32 v110, v110
	v_cvt_f32_i32_e32 v101, v101
	v_cvt_f32_i32_e32 v100, v100
	v_cvt_f32_i32_e32 v95, v95
	v_cvt_f32_i32_e32 v94, v94
	v_cvt_f32_i32_e32 v85, v85
	v_cvt_f32_i32_e32 v84, v84
	v_cvt_f32_i32_e32 v79, v79
	v_cvt_f32_i32_e32 v78, v78
	v_cvt_f32_i32_e32 v69, v69
	v_cvt_f32_i32_e32 v68, v68
	v_cvt_f32_i32_e32 v63, v63
	v_cvt_f32_i32_e32 v62, v62
	v_cvt_f32_i32_e32 v53, v53
	v_cvt_f32_i32_e32 v52, v52
	v_cvt_f32_i32_e32 v47, v47
	v_cvt_f32_i32_e32 v46, v46
	v_cvt_f32_i32_e32 v37, v37
	v_cvt_f32_i32_e32 v36, v36
	v_cvt_f32_i32_e32 v31, v31
	v_cvt_f32_i32_e32 v30, v30
	v_cvt_f32_i32_e32 v21, v21
	v_cvt_f32_i32_e32 v20, v20
	v_cvt_f32_i32_e32 v15, v15
	v_cvt_f32_i32_e32 v14, v14
	v_add_u32_e32 v207, 32, v164
	v_lshl_add_u64 v[216:217], v[124:125], 0, v[154:155]
	v_add_u32_e32 v189, 0xa0, v164
	v_cvt_f32_i32_e32 v213, v123
	v_add_u32_e32 v123, 0xb0, v164
	v_cvt_f32_i32_e32 v119, v119
	v_cvt_f32_i32_e32 v118, v118
	v_cvt_f32_i32_e32 v109, v109
	v_cvt_f32_i32_e32 v108, v108
	v_cvt_f32_i32_e32 v103, v103
	v_cvt_f32_i32_e32 v102, v102
	v_cvt_f32_i32_e32 v93, v93
	v_cvt_f32_i32_e32 v121, v121
	v_cvt_f32_i32_e32 v120, v120
	v_cvt_f32_i32_e32 v113, v113
	v_cvt_f32_i32_e32 v112, v112
	v_cvt_f32_i32_e32 v107, v107
	v_cvt_f32_i32_e32 v106, v106
	v_cvt_f32_i32_e32 v105, v105
	v_cvt_f32_i32_e32 v104, v104
	v_cvt_f32_i32_e32 v92, v92
	v_cvt_f32_i32_e32 v87, v87
	v_cvt_f32_i32_e32 v86, v86
	v_cvt_f32_i32_e32 v97, v97
	v_cvt_f32_i32_e32 v96, v96
	v_cvt_f32_i32_e32 v91, v91
	v_cvt_f32_i32_e32 v90, v90
	v_cvt_f32_i32_e32 v89, v89
	v_cvt_f32_i32_e32 v88, v88
	v_cvt_f32_i32_e32 v77, v77
	v_cvt_f32_i32_e32 v76, v76
	v_cvt_f32_i32_e32 v71, v71
	v_cvt_f32_i32_e32 v70, v70
	v_cvt_f32_i32_e32 v81, v81
	v_cvt_f32_i32_e32 v80, v80
	v_cvt_f32_i32_e32 v75, v75
	v_cvt_f32_i32_e32 v74, v74
	v_cvt_f32_i32_e32 v73, v73
	v_cvt_f32_i32_e32 v72, v72
	v_cvt_f32_i32_e32 v61, v61
	v_cvt_f32_i32_e32 v60, v60
	v_cvt_f32_i32_e32 v55, v55
	v_cvt_f32_i32_e32 v54, v54
	v_cvt_f32_i32_e32 v65, v65
	v_cvt_f32_i32_e32 v64, v64
	v_cvt_f32_i32_e32 v59, v59
	v_cvt_f32_i32_e32 v58, v58
	v_cvt_f32_i32_e32 v57, v57
	v_cvt_f32_i32_e32 v56, v56
	v_cvt_f32_i32_e32 v45, v45
	v_cvt_f32_i32_e32 v44, v44
	v_cvt_f32_i32_e32 v39, v39
	v_cvt_f32_i32_e32 v38, v38
	v_cvt_f32_i32_e32 v49, v49
	v_cvt_f32_i32_e32 v48, v48
	v_cvt_f32_i32_e32 v43, v43
	v_cvt_f32_i32_e32 v42, v42
	v_cvt_f32_i32_e32 v41, v41
	v_cvt_f32_i32_e32 v40, v40
	v_cvt_f32_i32_e32 v29, v29
	v_cvt_f32_i32_e32 v28, v28
	v_cvt_f32_i32_e32 v23, v23
	v_cvt_f32_i32_e32 v22, v22
	v_cvt_f32_i32_e32 v33, v33
	v_cvt_f32_i32_e32 v32, v32
	v_cvt_f32_i32_e32 v27, v27
	v_cvt_f32_i32_e32 v26, v26
	v_cvt_f32_i32_e32 v25, v25
	v_cvt_f32_i32_e32 v24, v24
	v_cvt_f32_i32_e32 v7, v7
	v_cvt_f32_i32_e32 v6, v6
	v_cvt_f32_i32_e32 v3, v3
	v_cvt_f32_i32_e32 v2, v2
	v_cvt_f32_i32_e32 v17, v17
	v_cvt_f32_i32_e32 v16, v16
	v_cvt_f32_i32_e32 v11, v11
	v_cvt_f32_i32_e32 v13, v13
	v_cvt_f32_i32_e32 v12, v12
	v_cvt_f32_i32_e32 v10, v10
	v_cvt_f32_i32_e32 v9, v9
	v_cvt_f32_i32_e32 v8, v8
	v_cvt_f32_i32_e32 v5, v5
	v_cvt_f32_i32_e32 v4, v4
	s_and_b64 vcc, exec, s[20:21]
	s_cbranch_vccz .LBB0_1195
	s_barrier

; #define BIDX opqs((int)blockIdx.x)
; #define PG8_LAS __attribute__((address_space(3)))
;     __device__ bool next(int i, Unit& u) const { const bool ok = StaticOrder::next(i >> 2, u); u.sub = i & 3; return ok; }
;     __host__ __device__ bool next(int i, Unit& u) const {
;         const long L = (long)i * G + c; if (L >= nwg) return false;
;         int wgid = (int)L; { const int q = nwg / NXCD, r = nwg % NXCD, xcd = wgid % NXCD, off = wgid / NXCD; wgid = (xcd < r ? xcd * (q + 1) : r * (q + 1) + (xcd - r) * q) + off; }
;         const int nig = WGM * nN, gid = wgid / nig, fm = gid * WGM, gsz = (nM - fm) < WGM ? (nM - fm) : WGM;
;         u.pm = fm + ((wgid % nig) % gsz); u.pn = (wgid % nig) / gsz; u.sub = 0; return true;
; template <int L, int Q>
; __device__ __forceinline__ void layer_phase(unsigned char* lds_raw) {
;     ...
;     } else if constexpr (Q == 4) {
;         typedef pg8::GemmT<DM, 256, 256, 512, 1024 * 256 * 2> GT; GT g{c.P, c.WbT + (size_t)l * 4 * 1024 * 256}; pg8::MergeOrder S; S.init(MT, DM, (int)gridDim.x, BIDX);
;         pg8::EpiMergeChain E{(const unsigned char*)c.Z, c.H, c.FF};
;         pg8::gemm_phase<pg8::EpiMergeChain, pg8::MergeOrder, GT, true, true>((PG8_LAS unsigned char*)lds_raw, g, S, E);
.LBB0_1253:
	s_nop 0
	s_nop 0
	s_nop 0
	s_nop 0
	s_nop 0
	s_nop 0
	s_nop 0
	s_nop 0
	s_nop 0
	s_nop 0
	s_nop 0
	s_nop 0
	s_nop 0
	s_nop 0
	s_nop 0
	s_nop 0
	s_nop 0
	s_nop 0
	s_nop 0
	s_nop 0
	s_nop 0
	s_nop 0
	s_nop 0
	s_nop 0
	s_nop 0
	s_nop 0
	s_nop 0
	s_nop 0
	s_nop 0
	s_nop 0
	s_nop 0
	s_nop 0
	s_nop 0
	s_nop 0
	s_nop 0
	s_nop 0
	s_nop 0
	s_nop 0
	s_nop 0
	s_nop 0
	s_nop 0
	s_nop 0
	s_nop 0
	s_nop 0
	s_nop 0
	s_nop 0
	s_nop 0
	s_nop 0
	s_nop 0
	s_nop 0
	s_nop 0
	s_nop 0
	s_nop 0
	s_nop 0
	s_nop 0
	s_nop 0
	s_nop 0
	s_nop 0
	s_cmp_lt_i32 s86, 5
	s_cselect_b64 s[0:1], -1, 0
	s_cmp_gt_i32 s87, 4
	s_cselect_b64 s[2:3], -1, 0
	s_and_b64 s[0:1], s[0:1], s[2:3]
	s_andn2_b64 vcc, exec, s[0:1]
	s_cbranch_vccnz .LBB0_1350
	v_readlane_b32 s4, v255, 0
	v_readlane_b32 s5, v255, 1
	s_mov_b64 s[0:1], s[4:5]
	s_load_dwordx2 s[2:3], s[0:1], 0x88
	s_add_u32 s8, s4, 0x98
	s_addc_u32 s9, s5, 0
	s_mov_b32 s33, s88
	s_waitcnt vmcnt(0)
	v_mov_b32_e32 v2, v0
	s_cmpk_lt_i32 s33, 0x200
	s_cselect_b64 s[4:5], -1, 0
	s_cmpk_gt_i32 s33, 0x1ff
	v_readfirstlane_b32 s18, v2
	s_cbranch_scc1 .LBB0_1260
	s_ashr_i32 s0, s33, 31
	s_lshr_b32 s0, s0, 29
	s_add_i32 s10, s33, s0
	s_and_b32 s0, s10, -8
	s_sub_i32 s6, s33, s0
	s_cmp_gt_i32 s6, -1
	s_cbranch_scc0 .LBB0_1257
	s_lshl_b32 s7, s6, 6
	s_ashr_i32 s0, s10, 3
	s_cbranch_execz .LBB0_1258
	s_branch .LBB0_1259

;     __device__ __forceinline__ void operator()(f32x4 (&acc)[2][2][4][2], const Unit& u, int wr, int wc, int fr, int fq) const {
;     ...
;         for (int ai = 0; ai < 2; ++ai)
; #pragma unroll
;             for (int m = 0; m < 4; ++m) {
;                 const int row = row0 + ai * HALF + m * 16;
;                 const float ss = __hip_atomic_load(SS + row, __ATOMIC_RELAXED, __HIP_MEMORY_SCOPE_AGENT);
;                 const float rstd = 1.0f / sqrtf(ss * (1.f / 1024.f) + 1e-6f);
;                 float qs = 0.f;
;                 if constexpr (!FINAL) {
;                     const float am = __uint_as_float(__hip_atomic_load(AM + row, __ATOMIC_RELAXED, __HIP_MEMORY_SCOPE_AGENT));
;                     qs = am > 0.f ? 127.f / am : 0.f;
;                     if (u.pn == 0 && wc == 0 && fq == 0) SH[row] = am * rstd * (1.f / 127.f);
;                 }
; #pragma unroll
;                 for (int bj = 0; bj < 2; ++bj) {
;                     const size_t off = (size_t)row * 1024 + col0 + bj * HALF;
;                     const f32x4 y0 = acc[ai][bj][m][0] * rstd * gv[bj][0], y1 = acc[ai][bj][m][1] * rstd * gv[bj][1];
;                     if constexpr (FINAL) { *(f32x4*)(out + off) = y0; *(f32x4*)(out + off + 4) = y1; }
;                     else {
;                         u32x2 q8; q8.x = q8x4(acc[ai][bj][m][0] * gv[bj][0], qs); q8.y = q8x4(acc[ai][bj][m][1] * gv[bj][1], qs);
;                         *(u32x2*)(H8 + off) = q8;
;                     }
;                 }
.LBB0_1422:
	s_or_b64 exec, exec, s[2:3]
	v_lshlrev_b64 v[148:149], 2, v[224:225]
	v_lshl_add_u64 v[146:147], s[22:23], 0, v[148:149]
	v_lshl_add_u64 v[148:149], s[24:25], 0, v[148:149]
	global_load_dword v158, v[146:147], off sc1
	global_load_dword v159, v[148:149], off sc1
	global_load_dword v160, v[146:147], off offset:64 sc1
	global_load_dword v161, v[148:149], off offset:64 sc1
	global_load_dword v162, v[146:147], off offset:128 sc1
	global_load_dword v163, v[148:149], off offset:128 sc1
	global_load_dword v164, v[146:147], off offset:192 sc1
	global_load_dword v165, v[148:149], off offset:192 sc1
	global_load_dword v166, v[146:147], off offset:512 sc1
	global_load_dword v167, v[148:149], off offset:512 sc1
	global_load_dword v168, v[146:147], off offset:576 sc1
	global_load_dword v169, v[148:149], off offset:576 sc1
	global_load_dword v170, v[146:147], off offset:640 sc1
	global_load_dword v171, v[148:149], off offset:640 sc1
	global_load_dword v172, v[146:147], off offset:704 sc1
	global_load_dword v173, v[148:149], off offset:704 sc1
	s_or_b32 s0, s8, s59
	v_or_b32_e32 v152, s0, v242
	v_cmp_eq_u32_e64 s[6:7], 0, v152
	s_and_saveexec_b64 s[0:1], s[6:7]
	s_cbranch_execz .LBB0_1424
	s_waitcnt vmcnt(14)
	v_fmamk_f32 v151, v158, 0x3a800000, v240
	v_mul_f32_e32 v152, 0x4f800000, v151
	v_cmp_gt_f32_e32 vcc, s68, v151
	s_nop 1
	v_cndmask_b32_e32 v151, v151, v152, vcc
	v_sqrt_f32_e32 v152, v151
	s_nop 0
	v_add_u32_e32 v153, -1, v152
	v_fma_f32 v155, -v153, v152, v151
	v_add_u32_e32 v154, 1, v152
	v_cmp_ge_f32_e64 s[8:9], 0, v155
	s_nop 1
	v_cndmask_b32_e64 v153, v152, v153, s[8:9]
	v_fma_f32 v152, -v154, v152, v151
	v_cmp_lt_f32_e64 s[8:9], 0, v152
	s_nop 1
	v_cndmask_b32_e64 v152, v153, v154, s[8:9]
	v_mul_f32_e32 v153, 0x37800000, v152
	v_cndmask_b32_e32 v152, v152, v153, vcc
	v_cmp_class_f32_e32 vcc, v151, v241
	s_nop 1
	v_cndmask_b32_e32 v151, v152, v151, vcc
	v_div_scale_f32 v152, s[2:3], v151, v151, 1.0
	v_rcp_f32_e32 v153, v152
	s_nop 0
	v_fma_f32 v154, -v152, v153, 1.0
	v_fmac_f32_e32 v153, v154, v153
	v_div_scale_f32 v154, vcc, 1.0, v151, 1.0
	v_mul_f32_e32 v155, v154, v153
	v_fma_f32 v156, -v152, v155, v154
	v_fmac_f32_e32 v155, v156, v153
	v_fma_f32 v152, -v152, v155, v154
	v_div_fmas_f32 v152, v152, v153, v155
	v_div_fixup_f32 v151, v152, v151, 1.0
	v_mul_f32_e32 v151, v151, v159
	v_mul_f32_e32 v151, 0x3c010204, v151
	v_lshl_add_u64 v[152:153], v[224:225], 2, s[26:27]
	global_store_dword v[152:153], v151, off
.LBB0_1424:
	s_or_b64 exec, exec, s[0:1]
	s_waitcnt vmcnt(14)
	v_div_scale_f32 v151, s[0:1], v159, v159, s69
	v_rcp_f32_e32 v152, v151
	v_div_scale_f32 v153, vcc, s69, v159, s69
	v_pk_mul_f32 v[96:97], v[96:97], v[16:17]
	v_fma_f32 v154, -v151, v152, 1.0
	v_fmac_f32_e32 v152, v154, v152
	v_mul_f32_e32 v154, v153, v152
	v_fma_f32 v155, -v151, v154, v153
	v_fmac_f32_e32 v154, v155, v152
	v_fma_f32 v151, -v151, v154, v153
	v_div_fmas_f32 v151, v151, v152, v154
	v_div_fixup_f32 v151, v151, v159, s69
	v_cmp_lt_f32_e32 vcc, 0, v159
	v_pk_mul_f32 v[94:95], v[94:95], v[14:15]
	v_pk_mul_f32 v[92:93], v[92:93], v[12:13]
	v_cndmask_b32_e32 v150, 0, v151, vcc
	v_pk_mul_f32 v[90:91], v[90:91], v[10:11]
	v_pk_fma_f32 v[94:95], v[94:95], v[150:151], s[34:35] op_sel_hi:[1,0,0]
	v_pk_fma_f32 v[96:97], v[96:97], v[150:151], s[34:35] op_sel_hi:[1,0,0]
	v_pk_fma_f32 v[90:91], v[90:91], v[150:151], s[34:35] op_sel_hi:[1,0,0]
	v_pk_fma_f32 v[92:93], v[92:93], v[150:151], s[34:35] op_sel_hi:[1,0,0]
	v_pk_mul_f32 v[88:89], v[88:89], v[8:9]
	v_pk_mul_f32 v[86:87], v[86:87], v[6:7]
	v_pk_mul_f32 v[84:85], v[84:85], v[4:5]
	v_pk_mul_f32 v[82:83], v[82:83], v[2:3]
	v_lshlrev_b32_e32 v95, 8, v95
	v_lshlrev_b32_e32 v96, 16, v96
	v_lshlrev_b32_e32 v91, 8, v91
	v_lshlrev_b32_e32 v92, 16, v92
	v_pk_fma_f32 v[86:87], v[86:87], v[150:151], s[34:35] op_sel_hi:[1,0,0]
	v_pk_fma_f32 v[88:89], v[88:89], v[150:151], s[34:35] op_sel_hi:[1,0,0]
	v_pk_fma_f32 v[82:83], v[82:83], v[150:151], s[34:35] op_sel_hi:[1,0,0]
	v_pk_fma_f32 v[84:85], v[84:85], v[150:151], s[34:35] op_sel_hi:[1,0,0]
	v_lshlrev_b64 v[152:153], 10, v[224:225]
	v_and_b32_e32 v95, 0xff00, v95
	v_and_b32_e32 v96, 0xff0000, v96
	v_perm_b32 v94, v97, v94, s70
	v_and_b32_e32 v91, 0xff00, v91
	v_and_b32_e32 v92, 0xff0000, v92
	v_perm_b32 v90, v93, v90, s70
	v_lshlrev_b32_e32 v87, 8, v87
	v_lshlrev_b32_e32 v88, 16, v88
	v_lshlrev_b32_e32 v83, 8, v83
	v_lshlrev_b32_e32 v84, 16, v84
	v_or3_b32 v94, v94, v95, v96
	v_or3_b32 v95, v90, v91, v92
	v_lshl_add_u64 v[90:91], s[18:19], 0, v[152:153]
	v_and_b32_e32 v87, 0xff00, v87
	v_and_b32_e32 v88, 0xff0000, v88
	v_perm_b32 v86, v89, v86, s70
	v_and_b32_e32 v83, 0xff00, v83
	v_and_b32_e32 v84, 0xff0000, v84
	v_perm_b32 v82, v85, v82, s70
	v_lshl_add_u64 v[90:91], v[90:91], 0, v[210:211]
	v_or3_b32 v86, v86, v87, v88
	v_or3_b32 v87, v82, v83, v84
	global_store_dwordx2 v[90:91], v[94:95], off
	global_store_dwordx2 v[90:91], v[86:87], off offset:128
	s_and_saveexec_b64 s[0:1], s[6:7]
	s_cbranch_execz .LBB0_1426
	s_waitcnt vmcnt(14)
	v_fmamk_f32 v83, v160, 0x3a800000, v240
	v_mul_f32_e32 v84, 0x4f800000, v83
	v_cmp_gt_f32_e32 vcc, s68, v83
	s_nop 1
	v_cndmask_b32_e32 v83, v83, v84, vcc
	v_sqrt_f32_e32 v84, v83
	s_nop 0
	v_add_u32_e32 v85, -1, v84
	v_fma_f32 v87, -v85, v84, v83
	v_add_u32_e32 v86, 1, v84
	v_cmp_ge_f32_e64 s[8:9], 0, v87
	s_nop 1
	v_cndmask_b32_e64 v85, v84, v85, s[8:9]
	v_fma_f32 v84, -v86, v84, v83
	v_cmp_lt_f32_e64 s[8:9], 0, v84
	s_nop 1
	v_cndmask_b32_e64 v84, v85, v86, s[8:9]
	v_mul_f32_e32 v85, 0x37800000, v84
	v_cndmask_b32_e32 v84, v84, v85, vcc
	v_cmp_class_f32_e32 vcc, v83, v241
	s_nop 1
	v_cndmask_b32_e32 v83, v84, v83, vcc
	v_div_scale_f32 v84, s[2:3], v83, v83, 1.0
	v_rcp_f32_e32 v85, v84
	s_nop 0
	v_fma_f32 v86, -v84, v85, 1.0
	v_fmac_f32_e32 v85, v86, v85
	v_div_scale_f32 v86, vcc, 1.0, v83, 1.0
	v_mul_f32_e32 v87, v86, v85
	v_fma_f32 v88, -v84, v87, v86
	v_fmac_f32_e32 v87, v88, v85
	v_fma_f32 v84, -v84, v87, v86
	v_div_fmas_f32 v84, v84, v85, v87
	v_div_fixup_f32 v83, v84, v83, 1.0
	v_mul_f32_e32 v83, v83, v161
	v_mul_f32_e32 v83, 0x3c010204, v83
	v_lshl_add_u64 v[84:85], v[216:217], 2, s[26:27]
	global_store_dword v[84:85], v83, off
;     __device__ __forceinline__ void operator()(f32x4 (&acc)[2][2][4][2], const Unit& u, int wr, int wc, int fr, int fq) const {
;     ...
;         for (int ai = 0; ai < 2; ++ai)
; #pragma unroll
;             for (int m = 0; m < 4; ++m) {
;                 const int row = row0 + ai * HALF + m * 16;
;                 const float ss = __hip_atomic_load(SS + row, __ATOMIC_RELAXED, __HIP_MEMORY_SCOPE_AGENT);
;                 const float rstd = 1.0f / sqrtf(ss * (1.f / 1024.f) + 1e-6f);
;                 float qs = 0.f;
;                 if constexpr (!FINAL) {
;                     const float am = __uint_as_float(__hip_atomic_load(AM + row, __ATOMIC_RELAXED, __HIP_MEMORY_SCOPE_AGENT));
;                     qs = am > 0.f ? 127.f / am : 0.f;
;                     if (u.pn == 0 && wc == 0 && fq == 0) SH[row] = am * rstd * (1.f / 127.f);
;                 }
; #pragma unroll
;                 for (int bj = 0; bj < 2; ++bj) {
;                     const size_t off = (size_t)row * 1024 + col0 + bj * HALF;
;                     const f32x4 y0 = acc[ai][bj][m][0] * rstd * gv[bj][0], y1 = acc[ai][bj][m][1] * rstd * gv[bj][1];
;                     if constexpr (FINAL) { *(f32x4*)(out + off) = y0; *(f32x4*)(out + off + 4) = y1; }
;                     else {
;                         u32x2 q8; q8.x = q8x4(acc[ai][bj][m][0] * gv[bj][0], qs); q8.y = q8x4(acc[ai][bj][m][1] * gv[bj][1], qs);
;                         *(u32x2*)(H8 + off) = q8;
;                     }
;                 }
.LBB0_1426:
	s_or_b64 exec, exec, s[0:1]
	s_waitcnt vmcnt(14)
	v_div_scale_f32 v83, s[0:1], v161, v161, s69
	v_rcp_f32_e32 v84, v83
	v_div_scale_f32 v85, vcc, s69, v161, s69
	v_pk_mul_f32 v[88:89], v[110:111], v[14:15]
	v_fma_f32 v86, -v83, v84, 1.0
	v_fmac_f32_e32 v84, v86, v84
	v_mul_f32_e32 v86, v85, v84
	v_fma_f32 v87, -v83, v86, v85
	v_fmac_f32_e32 v86, v87, v84
	v_fma_f32 v83, -v83, v86, v85
	v_div_fmas_f32 v83, v83, v84, v86
	v_div_fixup_f32 v83, v83, v161, s69
	v_cmp_lt_f32_e32 vcc, 0, v161
	v_pk_mul_f32 v[86:87], v[112:113], v[16:17]
	v_pk_mul_f32 v[90:91], v[106:107], v[10:11]
	v_cndmask_b32_e32 v82, 0, v83, vcc
	v_pk_fma_f32 v[88:89], v[88:89], v[82:83], s[34:35] op_sel_hi:[1,0,0]
	v_pk_fma_f32 v[86:87], v[86:87], v[82:83], s[34:35] op_sel_hi:[1,0,0]
	v_lshlrev_b32_e32 v83, 8, v89
	v_and_b32_e32 v83, 0xff00, v83
	v_lshlrev_b32_e32 v86, 16, v86
	v_perm_b32 v87, v87, v88, s70
	v_pk_mul_f32 v[88:89], v[108:109], v[12:13]
	v_and_b32_e32 v86, 0xff0000, v86
	v_pk_fma_f32 v[90:91], v[90:91], v[82:83], s[34:35] op_sel_hi:[1,0,0]
	v_pk_fma_f32 v[88:89], v[88:89], v[82:83], s[34:35] op_sel_hi:[1,0,0]
	v_lshlrev_b64 v[84:85], 10, v[216:217]
	v_or3_b32 v86, v87, v83, v86
	v_lshlrev_b32_e32 v83, 8, v91
	v_lshlrev_b32_e32 v87, 16, v88
	v_and_b32_e32 v83, 0xff00, v83
	v_and_b32_e32 v87, 0xff0000, v87
	v_perm_b32 v88, v89, v90, s70
	v_lshl_add_u64 v[84:85], s[18:19], 0, v[84:85]
	v_or3_b32 v87, v88, v83, v87
	v_lshl_add_u64 v[84:85], v[84:85], 0, v[210:211]
	global_store_dwordx2 v[84:85], v[86:87], off
	v_pk_mul_f32 v[86:87], v[104:105], v[8:9]
	v_pk_mul_f32 v[88:89], v[102:103], v[6:7]
	v_pk_fma_f32 v[86:87], v[86:87], v[82:83], s[34:35] op_sel_hi:[1,0,0]
	v_pk_fma_f32 v[88:89], v[88:89], v[82:83], s[34:35] op_sel_hi:[1,0,0]
	v_lshlrev_b32_e32 v86, 16, v86
	v_lshlrev_b32_e32 v83, 8, v89
	v_and_b32_e32 v83, 0xff00, v83
	v_and_b32_e32 v86, 0xff0000, v86
	v_perm_b32 v87, v87, v88, s70
	v_pk_mul_f32 v[88:89], v[100:101], v[4:5]
	v_pk_mul_f32 v[90:91], v[98:99], v[2:3]
	v_or3_b32 v86, v87, v83, v86
	v_pk_fma_f32 v[90:91], v[90:91], v[82:83], s[34:35] op_sel_hi:[1,0,0]
	v_pk_fma_f32 v[82:83], v[88:89], v[82:83], s[34:35] op_sel_hi:[1,0,0]
	v_lshlrev_b32_e32 v87, 8, v91
	v_lshlrev_b32_e32 v82, 16, v82
	v_and_b32_e32 v87, 0xff00, v87
	v_and_b32_e32 v82, 0xff0000, v82
	v_perm_b32 v83, v83, v90, s70
	v_or3_b32 v87, v83, v87, v82
	global_store_dwordx2 v[84:85], v[86:87], off offset:128
	s_and_saveexec_b64 s[0:1], s[6:7]
	s_cbranch_execz .LBB0_1428
	s_waitcnt vmcnt(14)
	v_fmamk_f32 v83, v162, 0x3a800000, v240
	v_mul_f32_e32 v84, 0x4f800000, v83
	v_cmp_gt_f32_e32 vcc, s68, v83
	s_nop 1
	v_cndmask_b32_e32 v83, v83, v84, vcc
	v_sqrt_f32_e32 v84, v83
	s_nop 0
	v_add_u32_e32 v85, -1, v84
	v_fma_f32 v87, -v85, v84, v83
	v_add_u32_e32 v86, 1, v84
	v_cmp_ge_f32_e64 s[8:9], 0, v87
	s_nop 1
	v_cndmask_b32_e64 v85, v84, v85, s[8:9]
	v_fma_f32 v84, -v86, v84, v83
	v_cmp_lt_f32_e64 s[8:9], 0, v84
	s_nop 1
	v_cndmask_b32_e64 v84, v85, v86, s[8:9]
	v_mul_f32_e32 v85, 0x37800000, v84
	v_cndmask_b32_e32 v84, v84, v85, vcc
	v_cmp_class_f32_e32 vcc, v83, v241
	s_nop 1
	v_cndmask_b32_e32 v83, v84, v83, vcc
	v_div_scale_f32 v84, s[2:3], v83, v83, 1.0
	v_rcp_f32_e32 v85, v84
	s_nop 0
	v_fma_f32 v86, -v84, v85, 1.0
	v_fmac_f32_e32 v85, v86, v85
	v_div_scale_f32 v86, vcc, 1.0, v83, 1.0
	v_mul_f32_e32 v87, v86, v85
	v_fma_f32 v88, -v84, v87, v86
	v_fmac_f32_e32 v87, v88, v85
	v_fma_f32 v84, -v84, v87, v86
	v_div_fmas_f32 v84, v84, v85, v87
	v_div_fixup_f32 v83, v84, v83, 1.0
	v_mul_f32_e32 v83, v83, v163
	v_mul_f32_e32 v83, 0x3c010204, v83
	v_lshl_add_u64 v[84:85], v[212:213], 2, s[26:27]
	global_store_dword v[84:85], v83, off
.LBB0_1428:
	s_or_b64 exec, exec, s[0:1]
	s_waitcnt vmcnt(14)
	v_div_scale_f32 v83, s[0:1], v163, v163, s69
	v_rcp_f32_e32 v84, v83
	v_div_scale_f32 v85, vcc, s69, v163, s69
	v_pk_mul_f32 v[88:89], v[130:131], v[14:15]
	v_fma_f32 v86, -v83, v84, 1.0
	v_fmac_f32_e32 v84, v86, v84
	v_mul_f32_e32 v86, v85, v84
	v_fma_f32 v87, -v83, v86, v85
	v_fmac_f32_e32 v86, v87, v84
	v_fma_f32 v83, -v83, v86, v85
	v_div_fmas_f32 v83, v83, v84, v86
	v_div_fixup_f32 v83, v83, v163, s69
	v_cmp_lt_f32_e32 vcc, 0, v163
	v_pk_mul_f32 v[86:87], v[132:133], v[16:17]
	v_pk_mul_f32 v[90:91], v[122:123], v[10:11]
	v_cndmask_b32_e32 v82, 0, v83, vcc
	v_pk_fma_f32 v[88:89], v[88:89], v[82:83], s[34:35] op_sel_hi:[1,0,0]
	v_pk_fma_f32 v[86:87], v[86:87], v[82:83], s[34:35] op_sel_hi:[1,0,0]
	v_lshlrev_b32_e32 v83, 8, v89
	v_and_b32_e32 v83, 0xff00, v83
	v_lshlrev_b32_e32 v86, 16, v86
	v_perm_b32 v87, v87, v88, s70
	v_pk_mul_f32 v[88:89], v[124:125], v[12:13]
	v_and_b32_e32 v86, 0xff0000, v86
	v_pk_fma_f32 v[90:91], v[90:91], v[82:83], s[34:35] op_sel_hi:[1,0,0]
	v_pk_fma_f32 v[88:89], v[88:89], v[82:83], s[34:35] op_sel_hi:[1,0,0]
	v_lshlrev_b64 v[84:85], 10, v[212:213]
	v_or3_b32 v86, v87, v83, v86
	v_lshlrev_b32_e32 v83, 8, v91
	v_lshlrev_b32_e32 v87, 16, v88
	v_and_b32_e32 v83, 0xff00, v83
	v_and_b32_e32 v87, 0xff0000, v87
	v_perm_b32 v88, v89, v90, s70
	v_lshl_add_u64 v[84:85], s[18:19], 0, v[84:85]
	v_or3_b32 v87, v88, v83, v87
	v_lshl_add_u64 v[84:85], v[84:85], 0, v[210:211]
	global_store_dwordx2 v[84:85], v[86:87], off
	v_pk_mul_f32 v[86:87], v[120:121], v[8:9]
	v_pk_mul_f32 v[88:89], v[118:119], v[6:7]
	v_pk_fma_f32 v[86:87], v[86:87], v[82:83], s[34:35] op_sel_hi:[1,0,0]
	v_pk_fma_f32 v[88:89], v[88:89], v[82:83], s[34:35] op_sel_hi:[1,0,0]
	v_lshlrev_b32_e32 v86, 16, v86
	v_lshlrev_b32_e32 v83, 8, v89
	v_and_b32_e32 v83, 0xff00, v83
	v_and_b32_e32 v86, 0xff0000, v86
	v_perm_b32 v87, v87, v88, s70
	v_pk_mul_f32 v[88:89], v[116:117], v[4:5]
	v_pk_mul_f32 v[90:91], v[114:115], v[2:3]
	v_or3_b32 v86, v87, v83, v86
	v_pk_fma_f32 v[90:91], v[90:91], v[82:83], s[34:35] op_sel_hi:[1,0,0]
	v_pk_fma_f32 v[82:83], v[88:89], v[82:83], s[34:35] op_sel_hi:[1,0,0]
	v_lshlrev_b32_e32 v87, 8, v91
	v_lshlrev_b32_e32 v82, 16, v82
	v_and_b32_e32 v87, 0xff00, v87
	v_and_b32_e32 v82, 0xff0000, v82
	v_perm_b32 v83, v83, v90, s70
	v_or3_b32 v87, v83, v87, v82
	global_store_dwordx2 v[84:85], v[86:87], off offset:128
	s_and_saveexec_b64 s[0:1], s[6:7]
	s_cbranch_execz .LBB0_1430
;     __device__ __forceinline__ void operator()(f32x4 (&acc)[2][2][4][2], const Unit& u, int wr, int wc, int fr, int fq) const {
;     ...
;         for (int ai = 0; ai < 2; ++ai)
; #pragma unroll
;             for (int m = 0; m < 4; ++m) {
;                 const int row = row0 + ai * HALF + m * 16;
;                 const float ss = __hip_atomic_load(SS + row, __ATOMIC_RELAXED, __HIP_MEMORY_SCOPE_AGENT);
;                 const float rstd = 1.0f / sqrtf(ss * (1.f / 1024.f) + 1e-6f);
;                 float qs = 0.f;
;                 if constexpr (!FINAL) {
;                     const float am = __uint_as_float(__hip_atomic_load(AM + row, __ATOMIC_RELAXED, __HIP_MEMORY_SCOPE_AGENT));
;                     qs = am > 0.f ? 127.f / am : 0.f;
;                     if (u.pn == 0 && wc == 0 && fq == 0) SH[row] = am * rstd * (1.f / 127.f);
;                 }
; #pragma unroll
;                 for (int bj = 0; bj < 2; ++bj) {
;                     const size_t off = (size_t)row * 1024 + col0 + bj * HALF;
;                     const f32x4 y0 = acc[ai][bj][m][0] * rstd * gv[bj][0], y1 = acc[ai][bj][m][1] * rstd * gv[bj][1];
;                     if constexpr (FINAL) { *(f32x4*)(out + off) = y0; *(f32x4*)(out + off + 4) = y1; }
;                     else {
;                         u32x2 q8; q8.x = q8x4(acc[ai][bj][m][0] * gv[bj][0], qs); q8.y = q8x4(acc[ai][bj][m][1] * gv[bj][1], qs);
;                         *(u32x2*)(H8 + off) = q8;
;                     }
;                 }
	s_waitcnt vmcnt(14)
	v_fmamk_f32 v83, v164, 0x3a800000, v240
	v_mul_f32_e32 v84, 0x4f800000, v83
	v_cmp_gt_f32_e32 vcc, s68, v83
	s_nop 1
	v_cndmask_b32_e32 v83, v83, v84, vcc
	v_sqrt_f32_e32 v84, v83
	s_nop 0
	v_add_u32_e32 v85, -1, v84
	v_fma_f32 v87, -v85, v84, v83
	v_add_u32_e32 v86, 1, v84
	v_cmp_ge_f32_e64 s[8:9], 0, v87
	s_nop 1
	v_cndmask_b32_e64 v85, v84, v85, s[8:9]
	v_fma_f32 v84, -v86, v84, v83
	v_cmp_lt_f32_e64 s[8:9], 0, v84
	s_nop 1
	v_cndmask_b32_e64 v84, v85, v86, s[8:9]
	v_mul_f32_e32 v85, 0x37800000, v84
	v_cndmask_b32_e32 v84, v84, v85, vcc
	v_cmp_class_f32_e32 vcc, v83, v241
	s_nop 1
	v_cndmask_b32_e32 v83, v84, v83, vcc
	v_div_scale_f32 v84, s[2:3], v83, v83, 1.0
	v_rcp_f32_e32 v85, v84
	s_nop 0
	v_fma_f32 v86, -v84, v85, 1.0
	v_fmac_f32_e32 v85, v86, v85
	v_div_scale_f32 v86, vcc, 1.0, v83, 1.0
	v_mul_f32_e32 v87, v86, v85
	v_fma_f32 v88, -v84, v87, v86
	v_fmac_f32_e32 v87, v88, v85
	v_fma_f32 v84, -v84, v87, v86
	v_div_fmas_f32 v84, v84, v85, v87
	v_div_fixup_f32 v83, v84, v83, 1.0
	v_mul_f32_e32 v83, v83, v165
	v_mul_f32_e32 v83, 0x3c010204, v83
	v_lshl_add_u64 v[84:85], v[214:215], 2, s[26:27]
	global_store_dword v[84:85], v83, off
.LBB0_1430:
	s_or_b64 exec, exec, s[0:1]
	s_waitcnt vmcnt(14)
	v_div_scale_f32 v83, s[0:1], v165, v165, s69
	v_rcp_f32_e32 v84, v83
	v_div_scale_f32 v85, vcc, s69, v165, s69
	v_pk_mul_f32 v[88:89], v[142:143], v[14:15]
	v_fma_f32 v86, -v83, v84, 1.0
	v_fmac_f32_e32 v84, v86, v84
	v_mul_f32_e32 v86, v85, v84
	v_fma_f32 v87, -v83, v86, v85
	v_fmac_f32_e32 v86, v87, v84
	v_fma_f32 v83, -v83, v86, v85
	v_div_fmas_f32 v83, v83, v84, v86
	v_div_fixup_f32 v83, v83, v165, s69
	v_cmp_lt_f32_e32 vcc, 0, v165
	v_pk_mul_f32 v[86:87], v[144:145], v[16:17]
	v_pk_mul_f32 v[90:91], v[138:139], v[10:11]
	v_cndmask_b32_e32 v82, 0, v83, vcc
	v_pk_fma_f32 v[88:89], v[88:89], v[82:83], s[34:35] op_sel_hi:[1,0,0]
	v_pk_fma_f32 v[86:87], v[86:87], v[82:83], s[34:35] op_sel_hi:[1,0,0]
	v_lshlrev_b32_e32 v83, 8, v89
	v_and_b32_e32 v83, 0xff00, v83
	v_lshlrev_b32_e32 v86, 16, v86
	v_perm_b32 v87, v87, v88, s70
	v_pk_mul_f32 v[88:89], v[140:141], v[12:13]
	v_and_b32_e32 v86, 0xff0000, v86
	v_pk_fma_f32 v[90:91], v[90:91], v[82:83], s[34:35] op_sel_hi:[1,0,0]
	v_pk_fma_f32 v[88:89], v[88:89], v[82:83], s[34:35] op_sel_hi:[1,0,0]
	v_lshlrev_b64 v[84:85], 10, v[214:215]
	v_or3_b32 v86, v87, v83, v86
	v_lshlrev_b32_e32 v83, 8, v91
	v_lshlrev_b32_e32 v87, 16, v88
	v_and_b32_e32 v83, 0xff00, v83
	v_and_b32_e32 v87, 0xff0000, v87
	v_perm_b32 v88, v89, v90, s70
	v_lshl_add_u64 v[84:85], s[18:19], 0, v[84:85]
	v_or3_b32 v87, v88, v83, v87
	v_lshl_add_u64 v[84:85], v[84:85], 0, v[210:211]
	global_store_dwordx2 v[84:85], v[86:87], off
	v_pk_mul_f32 v[86:87], v[136:137], v[8:9]
	v_pk_mul_f32 v[88:89], v[134:135], v[6:7]
	v_pk_fma_f32 v[86:87], v[86:87], v[82:83], s[34:35] op_sel_hi:[1,0,0]
	v_pk_fma_f32 v[88:89], v[88:89], v[82:83], s[34:35] op_sel_hi:[1,0,0]
	v_lshlrev_b32_e32 v86, 16, v86
	v_lshlrev_b32_e32 v83, 8, v89
	v_and_b32_e32 v83, 0xff00, v83
	v_and_b32_e32 v86, 0xff0000, v86
	v_perm_b32 v87, v87, v88, s70
	v_pk_mul_f32 v[88:89], v[128:129], v[4:5]
	v_pk_mul_f32 v[90:91], v[126:127], v[2:3]
	v_or3_b32 v86, v87, v83, v86
	v_pk_fma_f32 v[90:91], v[90:91], v[82:83], s[34:35] op_sel_hi:[1,0,0]
	v_pk_fma_f32 v[82:83], v[88:89], v[82:83], s[34:35] op_sel_hi:[1,0,0]
	v_lshlrev_b32_e32 v87, 8, v91
	v_lshlrev_b32_e32 v82, 16, v82
	v_and_b32_e32 v87, 0xff00, v87
	v_and_b32_e32 v82, 0xff0000, v82
	v_perm_b32 v83, v83, v90, s70
	v_or3_b32 v87, v83, v87, v82
	global_store_dwordx2 v[84:85], v[86:87], off offset:128
	s_and_saveexec_b64 s[0:1], s[6:7]
	s_cbranch_execz .LBB0_1432
	s_waitcnt vmcnt(14)
	v_fmamk_f32 v83, v166, 0x3a800000, v240
	v_mul_f32_e32 v84, 0x4f800000, v83
	v_cmp_gt_f32_e32 vcc, s68, v83
	s_nop 1
	v_cndmask_b32_e32 v83, v83, v84, vcc
	v_sqrt_f32_e32 v84, v83
	s_nop 0
	v_add_u32_e32 v85, -1, v84
	v_fma_f32 v87, -v85, v84, v83
	v_add_u32_e32 v86, 1, v84
	v_cmp_ge_f32_e64 s[8:9], 0, v87
	s_nop 1
	v_cndmask_b32_e64 v85, v84, v85, s[8:9]
	v_fma_f32 v84, -v86, v84, v83
	v_cmp_lt_f32_e64 s[8:9], 0, v84
	s_nop 1
	v_cndmask_b32_e64 v84, v85, v86, s[8:9]
	v_mul_f32_e32 v85, 0x37800000, v84
	v_cndmask_b32_e32 v84, v84, v85, vcc
	v_cmp_class_f32_e32 vcc, v83, v241
	s_nop 1
	v_cndmask_b32_e32 v83, v84, v83, vcc
	v_div_scale_f32 v84, s[2:3], v83, v83, 1.0
	v_rcp_f32_e32 v85, v84
	s_nop 0
	v_fma_f32 v86, -v84, v85, 1.0
	v_fmac_f32_e32 v85, v86, v85
	v_div_scale_f32 v86, vcc, 1.0, v83, 1.0
	v_mul_f32_e32 v87, v86, v85
	v_fma_f32 v88, -v84, v87, v86
	v_fmac_f32_e32 v87, v88, v85
	v_fma_f32 v84, -v84, v87, v86
	v_div_fmas_f32 v84, v84, v85, v87
	v_div_fixup_f32 v83, v84, v83, 1.0
	v_mul_f32_e32 v83, v83, v167
	v_mul_f32_e32 v83, 0x3c010204, v83
	v_lshl_add_u64 v[84:85], v[218:219], 2, s[26:27]
	global_store_dword v[84:85], v83, off
;     __device__ __forceinline__ void operator()(f32x4 (&acc)[2][2][4][2], const Unit& u, int wr, int wc, int fr, int fq) const {
;     ...
;         for (int ai = 0; ai < 2; ++ai)
; #pragma unroll
;             for (int m = 0; m < 4; ++m) {
;                 const int row = row0 + ai * HALF + m * 16;
;                 const float ss = __hip_atomic_load(SS + row, __ATOMIC_RELAXED, __HIP_MEMORY_SCOPE_AGENT);
;                 const float rstd = 1.0f / sqrtf(ss * (1.f / 1024.f) + 1e-6f);
;                 float qs = 0.f;
;                 if constexpr (!FINAL) {
;                     const float am = __uint_as_float(__hip_atomic_load(AM + row, __ATOMIC_RELAXED, __HIP_MEMORY_SCOPE_AGENT));
;                     qs = am > 0.f ? 127.f / am : 0.f;
;                     if (u.pn == 0 && wc == 0 && fq == 0) SH[row] = am * rstd * (1.f / 127.f);
;                 }
; #pragma unroll
;                 for (int bj = 0; bj < 2; ++bj) {
;                     const size_t off = (size_t)row * 1024 + col0 + bj * HALF;
;                     const f32x4 y0 = acc[ai][bj][m][0] * rstd * gv[bj][0], y1 = acc[ai][bj][m][1] * rstd * gv[bj][1];
;                     if constexpr (FINAL) { *(f32x4*)(out + off) = y0; *(f32x4*)(out + off + 4) = y1; }
;                     else {
;                         u32x2 q8; q8.x = q8x4(acc[ai][bj][m][0] * gv[bj][0], qs); q8.y = q8x4(acc[ai][bj][m][1] * gv[bj][1], qs);
;                         *(u32x2*)(H8 + off) = q8;
;                     }
;                 }
.LBB0_1432:
	s_or_b64 exec, exec, s[0:1]
	s_waitcnt vmcnt(14)
	v_div_scale_f32 v83, s[0:1], v167, v167, s69
	v_rcp_f32_e32 v84, v83
	v_div_scale_f32 v85, vcc, s69, v167, s69
	v_pk_mul_f32 v[80:81], v[80:81], v[16:17]
	v_fma_f32 v86, -v83, v84, 1.0
	v_fmac_f32_e32 v84, v86, v84
	v_mul_f32_e32 v86, v85, v84
	v_fma_f32 v87, -v83, v86, v85
	v_fmac_f32_e32 v86, v87, v84
	v_fma_f32 v83, -v83, v86, v85
	v_div_fmas_f32 v83, v83, v84, v86
	v_div_fixup_f32 v83, v83, v167, s69
	v_cmp_lt_f32_e32 vcc, 0, v167
	v_pk_mul_f32 v[78:79], v[78:79], v[14:15]
	v_pk_mul_f32 v[76:77], v[76:77], v[12:13]
	v_cndmask_b32_e32 v82, 0, v83, vcc
	v_pk_mul_f32 v[74:75], v[74:75], v[10:11]
	v_pk_fma_f32 v[78:79], v[78:79], v[82:83], s[34:35] op_sel_hi:[1,0,0]
	v_pk_fma_f32 v[80:81], v[80:81], v[82:83], s[34:35] op_sel_hi:[1,0,0]
	v_pk_fma_f32 v[74:75], v[74:75], v[82:83], s[34:35] op_sel_hi:[1,0,0]
	v_pk_fma_f32 v[76:77], v[76:77], v[82:83], s[34:35] op_sel_hi:[1,0,0]
	v_pk_mul_f32 v[72:73], v[72:73], v[8:9]
	v_pk_mul_f32 v[70:71], v[70:71], v[6:7]
	v_pk_mul_f32 v[68:69], v[68:69], v[4:5]
	v_pk_mul_f32 v[66:67], v[66:67], v[2:3]
	v_lshlrev_b32_e32 v79, 8, v79
	v_lshlrev_b32_e32 v80, 16, v80
	v_lshlrev_b32_e32 v75, 8, v75
	v_lshlrev_b32_e32 v76, 16, v76
	v_pk_fma_f32 v[70:71], v[70:71], v[82:83], s[34:35] op_sel_hi:[1,0,0]
	v_pk_fma_f32 v[72:73], v[72:73], v[82:83], s[34:35] op_sel_hi:[1,0,0]
	v_pk_fma_f32 v[66:67], v[66:67], v[82:83], s[34:35] op_sel_hi:[1,0,0]
	v_pk_fma_f32 v[68:69], v[68:69], v[82:83], s[34:35] op_sel_hi:[1,0,0]
	v_lshlrev_b64 v[84:85], 10, v[218:219]
	v_and_b32_e32 v79, 0xff00, v79
	v_and_b32_e32 v80, 0xff0000, v80
	v_perm_b32 v78, v81, v78, s70
	v_and_b32_e32 v75, 0xff00, v75
	v_and_b32_e32 v76, 0xff0000, v76
	v_perm_b32 v74, v77, v74, s70
	v_lshlrev_b32_e32 v71, 8, v71
	v_lshlrev_b32_e32 v72, 16, v72
	v_lshlrev_b32_e32 v67, 8, v67
	v_lshlrev_b32_e32 v68, 16, v68
	v_or3_b32 v78, v78, v79, v80
	v_or3_b32 v79, v74, v75, v76
	v_lshl_add_u64 v[74:75], s[18:19], 0, v[84:85]
	v_and_b32_e32 v71, 0xff00, v71
	v_and_b32_e32 v72, 0xff0000, v72
	v_perm_b32 v70, v73, v70, s70
	v_and_b32_e32 v67, 0xff00, v67
	v_and_b32_e32 v68, 0xff0000, v68
	v_perm_b32 v66, v69, v66, s70
	v_lshl_add_u64 v[74:75], v[74:75], 0, v[210:211]
	v_or3_b32 v70, v70, v71, v72
	v_or3_b32 v71, v66, v67, v68
	global_store_dwordx2 v[74:75], v[78:79], off
	global_store_dwordx2 v[74:75], v[70:71], off offset:128
	s_and_saveexec_b64 s[0:1], s[6:7]
	s_cbranch_execz .LBB0_1434
	s_waitcnt vmcnt(14)
	v_fmamk_f32 v67, v168, 0x3a800000, v240
	v_mul_f32_e32 v68, 0x4f800000, v67
	v_cmp_gt_f32_e32 vcc, s68, v67
	s_nop 1
	v_cndmask_b32_e32 v67, v67, v68, vcc
	v_sqrt_f32_e32 v68, v67
	s_nop 0
	v_add_u32_e32 v69, -1, v68
	v_fma_f32 v71, -v69, v68, v67
	v_add_u32_e32 v70, 1, v68
	v_cmp_ge_f32_e64 s[8:9], 0, v71
	s_nop 1
	v_cndmask_b32_e64 v69, v68, v69, s[8:9]
	v_fma_f32 v68, -v70, v68, v67
	v_cmp_lt_f32_e64 s[8:9], 0, v68
	s_nop 1
	v_cndmask_b32_e64 v68, v69, v70, s[8:9]
	v_mul_f32_e32 v69, 0x37800000, v68
	v_cndmask_b32_e32 v68, v68, v69, vcc
	v_cmp_class_f32_e32 vcc, v67, v241
	s_nop 1
	v_cndmask_b32_e32 v67, v68, v67, vcc
	v_div_scale_f32 v68, s[2:3], v67, v67, 1.0
	v_rcp_f32_e32 v69, v68
	s_nop 0
	v_fma_f32 v70, -v68, v69, 1.0
	v_fmac_f32_e32 v69, v70, v69
	v_div_scale_f32 v70, vcc, 1.0, v67, 1.0
	v_mul_f32_e32 v71, v70, v69
	v_fma_f32 v72, -v68, v71, v70
	v_fmac_f32_e32 v71, v72, v69
	v_fma_f32 v68, -v68, v71, v70
	v_div_fmas_f32 v68, v68, v69, v71
	v_div_fixup_f32 v67, v68, v67, 1.0
	v_mul_f32_e32 v67, v67, v169
	v_mul_f32_e32 v67, 0x3c010204, v67
	v_lshl_add_u64 v[68:69], v[220:221], 2, s[26:27]
	global_store_dword v[68:69], v67, off
.LBB0_1434:
	s_or_b64 exec, exec, s[0:1]
	s_waitcnt vmcnt(14)
	v_div_scale_f32 v67, s[0:1], v169, v169, s69
	v_rcp_f32_e32 v68, v67
	v_div_scale_f32 v69, vcc, s69, v169, s69
	v_pk_mul_f32 v[64:65], v[64:65], v[16:17]
	v_fma_f32 v70, -v67, v68, 1.0
	v_fmac_f32_e32 v68, v70, v68
	v_mul_f32_e32 v70, v69, v68
	v_fma_f32 v71, -v67, v70, v69
	v_fmac_f32_e32 v70, v71, v68
	v_fma_f32 v67, -v67, v70, v69
	v_div_fmas_f32 v67, v67, v68, v70
	v_div_fixup_f32 v67, v67, v169, s69
	v_cmp_lt_f32_e32 vcc, 0, v169
	v_pk_mul_f32 v[62:63], v[62:63], v[14:15]
	v_pk_mul_f32 v[60:61], v[60:61], v[12:13]
	v_cndmask_b32_e32 v66, 0, v67, vcc
	v_pk_mul_f32 v[58:59], v[58:59], v[10:11]
	v_pk_fma_f32 v[62:63], v[62:63], v[66:67], s[34:35] op_sel_hi:[1,0,0]
	v_pk_fma_f32 v[64:65], v[64:65], v[66:67], s[34:35] op_sel_hi:[1,0,0]
	v_pk_fma_f32 v[58:59], v[58:59], v[66:67], s[34:35] op_sel_hi:[1,0,0]
	v_pk_fma_f32 v[60:61], v[60:61], v[66:67], s[34:35] op_sel_hi:[1,0,0]
	v_pk_mul_f32 v[56:57], v[56:57], v[8:9]
	v_pk_mul_f32 v[54:55], v[54:55], v[6:7]
	v_pk_mul_f32 v[52:53], v[52:53], v[4:5]
	v_pk_mul_f32 v[50:51], v[50:51], v[2:3]
	v_lshlrev_b32_e32 v63, 8, v63
	v_lshlrev_b32_e32 v64, 16, v64
	v_lshlrev_b32_e32 v59, 8, v59
	v_lshlrev_b32_e32 v60, 16, v60
	v_pk_fma_f32 v[54:55], v[54:55], v[66:67], s[34:35] op_sel_hi:[1,0,0]
	v_pk_fma_f32 v[56:57], v[56:57], v[66:67], s[34:35] op_sel_hi:[1,0,0]
	v_pk_fma_f32 v[50:51], v[50:51], v[66:67], s[34:35] op_sel_hi:[1,0,0]
	v_pk_fma_f32 v[52:53], v[52:53], v[66:67], s[34:35] op_sel_hi:[1,0,0]
	v_lshlrev_b64 v[68:69], 10, v[220:221]
	v_and_b32_e32 v63, 0xff00, v63
	v_and_b32_e32 v64, 0xff0000, v64
	v_perm_b32 v62, v65, v62, s70
	v_and_b32_e32 v59, 0xff00, v59
	v_and_b32_e32 v60, 0xff0000, v60
	v_perm_b32 v58, v61, v58, s70
	v_lshlrev_b32_e32 v55, 8, v55
	v_lshlrev_b32_e32 v56, 16, v56
	v_lshlrev_b32_e32 v51, 8, v51
	v_lshlrev_b32_e32 v52, 16, v52
	v_or3_b32 v62, v62, v63, v64
	v_or3_b32 v63, v58, v59, v60
	v_lshl_add_u64 v[58:59], s[18:19], 0, v[68:69]
	v_and_b32_e32 v55, 0xff00, v55
	v_and_b32_e32 v56, 0xff0000, v56
	v_perm_b32 v54, v57, v54, s70
	v_and_b32_e32 v51, 0xff00, v51
	v_and_b32_e32 v52, 0xff0000, v52
	v_perm_b32 v50, v53, v50, s70
	v_lshl_add_u64 v[58:59], v[58:59], 0, v[210:211]
	v_or3_b32 v54, v54, v55, v56
	v_or3_b32 v55, v50, v51, v52
	global_store_dwordx2 v[58:59], v[62:63], off
	global_store_dwordx2 v[58:59], v[54:55], off offset:128
	s_and_saveexec_b64 s[0:1], s[6:7]
	s_cbranch_execz .LBB0_1436
;     __device__ __forceinline__ void operator()(f32x4 (&acc)[2][2][4][2], const Unit& u, int wr, int wc, int fr, int fq) const {
;     ...
;         for (int ai = 0; ai < 2; ++ai)
; #pragma unroll
;             for (int m = 0; m < 4; ++m) {
;                 const int row = row0 + ai * HALF + m * 16;
;                 const float ss = __hip_atomic_load(SS + row, __ATOMIC_RELAXED, __HIP_MEMORY_SCOPE_AGENT);
;                 const float rstd = 1.0f / sqrtf(ss * (1.f / 1024.f) + 1e-6f);
;                 float qs = 0.f;
;                 if constexpr (!FINAL) {
;                     const float am = __uint_as_float(__hip_atomic_load(AM + row, __ATOMIC_RELAXED, __HIP_MEMORY_SCOPE_AGENT));
;                     qs = am > 0.f ? 127.f / am : 0.f;
;                     if (u.pn == 0 && wc == 0 && fq == 0) SH[row] = am * rstd * (1.f / 127.f);
;                 }
; #pragma unroll
;                 for (int bj = 0; bj < 2; ++bj) {
;                     const size_t off = (size_t)row * 1024 + col0 + bj * HALF;
;                     const f32x4 y0 = acc[ai][bj][m][0] * rstd * gv[bj][0], y1 = acc[ai][bj][m][1] * rstd * gv[bj][1];
;                     if constexpr (FINAL) { *(f32x4*)(out + off) = y0; *(f32x4*)(out + off + 4) = y1; }
;                     else {
;                         u32x2 q8; q8.x = q8x4(acc[ai][bj][m][0] * gv[bj][0], qs); q8.y = q8x4(acc[ai][bj][m][1] * gv[bj][1], qs);
;                         *(u32x2*)(H8 + off) = q8;
;                     }
;                 }
	s_waitcnt vmcnt(14)
	v_fmamk_f32 v51, v170, 0x3a800000, v240
	v_mul_f32_e32 v52, 0x4f800000, v51
	v_cmp_gt_f32_e32 vcc, s68, v51
	s_nop 1
	v_cndmask_b32_e32 v51, v51, v52, vcc
	v_sqrt_f32_e32 v52, v51
	s_nop 0
	v_add_u32_e32 v53, -1, v52
	v_fma_f32 v55, -v53, v52, v51
	v_add_u32_e32 v54, 1, v52
	v_cmp_ge_f32_e64 s[8:9], 0, v55
	s_nop 1
	v_cndmask_b32_e64 v53, v52, v53, s[8:9]
	v_fma_f32 v52, -v54, v52, v51
	v_cmp_lt_f32_e64 s[8:9], 0, v52
	s_nop 1
	v_cndmask_b32_e64 v52, v53, v54, s[8:9]
	v_mul_f32_e32 v53, 0x37800000, v52
	v_cndmask_b32_e32 v52, v52, v53, vcc
	v_cmp_class_f32_e32 vcc, v51, v241
	s_nop 1
	v_cndmask_b32_e32 v51, v52, v51, vcc
	v_div_scale_f32 v52, s[2:3], v51, v51, 1.0
	v_rcp_f32_e32 v53, v52
	s_nop 0
	v_fma_f32 v54, -v52, v53, 1.0
	v_fmac_f32_e32 v53, v54, v53
	v_div_scale_f32 v54, vcc, 1.0, v51, 1.0
	v_mul_f32_e32 v55, v54, v53
	v_fma_f32 v56, -v52, v55, v54
	v_fmac_f32_e32 v55, v56, v53
	v_fma_f32 v52, -v52, v55, v54
	v_div_fmas_f32 v52, v52, v53, v55
	v_div_fixup_f32 v51, v52, v51, 1.0
	v_mul_f32_e32 v51, v51, v171
	v_mul_f32_e32 v51, 0x3c010204, v51
	v_lshl_add_u64 v[52:53], v[222:223], 2, s[26:27]
	global_store_dword v[52:53], v51, off
.LBB0_1436:
	s_or_b64 exec, exec, s[0:1]
	s_waitcnt vmcnt(14)
	v_div_scale_f32 v51, s[0:1], v171, v171, s69
	v_rcp_f32_e32 v52, v51
	v_div_scale_f32 v53, vcc, s69, v171, s69
	v_pk_mul_f32 v[48:49], v[48:49], v[16:17]
	v_fma_f32 v54, -v51, v52, 1.0
	v_fmac_f32_e32 v52, v54, v52
	v_mul_f32_e32 v54, v53, v52
	v_fma_f32 v55, -v51, v54, v53
	v_fmac_f32_e32 v54, v55, v52
	v_fma_f32 v51, -v51, v54, v53
	v_div_fmas_f32 v51, v51, v52, v54
	v_div_fixup_f32 v51, v51, v171, s69
	v_cmp_lt_f32_e32 vcc, 0, v171
	v_pk_mul_f32 v[46:47], v[46:47], v[14:15]
	v_pk_mul_f32 v[44:45], v[44:45], v[12:13]
	v_cndmask_b32_e32 v50, 0, v51, vcc
	v_pk_mul_f32 v[42:43], v[42:43], v[10:11]
	v_pk_fma_f32 v[46:47], v[46:47], v[50:51], s[34:35] op_sel_hi:[1,0,0]
	v_pk_fma_f32 v[48:49], v[48:49], v[50:51], s[34:35] op_sel_hi:[1,0,0]
	v_pk_fma_f32 v[42:43], v[42:43], v[50:51], s[34:35] op_sel_hi:[1,0,0]
	v_pk_fma_f32 v[44:45], v[44:45], v[50:51], s[34:35] op_sel_hi:[1,0,0]
	v_pk_mul_f32 v[40:41], v[40:41], v[8:9]
	v_pk_mul_f32 v[38:39], v[38:39], v[6:7]
	v_pk_mul_f32 v[36:37], v[36:37], v[4:5]
	v_pk_mul_f32 v[34:35], v[34:35], v[2:3]
	v_lshlrev_b32_e32 v47, 8, v47
	v_lshlrev_b32_e32 v48, 16, v48
	v_lshlrev_b32_e32 v43, 8, v43
	v_lshlrev_b32_e32 v44, 16, v44
	v_pk_fma_f32 v[38:39], v[38:39], v[50:51], s[34:35] op_sel_hi:[1,0,0]
	v_pk_fma_f32 v[40:41], v[40:41], v[50:51], s[34:35] op_sel_hi:[1,0,0]
	v_pk_fma_f32 v[34:35], v[34:35], v[50:51], s[34:35] op_sel_hi:[1,0,0]
	v_pk_fma_f32 v[36:37], v[36:37], v[50:51], s[34:35] op_sel_hi:[1,0,0]
	v_lshlrev_b64 v[52:53], 10, v[222:223]
	v_and_b32_e32 v47, 0xff00, v47
	v_and_b32_e32 v48, 0xff0000, v48
	v_perm_b32 v46, v49, v46, s70
	v_and_b32_e32 v43, 0xff00, v43
	v_and_b32_e32 v44, 0xff0000, v44
	v_perm_b32 v42, v45, v42, s70
	v_lshlrev_b32_e32 v39, 8, v39
	v_lshlrev_b32_e32 v40, 16, v40
	v_lshlrev_b32_e32 v35, 8, v35
	v_lshlrev_b32_e32 v36, 16, v36
	v_or3_b32 v46, v46, v47, v48
	v_or3_b32 v47, v42, v43, v44
	v_lshl_add_u64 v[42:43], s[18:19], 0, v[52:53]
	v_and_b32_e32 v39, 0xff00, v39
	v_and_b32_e32 v40, 0xff0000, v40
	v_perm_b32 v38, v41, v38, s70
	v_and_b32_e32 v35, 0xff00, v35
	v_and_b32_e32 v36, 0xff0000, v36
	v_perm_b32 v34, v37, v34, s70
	v_lshl_add_u64 v[42:43], v[42:43], 0, v[210:211]
	v_or3_b32 v38, v38, v39, v40
	v_or3_b32 v39, v34, v35, v36
	global_store_dwordx2 v[42:43], v[46:47], off
	global_store_dwordx2 v[42:43], v[38:39], off offset:128
	s_and_saveexec_b64 s[0:1], s[6:7]
	s_cbranch_execz .LBB0_1438
	s_waitcnt vmcnt(14)
	v_fmamk_f32 v35, v172, 0x3a800000, v240
	v_mul_f32_e32 v36, 0x4f800000, v35
	v_cmp_gt_f32_e32 vcc, s68, v35
	s_nop 1
	v_cndmask_b32_e32 v35, v35, v36, vcc
	v_sqrt_f32_e32 v36, v35
	s_nop 0
	v_add_u32_e32 v37, -1, v36
	v_fma_f32 v39, -v37, v36, v35
	v_add_u32_e32 v38, 1, v36
	v_cmp_ge_f32_e64 s[6:7], 0, v39
	s_nop 1
	v_cndmask_b32_e64 v37, v36, v37, s[6:7]
	v_fma_f32 v36, -v38, v36, v35
	v_cmp_lt_f32_e64 s[6:7], 0, v36
	s_nop 1
	v_cndmask_b32_e64 v36, v37, v38, s[6:7]
	v_mul_f32_e32 v37, 0x37800000, v36
	v_cndmask_b32_e32 v36, v36, v37, vcc
	v_cmp_class_f32_e32 vcc, v35, v241
	s_nop 1
	v_cndmask_b32_e32 v35, v36, v35, vcc
	v_div_scale_f32 v36, s[2:3], v35, v35, 1.0
	v_rcp_f32_e32 v37, v36
	s_nop 0
	v_fma_f32 v38, -v36, v37, 1.0
	v_fmac_f32_e32 v37, v38, v37
	v_div_scale_f32 v38, vcc, 1.0, v35, 1.0
	v_mul_f32_e32 v39, v38, v37
	v_fma_f32 v40, -v36, v39, v38
	v_fmac_f32_e32 v39, v40, v37
	v_fma_f32 v36, -v36, v39, v38
	v_div_fmas_f32 v36, v36, v37, v39
	v_div_fixup_f32 v35, v36, v35, 1.0
	v_mul_f32_e32 v35, v35, v173
	v_mul_f32_e32 v35, 0x3c010204, v35
	v_lshl_add_u64 v[36:37], v[226:227], 2, s[26:27]
	global_store_dword v[36:37], v35, off
; #define PG8_BAR __builtin_amdgcn_s_barrier()
;     __device__ __forceinline__ void operator()(f32x4 (&acc)[2][2][4][2], const Unit& u, int wr, int wc, int fr, int fq) const {
;     ...
;         for (int ai = 0; ai < 2; ++ai)
; #pragma unroll
;             for (int m = 0; m < 4; ++m) {
;                 const int row = row0 + ai * HALF + m * 16;
;                 const float ss = __hip_atomic_load(SS + row, __ATOMIC_RELAXED, __HIP_MEMORY_SCOPE_AGENT);
;                 const float rstd = 1.0f / sqrtf(ss * (1.f / 1024.f) + 1e-6f);
;                 float qs = 0.f;
;                 if constexpr (!FINAL) {
;                     const float am = __uint_as_float(__hip_atomic_load(AM + row, __ATOMIC_RELAXED, __HIP_MEMORY_SCOPE_AGENT));
;                     qs = am > 0.f ? 127.f / am : 0.f;
;                     if (u.pn == 0 && wc == 0 && fq == 0) SH[row] = am * rstd * (1.f / 127.f);
;                 }
; #pragma unroll
;                 for (int bj = 0; bj < 2; ++bj) {
;                     const size_t off = (size_t)row * 1024 + col0 + bj * HALF;
;                     const f32x4 y0 = acc[ai][bj][m][0] * rstd * gv[bj][0], y1 = acc[ai][bj][m][1] * rstd * gv[bj][1];
;                     if constexpr (FINAL) { *(f32x4*)(out + off) = y0; *(f32x4*)(out + off + 4) = y1; }
;                     else {
;                         u32x2 q8; q8.x = q8x4(acc[ai][bj][m][0] * gv[bj][0], qs); q8.y = q8x4(acc[ai][bj][m][1] * gv[bj][1], qs);
;                         *(u32x2*)(H8 + off) = q8;
;                     }
;                 }
; template <class Epi, class Sched, class Gemm, bool ALIGN_EPI = false, bool SP2 = false>
; __device__ __forceinline__ void gemm_phase(PG8_LAS unsigned char* lds, const Gemm g, const Sched& S, const Epi& E) {
;     ...
;         if (!has_next) break;
;         if constexpr (!epi_chain<Epi>::value) {
; #pragma unroll
;         for (int a = 0; a < 2; ++a)
; #pragma unroll
;             for (int b = 0; b < 2; ++b)
; #pragma unroll
;                 for (int m = 0; m < 4; ++m)
; #pragma unroll
;                     for (int n = 0; n < 2; ++n) acc[a][b][m][n] = (f32x4){0.f, 0.f, 0.f, 0.f};
;         }
;         cur = nxt; cA = nA; cB = nB; ++ui;
;         if constexpr (ALIGN_EPI) { if (wr == 1) PG8_BAR; }
.LBB0_1438:
	s_or_b64 exec, exec, s[0:1]
	s_waitcnt vmcnt(14)
	v_div_scale_f32 v35, s[0:1], v173, v173, s69
	v_rcp_f32_e32 v36, v35
	v_div_scale_f32 v37, vcc, s69, v173, s69
	v_pk_mul_f32 v[16:17], v[32:33], v[16:17]
	v_fma_f32 v38, -v35, v36, 1.0
	v_fmac_f32_e32 v36, v38, v36
	v_mul_f32_e32 v38, v37, v36
	v_fma_f32 v39, -v35, v38, v37
	v_fmac_f32_e32 v38, v39, v36
	v_fma_f32 v35, -v35, v38, v37
	v_div_fmas_f32 v35, v35, v36, v38
	v_div_fixup_f32 v35, v35, v173, s69
	v_cmp_lt_f32_e32 vcc, 0, v173
	v_pk_mul_f32 v[14:15], v[30:31], v[14:15]
	v_pk_mul_f32 v[12:13], v[28:29], v[12:13]
	v_cndmask_b32_e32 v34, 0, v35, vcc
	v_pk_mul_f32 v[10:11], v[26:27], v[10:11]
	v_pk_fma_f32 v[14:15], v[14:15], v[34:35], s[34:35] op_sel_hi:[1,0,0]
	v_pk_fma_f32 v[16:17], v[16:17], v[34:35], s[34:35] op_sel_hi:[1,0,0]
	v_pk_fma_f32 v[10:11], v[10:11], v[34:35], s[34:35] op_sel_hi:[1,0,0]
	v_pk_fma_f32 v[12:13], v[12:13], v[34:35], s[34:35] op_sel_hi:[1,0,0]
	v_pk_mul_f32 v[8:9], v[24:25], v[8:9]
	v_pk_mul_f32 v[6:7], v[22:23], v[6:7]
	v_pk_mul_f32 v[4:5], v[20:21], v[4:5]
	v_pk_mul_f32 v[2:3], v[18:19], v[2:3]
	v_lshlrev_b32_e32 v15, 8, v15
	v_lshlrev_b32_e32 v16, 16, v16
	v_lshlrev_b32_e32 v11, 8, v11
	v_lshlrev_b32_e32 v12, 16, v12
	v_pk_fma_f32 v[6:7], v[6:7], v[34:35], s[34:35] op_sel_hi:[1,0,0]
	v_pk_fma_f32 v[8:9], v[8:9], v[34:35], s[34:35] op_sel_hi:[1,0,0]
	v_pk_fma_f32 v[2:3], v[2:3], v[34:35], s[34:35] op_sel_hi:[1,0,0]
	v_pk_fma_f32 v[4:5], v[4:5], v[34:35], s[34:35] op_sel_hi:[1,0,0]
	v_lshlrev_b64 v[36:37], 10, v[226:227]
	v_and_b32_e32 v15, 0xff00, v15
	v_and_b32_e32 v16, 0xff0000, v16
	v_perm_b32 v14, v17, v14, s70
	v_and_b32_e32 v11, 0xff00, v11
	v_and_b32_e32 v12, 0xff0000, v12
	v_perm_b32 v10, v13, v10, s70
	v_lshlrev_b32_e32 v7, 8, v7
	v_lshlrev_b32_e32 v8, 16, v8
	v_lshlrev_b32_e32 v3, 8, v3
	v_lshlrev_b32_e32 v4, 16, v4
	v_or3_b32 v14, v14, v15, v16
	v_or3_b32 v15, v10, v11, v12
	v_lshl_add_u64 v[10:11], s[18:19], 0, v[36:37]
	v_and_b32_e32 v7, 0xff00, v7
	v_and_b32_e32 v8, 0xff0000, v8
	v_perm_b32 v6, v9, v6, s70
	v_and_b32_e32 v3, 0xff00, v3
	v_and_b32_e32 v4, 0xff0000, v4
	v_perm_b32 v2, v5, v2, s70
	v_lshl_add_u64 v[10:11], v[10:11], 0, v[210:211]
	v_or3_b32 v6, v6, v7, v8
	v_or3_b32 v7, v2, v3, v4
	s_andn2_b64 vcc, exec, s[4:5]
	s_mov_b64 s[0:1], -1
	global_store_dwordx2 v[10:11], v[14:15], off
	global_store_dwordx2 v[10:11], v[6:7], off offset:128
	s_cbranch_vccnz .LBB0_1362
	s_andn2_b64 vcc, exec, s[20:21]
	s_cbranch_vccnz .LBB0_1361
	s_barrier
	s_branch .LBB0_1361

; #define TIDX opq((int)threadIdx.x)
; #define PG8_STAGE(bufoff, gbase, voff) do { _Pragma("unroll") for (int _i = 0; _i < 2; ++_i) \
;         __builtin_amdgcn_global_load_lds((const unsigned*)((const char*)(gbase) + (voff)[_i]), (PG8_LAS unsigned*)(lds + (bufoff) + ldsw + _i * 8192), 16, 0, 0); } while (0)
; #define PG8_WAIT_V(n) asm volatile("s_waitcnt vmcnt(" #n ")" ::: "memory")
; #define PG8_BAR __builtin_amdgcn_s_barrier()
; template <class Epi, class Sched, class Gemm, bool ALIGN_EPI = false, bool SP2 = false>
; __device__ __forceinline__ void gemm_phase(PG8_LAS unsigned char* lds, const Gemm g, const Sched& S, const Epi& E) {
;     const int tid = TIDX, wid = __builtin_amdgcn_readfirstlane(tid >> 6), lane = tid & 63, wr = wid >> 2, wc = wid & 3, fr = lane & 15, fq = lane >> 4;
;     constexpr int K = Gemm::K, nt = K / BK, lda = Gemm::lda, ldb = Gemm::ldb;
;     constexpr int BP = epi_bperm<Epi>::value;
;     unsigned voffA[2], voffB[2], voffB1[2];
; #pragma unroll
;     for (int i = 0; i < 2; ++i) { int R, C; stage_rc(tid * 16 + i * 8192, R, C);
;         voffA[i] = (unsigned)(R * lda + C) * 2u;
;         if constexpr (BP == 2) { const int w_ = R >> 5, n_ = (R >> 4) & 1, j_ = R & 15, cb_ = w_ * 64 + 16 * (j_ >> 2) + 4 * n_ + (j_ & 3);
;             voffB[i] = (unsigned)(cb_ * ldb + C) * 2u; voffB1[i] = voffB[i]; }
;         else { const int Rb = (BP == 1) ? ((R & ~31) + perm32(R & 31)) : R; voffB[i] = (unsigned)(Rb * ldb + C) * 2u; voffB1[i] = voffB[i]; } }
;     const size_t kstep = (size_t)(BK * 2);
;     const size_t hstepA = (size_t)HALF * lda * 2, hstepB = (size_t)HALF * ldb * 2, hB1 = (BP == 2) ? (size_t)8 * ldb * 2 : hstepB;
;     const size_t tstepA = 2 * hstepA, tstepB = 2 * hstepB;
;     const unsigned ldsw = (unsigned)wid * 1024u;
;     const int aoff = lds_byte(wr * 64 + fr, fq * 8), boff = lds_byte(wc * 32 + fr, fq * 8);
;     ...
;     if constexpr (SP2) {
;         PG8_STAGE(PG8_SB(0, 0), cB, voffB); PG8_STAGE(PG8_SB(0, 1), cB + hB1, voffB1); PG8_STAGE(PG8_SA(0, 0), cA, voffA); PG8_STAGE(PG8_SA(0, 1), cA + hstepA, voffA);
;         if (wr == 1) PG8_BAR;
;         PG8_WAIT_V(2); PG8_BAR;
;         PG8_STAGE(PG8_SB(1, 0), cB + kstep, voffB); PG8_STAGE(PG8_SA(1, 0), cA + kstep, voffA); PG8_STAGE(PG8_SB(1, 1), cB + hB1 + kstep, voffB1);
;         PG8_WAIT_V(6); PG8_BAR;
.LBB0_2542:
	s_add_u32 s14, s14, 0x4000
	s_addc_u32 s15, s15, 0
	s_add_u32 s16, s12, 0x1dd2c000
	s_addc_u32 s17, s13, 0
	s_and_b32 s22, s18, 3
	s_lshl_b32 s50, s19, 6
	s_lshl_b32 s24, s19, 13
	s_lshl_b32 s26, s22, 12
	s_add_u32 s12, s12, 0x1dd08000
	s_mov_b64 s[18:19], 0x80
	s_addc_u32 s13, s13, 0
	s_add_i32 m0, s39, 0x18000
	v_lshl_add_u64 v[8:9], v[8:9], 0, s[18:19]
	s_waitcnt vmcnt(2)
	s_barrier
	global_load_lds_dwordx4 v[8:9], off
	v_lshl_add_u64 v[6:7], v[6:7], 0, s[18:19]
	s_add_i32 m0, s39, 0x1a000
	s_add_i32 s51, s39, 0x8000
	s_add_i32 s52, s39, 0xa000
	global_load_lds_dwordx4 v[6:7], off
	v_lshl_add_u64 v[2:3], v[2:3], 0, s[18:19]
	s_mov_b32 m0, s51
	s_add_u32 s20, s0, 0x2080
	global_load_lds_dwordx4 v[2:3], off
	v_lshl_add_u64 v[2:3], v[4:5], 0, s[18:19]
	s_mov_b32 m0, s52
	s_addc_u32 s21, s1, 0
	global_load_lds_dwordx4 v[2:3], off
	s_add_i32 m0, s39, 0x1c000
	v_lshl_add_u64 v[2:3], s[20:21], 0, v[148:149]
	global_load_lds_dwordx4 v[2:3], off
	v_lshl_add_u64 v[2:3], s[20:21], 0, v[152:153]
	s_add_i32 m0, s39, 0x1e000
	v_bfe_u32 v179, v10, 4, 2
	global_load_lds_dwordx4 v[2:3], off
	v_and_b32_e32 v1, 15, v10
	v_lshlrev_b32_e32 v2, 4, v179
	v_lshlrev_b32_e32 v3, 2, v10
	v_lshl_or_b32 v2, v1, 6, v2
	v_and_b32_e32 v3, 32, v3
	v_bitop3_b32 v4, v2, s24, v3 bitop3:0xde
	v_bitop3_b32 v181, v2, s26, v3 bitop3:0xde
	v_lshlrev_b32_e32 v2, 13, v14
	v_and_b32_e32 v2, 0xffffc000, v2
	v_lshl_add_u32 v2, v15, 10, v2
	v_and_b32_e32 v3, 1, v14
	v_lshl_or_b32 v2, v3, 6, v2
	v_lshl_add_u32 v156, v16, 1, v2
	v_lshlrev_b32_e32 v2, 13, v11
	v_and_b32_e32 v2, 0xffffc000, v2
	s_waitcnt vmcnt(6)
	s_cmpk_lt_u32 s5, 0x100
	v_lshl_add_u32 v2, v12, 10, v2
	v_and_b32_e32 v3, 1, v11
	s_cselect_b64 s[20:21], -1, 0
	v_lshl_or_b32 v2, v3, 6, v2
	s_add_i32 s55, 0, 0x10000
	s_add_i32 s56, 0, 0x14000
	s_sext_i32_i8 s59, s4
	s_lshl_b32 s53, s22, 6
	s_ashr_i32 s54, s23, 31
	v_mov_b32_e32 v157, v155
	v_lshl_add_u32 v158, v13, 1, v2
	v_mov_b32_e32 v159, v155
	v_mov_b64_e32 v[252:253], 0x800
	v_add_u32_e32 v183, s55, v181
	v_add_u32_e32 v185, s56, v181
	v_add_u32_e32 v187, 0, v4
	s_mov_b32 s22, 0xbfb8aa3b
	s_movk_i32 s57, 0x2200
	s_mov_b32 s24, 0x4b000000
	s_mov_b32 s26, 0x437f0000
	s_mov_b32 s58, 0xc0c0400
	s_barrier
	s_waitcnt vmcnt(0)
	s_nop 0
	s_branch .LBB0_2545

;     __device__ bool next(int i, Unit& u) const { const bool ok = StaticOrder::next(i >> 2, u); u.sub = i & 3; return ok; }
; template <class Epi, class Sched, class Gemm, bool ALIGN_EPI = false, bool SP2 = false>
; __device__ __forceinline__ void gemm_phase(PG8_LAS unsigned char* lds, const Gemm g, const Sched& S, const Epi& E) {
;     ...
;         const bool has_next = S.next(ui + 1, nxt);
;         const char* nA = has_next ? (const char*)g.A + (size_t)nxt.pm * tstepA + (size_t)nxt.sub * g.a_sub : cA; const char* nB = has_next ? (const char*)g.Bt + (size_t)nxt.pn * tstepB + (size_t)nxt.sub * g.b_sub : cB;
;     ...
;         if constexpr (!epi_chain<Epi>::value) {
; #pragma unroll
;         for (int a = 0; a < 2; ++a)
; #pragma unroll
;             for (int b = 0; b < 2; ++b)
; #pragma unroll
;                 for (int m = 0; m < 4; ++m)
; #pragma unroll
;                     for (int n = 0; n < 2; ++n) acc[a][b][m][n] = (f32x4){0.f, 0.f, 0.f, 0.f};
;         }
;         cur = nxt; cA = nA; cB = nB; ++ui;
.LBB0_2551:
	s_ashr_i32 s31, s30, 31
	s_lshl_b64 s[34:35], s[30:31], 18
	s_add_u32 s34, s44, s34
	s_addc_u32 s35, s45, s35
	s_and_b64 s[36:37], s[4:5], exec
	s_cselect_b32 s31, s35, s3
	s_cselect_b32 s60, s34, s2
	s_ashr_i32 s29, s28, 31
	s_lshl_b64 s[36:37], s[28:29], 18
	s_add_u32 s36, s33, s36
	s_addc_u32 s37, s42, s37
	s_and_b64 s[40:41], s[4:5], exec
	s_cselect_b32 s29, s37, s1
	s_cselect_b32 s61, s36, s0
	s_add_u32 s62, s0, 0x100
	s_addc_u32 s63, s1, 0
	s_add_u32 s0, s2, 0x20080
	v_mov_b32_e32 v2, 0
	s_addc_u32 s1, s3, 0
	s_mov_b32 s64, -2
	v_mov_b32_e32 v3, v2
	v_mov_b32_e32 v4, v2
	v_mov_b32_e32 v5, v2
	v_mov_b32_e32 v6, v2
	v_mov_b32_e32 v7, v2
	v_mov_b32_e32 v8, v2
	v_mov_b32_e32 v9, v2
	s_nop 0
	v_mov_b64_e32 v[18:19], 0
	v_mov_b64_e32 v[20:21], 0
	v_mov_b64_e32 v[22:23], 0
	v_mov_b64_e32 v[24:25], 0
	v_mov_b64_e32 v[34:35], 0
	v_mov_b64_e32 v[36:37], 0
	v_mov_b64_e32 v[38:39], 0
	v_mov_b64_e32 v[40:41], 0
	v_mov_b64_e32 v[50:51], 0
	v_mov_b64_e32 v[52:53], 0
	v_mov_b64_e32 v[54:55], 0
	v_mov_b64_e32 v[56:57], 0
	v_mov_b64_e32 v[10:11], 0
	v_mov_b64_e32 v[12:13], 0
	v_mov_b64_e32 v[14:15], 0
	v_mov_b64_e32 v[16:17], 0
	v_mov_b64_e32 v[26:27], 0
	v_mov_b64_e32 v[28:29], 0
	v_mov_b64_e32 v[30:31], 0
	v_mov_b64_e32 v[32:33], 0
	v_mov_b64_e32 v[42:43], 0
	v_mov_b64_e32 v[44:45], 0
	v_mov_b64_e32 v[46:47], 0
	v_mov_b64_e32 v[48:49], 0
	v_mov_b64_e32 v[58:59], 0
	v_mov_b64_e32 v[60:61], 0
	v_mov_b64_e32 v[62:63], 0
	v_mov_b64_e32 v[64:65], 0
	v_mov_b64_e32 v[66:67], 0
	v_mov_b64_e32 v[68:69], 0
	v_mov_b64_e32 v[70:71], 0
	v_mov_b64_e32 v[72:73], 0
	v_mov_b64_e32 v[82:83], 0
	v_mov_b64_e32 v[84:85], 0
	v_mov_b64_e32 v[86:87], 0
	v_mov_b64_e32 v[88:89], 0
	v_mov_b64_e32 v[98:99], 0
	v_mov_b64_e32 v[100:101], 0
	v_mov_b64_e32 v[102:103], 0
	v_mov_b64_e32 v[104:105], 0
	v_mov_b64_e32 v[114:115], 0
	v_mov_b64_e32 v[116:117], 0
	v_mov_b64_e32 v[118:119], 0
	v_mov_b64_e32 v[120:121], 0
	v_mov_b64_e32 v[74:75], 0
	v_mov_b64_e32 v[76:77], 0
	v_mov_b64_e32 v[78:79], 0
	v_mov_b64_e32 v[80:81], 0
	v_mov_b64_e32 v[90:91], 0
	v_mov_b64_e32 v[92:93], 0
	v_mov_b64_e32 v[94:95], 0
	v_mov_b64_e32 v[96:97], 0
	v_mov_b64_e32 v[106:107], 0
	v_mov_b64_e32 v[108:109], 0
	v_mov_b64_e32 v[110:111], 0
	v_mov_b64_e32 v[112:113], 0
	v_mov_b64_e32 v[122:123], 0
	v_mov_b64_e32 v[124:125], 0
	v_mov_b64_e32 v[126:127], 0
	v_mov_b64_e32 v[128:129], 0
	s_mov_b64 vcc, -1

; #define PG8_STAGE(bufoff, gbase, voff) do { _Pragma("unroll") for (int _i = 0; _i < 2; ++_i) \
;         __builtin_amdgcn_global_load_lds((const unsigned*)((const char*)(gbase) + (voff)[_i]), (PG8_LAS unsigned*)(lds + (bufoff) + ldsw + _i * 8192), 16, 0, 0); } while (0)
; #define PG8_LDA(dst, b, h) do { _Pragma("unroll") for (int m = 0; m < 4; ++m) _Pragma("unroll") for (int k = 0; k < 2; ++k) dst[m][k] = *(const PG8_LAS bf16x8*)(lds + PG8_SA(b, h) + aoff + m * 2048 + k * 1024); } while (0)
; #define PG8_LDB(dst, b, h) do { _Pragma("unroll") for (int n = 0; n < 2; ++n) _Pragma("unroll") for (int k = 0; k < 2; ++k) dst[n][k] = *(const PG8_LAS bf16x8*)(lds + PG8_SB(b, h) + boff + n * 2048 + k * 1024); } while (0)
; #define PG8_MMA(ai, bj, At, Bt) do { __builtin_amdgcn_s_setprio(1); _Pragma("unroll") for (int m = 0; m < 4; ++m) _Pragma("unroll") for (int n = 0; n < 2; ++n) _Pragma("unroll") for (int k = 0; k < 2; ++k) \
;         acc[ai][bj][m][n] = Gemm::i8 ? ::mfma16i8_g(Bt[n][k], At[m][k], acc[ai][bj][m][n]) : ::mfma16_g(Bt[n][k], At[m][k], acc[ai][bj][m][n]); __builtin_amdgcn_s_setprio(0); } while (0)
; #define PG8_WAIT_V(n) asm volatile("s_waitcnt vmcnt(" #n ")" ::: "memory")
; #define PG8_WAIT_L(n) asm volatile("s_waitcnt lgkmcnt(" #n ")" ::: "memory")
; #define PG8_BAR __builtin_amdgcn_s_barrier()
; #define PG8_SCHED __builtin_amdgcn_sched_barrier(0)
; template <class Epi, class Sched, class Gemm, bool ALIGN_EPI = false, bool SP2 = false>
; __device__ __forceinline__ void gemm_phase(PG8_LAS unsigned char* lds, const Gemm g, const Sched& S, const Epi& E) {
;     ...
;             PG8_LDB(B0, 0, 0); PG8_LDB(B1, 0, 1); PG8_SCHED; PG8_LDA(At, 0, 0); PG8_STAGE(PG8_SA(1, 1), a1 + hstepA, voffA);
;             PG8_WAIT_V(8); PG8_WAIT_L(0); PG8_BAR; PG8_MMA(0, 0, At, B0); PG8_MMA(0, 1, At, B1); PG8_BAR; PG8_SCHED;
;             PG8_LDA(At, 0, 1); PG8_STAGE(PG8_SB(0, 0), b2, voffB); PG8_STAGE(PG8_SB(0, 1), b2 + hB1, voffB1); PG8_STAGE(PG8_SA(0, 0), a2, voffA);
;             PG8_WAIT_V(8); PG8_WAIT_L(0); PG8_BAR; PG8_MMA(1, 0, At, B0); PG8_MMA(1, 1, At, B1); PG8_BAR; PG8_SCHED;
.Lfw_2:
	s_waitcnt lgkmcnt(0)
	s_barrier
	s_setprio 1
	s_waitcnt lgkmcnt(0)
	v_mfma_i32_16x16x64_i8 v[224:227], v[172:175], v[164:167], v[126:129]
	v_mfma_i32_16x16x64_i8 v[126:129], v[188:191], v[168:171], v[224:227]
	v_mfma_i32_16x16x64_i8 v[228:231], v[192:195], v[164:167], v[122:125]
	v_mfma_i32_16x16x64_i8 v[232:235], v[172:175], v[200:203], v[110:113]
	v_mfma_i32_16x16x64_i8 v[236:239], v[192:195], v[200:203], v[106:109]
	v_mfma_i32_16x16x64_i8 v[240:243], v[172:175], v[208:211], v[94:97]
	v_mfma_i32_16x16x64_i8 v[244:247], v[192:195], v[208:211], v[90:93]
	v_mfma_i32_16x16x64_i8 v[224:227], v[172:175], v[216:219], v[78:81]
	v_mfma_i32_16x16x64_i8 v[74:77], v[192:195], v[216:219], v[74:77]
	v_mfma_i32_16x16x64_i8 v[122:125], v[196:199], v[168:171], v[228:231]
	v_mfma_i32_16x16x64_i8 v[110:113], v[188:191], v[204:207], v[232:235]
	v_mfma_i32_16x16x64_i8 v[106:109], v[196:199], v[204:207], v[236:239]
	v_mfma_i32_16x16x64_i8 v[94:97], v[188:191], v[212:215], v[240:243]
	v_mfma_i32_16x16x64_i8 v[90:93], v[196:199], v[212:215], v[244:247]
	v_mfma_i32_16x16x64_i8 v[78:81], v[188:191], v[220:223], v[224:227]
	v_mfma_i32_16x16x64_i8 v[74:77], v[196:199], v[220:223], v[74:77]
	s_setprio 0
	s_setprio 1
	v_mfma_i32_16x16x64_i8 v[224:227], v[134:137], v[164:167], v[118:121]
	v_mfma_i32_16x16x64_i8 v[118:121], v[138:141], v[168:171], v[224:227]
	v_mfma_i32_16x16x64_i8 v[228:231], v[142:145], v[164:167], v[114:117]
	v_mfma_i32_16x16x64_i8 v[232:235], v[134:137], v[200:203], v[102:105]
	v_mfma_i32_16x16x64_i8 v[236:239], v[142:145], v[200:203], v[98:101]
	v_mfma_i32_16x16x64_i8 v[240:243], v[134:137], v[208:211], v[86:89]
	v_mfma_i32_16x16x64_i8 v[244:247], v[142:145], v[208:211], v[82:85]
	v_mfma_i32_16x16x64_i8 v[164:167], v[134:137], v[216:219], v[70:73]
	v_mfma_i32_16x16x64_i8 v[66:69], v[142:145], v[216:219], v[66:69]
	v_mfma_i32_16x16x64_i8 v[114:117], v[130:133], v[168:171], v[228:231]
	v_mfma_i32_16x16x64_i8 v[102:105], v[138:141], v[204:207], v[232:235]
	v_mfma_i32_16x16x64_i8 v[98:101], v[130:133], v[204:207], v[236:239]
	v_mfma_i32_16x16x64_i8 v[86:89], v[138:141], v[212:215], v[240:243]
	v_mfma_i32_16x16x64_i8 v[82:85], v[130:133], v[212:215], v[244:247]
	v_mfma_i32_16x16x64_i8 v[70:73], v[138:141], v[220:223], v[164:167]
	v_mfma_i32_16x16x64_i8 v[66:69], v[130:133], v[220:223], v[66:69]
	s_setprio 0
	s_barrier
	s_add_i32 s65, s55, s43
	v_lshl_add_u64 v[164:165], s[40:41], 0, v[148:149]
	s_mov_b32 m0, s65
	ds_read_b128 v[200:203], v187 offset:16384
	ds_read_b128 v[204:207], v187 offset:17408
	ds_read_b128 v[208:211], v187 offset:18432
	ds_read_b128 v[212:215], v187 offset:19456
	ds_read_b128 v[216:219], v187 offset:20480
	ds_read_b128 v[220:223], v187 offset:21504
	ds_read_b128 v[224:227], v187 offset:22528
	ds_read_b128 v[228:231], v187 offset:23552
	global_load_lds_dwordx4 v[164:165], off
	s_add_i32 m0, s65, 0x2000
	s_add_u32 s66, s40, 0x2000
	v_lshl_add_u64 v[166:167], s[40:41], 0, v[152:153]
	s_addc_u32 s67, s41, 0
	s_add_i32 s65, s56, s43
	global_load_lds_dwordx4 v[166:167], off
	v_lshl_add_u64 v[160:161], s[66:67], 0, v[148:149]
	s_mov_b32 m0, s65
	v_lshl_add_u64 v[168:169], s[2:3], 0, v[146:147]
	global_load_lds_dwordx4 v[160:161], off
	v_lshl_add_u64 v[160:161], s[66:67], 0, v[152:153]
	s_add_i32 m0, s65, 0x2000
	v_lshl_add_u64 v[170:171], s[2:3], 0, v[150:151]
	global_load_lds_dwordx4 v[160:161], off
	s_mov_b32 m0, s39
	s_nop 0
	global_load_lds_dwordx4 v[168:169], off
	s_mov_b32 m0, s46
	s_nop 0
	global_load_lds_dwordx4 v[170:171], off
	s_cbranch_vccnz .Lfw_3
	s_waitcnt vmcnt(8)
.Lfw_3:
	s_waitcnt lgkmcnt(0)
	s_barrier
	s_setprio 1
	s_waitcnt lgkmcnt(0)
	v_mfma_i32_16x16x64_i8 v[232:235], v[172:175], v[200:203], v[62:65]
	v_mfma_i32_16x16x64_i8 v[62:65], v[188:191], v[204:207], v[232:235]
	v_mfma_i32_16x16x64_i8 v[236:239], v[192:195], v[200:203], v[58:61]
	v_mfma_i32_16x16x64_i8 v[240:243], v[172:175], v[208:211], v[46:49]
	v_mfma_i32_16x16x64_i8 v[244:247], v[192:195], v[208:211], v[42:45]
	v_mfma_i32_16x16x64_i8 v[248:251], v[172:175], v[216:219], v[30:33]
	v_mfma_i32_16x16x64_i8 v[160:163], v[192:195], v[216:219], v[26:29]
	v_mfma_i32_16x16x64_i8 v[232:235], v[172:175], v[224:227], v[14:17]
	v_mfma_i32_16x16x64_i8 v[10:13], v[192:195], v[224:227], v[10:13]
	v_mfma_i32_16x16x64_i8 v[58:61], v[196:199], v[204:207], v[236:239]
	v_mfma_i32_16x16x64_i8 v[46:49], v[188:191], v[212:215], v[240:243]
	v_mfma_i32_16x16x64_i8 v[42:45], v[196:199], v[212:215], v[244:247]
	v_mfma_i32_16x16x64_i8 v[30:33], v[188:191], v[220:223], v[248:251]
	v_mfma_i32_16x16x64_i8 v[26:29], v[196:199], v[220:223], v[160:163]
	v_mfma_i32_16x16x64_i8 v[14:17], v[188:191], v[228:231], v[232:235]
	v_mfma_i32_16x16x64_i8 v[10:13], v[196:199], v[228:231], v[10:13]
	s_setprio 0
	s_setprio 1
	v_mfma_i32_16x16x64_i8 v[160:163], v[134:137], v[200:203], v[54:57]
	v_mfma_i32_16x16x64_i8 v[54:57], v[138:141], v[204:207], v[160:163]
	v_mfma_i32_16x16x64_i8 v[172:175], v[142:145], v[200:203], v[50:53]
	v_mfma_i32_16x16x64_i8 v[188:191], v[134:137], v[208:211], v[38:41]
	v_mfma_i32_16x16x64_i8 v[192:195], v[142:145], v[208:211], v[34:37]
	v_mfma_i32_16x16x64_i8 v[196:199], v[134:137], v[216:219], v[22:25]
	v_mfma_i32_16x16x64_i8 v[232:235], v[142:145], v[216:219], v[18:21]
	v_mfma_i32_16x16x64_i8 v[160:163], v[134:137], v[224:227], v[6:9]
	v_mfma_i32_16x16x64_i8 v[2:5], v[142:145], v[224:227], v[2:5]
	v_mfma_i32_16x16x64_i8 v[50:53], v[130:133], v[204:207], v[172:175]
	v_mfma_i32_16x16x64_i8 v[38:41], v[138:141], v[212:215], v[188:191]
	v_mfma_i32_16x16x64_i8 v[34:37], v[130:133], v[212:215], v[192:195]
	v_mfma_i32_16x16x64_i8 v[22:25], v[138:141], v[220:223], v[196:199]
	v_mfma_i32_16x16x64_i8 v[18:21], v[130:133], v[220:223], v[232:235]
	v_mfma_i32_16x16x64_i8 v[6:9], v[138:141], v[228:231], v[160:163]
	v_mfma_i32_16x16x64_i8 v[2:5], v[130:133], v[228:231], v[2:5]
	s_setprio 0
	s_barrier
; #define PG8_STAGE(bufoff, gbase, voff) do { _Pragma("unroll") for (int _i = 0; _i < 2; ++_i) \
;         __builtin_amdgcn_global_load_lds((const unsigned*)((const char*)(gbase) + (voff)[_i]), (PG8_LAS unsigned*)(lds + (bufoff) + ldsw + _i * 8192), 16, 0, 0); } while (0)
; #define PG8_LDA(dst, b, h) do { _Pragma("unroll") for (int m = 0; m < 4; ++m) _Pragma("unroll") for (int k = 0; k < 2; ++k) dst[m][k] = *(const PG8_LAS bf16x8*)(lds + PG8_SA(b, h) + aoff + m * 2048 + k * 1024); } while (0)
; #define PG8_LDB(dst, b, h) do { _Pragma("unroll") for (int n = 0; n < 2; ++n) _Pragma("unroll") for (int k = 0; k < 2; ++k) dst[n][k] = *(const PG8_LAS bf16x8*)(lds + PG8_SB(b, h) + boff + n * 2048 + k * 1024); } while (0)
; #define PG8_MMA(ai, bj, At, Bt) do { __builtin_amdgcn_s_setprio(1); _Pragma("unroll") for (int m = 0; m < 4; ++m) _Pragma("unroll") for (int n = 0; n < 2; ++n) _Pragma("unroll") for (int k = 0; k < 2; ++k) \
;         acc[ai][bj][m][n] = Gemm::i8 ? ::mfma16i8_g(Bt[n][k], At[m][k], acc[ai][bj][m][n]) : ::mfma16_g(Bt[n][k], At[m][k], acc[ai][bj][m][n]); __builtin_amdgcn_s_setprio(0); } while (0)
; #define PG8_WAIT_V(n) asm volatile("s_waitcnt vmcnt(" #n ")" ::: "memory")
; #define PG8_WAIT_L(n) asm volatile("s_waitcnt lgkmcnt(" #n ")" ::: "memory")
; #define PG8_BAR __builtin_amdgcn_s_barrier()
; #define PG8_SCHED __builtin_amdgcn_sched_barrier(0)
; template <class Epi, class Sched, class Gemm, bool ALIGN_EPI = false, bool SP2 = false>
; __device__ __forceinline__ void gemm_phase(PG8_LAS unsigned char* lds, const Gemm g, const Sched& S, const Epi& E) {
;     ...
;             PG8_LDB(B0, 1, 0); PG8_LDB(B1, 1, 1); PG8_SCHED; PG8_LDA(At, 1, 0); PG8_STAGE(PG8_SA(0, 1), a2 + hstepA, voffA);
;             PG8_WAIT_V(8); PG8_WAIT_L(0); PG8_BAR; PG8_MMA(0, 0, At, B0); PG8_MMA(0, 1, At, B1); PG8_BAR; PG8_SCHED;
;             PG8_LDA(At, 1, 1); PG8_STAGE(PG8_SB(1, 0), b3, voffB); PG8_STAGE(PG8_SB(1, 1), b3 + hB1, voffB1); PG8_STAGE(PG8_SA(1, 0), a3, voffA);
;             PG8_WAIT_V(8);
;             if constexpr (epi_pre<Epi>::value) { if (last) E.pre(pre, cur, wr, wc, lane); }
	s_add_i32 s65, 0, 0x18000
	s_add_i32 s66, 0, 0x1c000
	v_add_u32_e32 v130, s65, v181
	v_add_u32_e32 v131, s66, v181
	ds_read_b128 v[160:163], v130
	ds_read_b128 v[172:175], v130 offset:1024
	ds_read_b128 v[188:191], v130 offset:2048
	ds_read_b128 v[192:195], v130 offset:3072
	ds_read_b128 v[134:137], v131
	ds_read_b128 v[138:141], v131 offset:1024
	ds_read_b128 v[142:145], v131 offset:2048
	ds_read_b128 v[130:133], v131 offset:3072
	s_add_u32 s2, s2, 0x20000
	s_addc_u32 s3, s3, 0
	s_mov_b32 m0, s47
	v_lshl_add_u64 v[176:177], s[2:3], 0, v[146:147]
	ds_read_b128 v[196:199], v187 offset:32768
	ds_read_b128 v[200:203], v187 offset:33792
	ds_read_b128 v[204:207], v187 offset:34816
	ds_read_b128 v[208:211], v187 offset:35840
	ds_read_b128 v[212:215], v187 offset:36864
	ds_read_b128 v[216:219], v187 offset:37888
	ds_read_b128 v[220:223], v187 offset:38912
	ds_read_b128 v[224:227], v187 offset:39936
	global_load_lds_dwordx4 v[176:177], off
	v_lshl_add_u64 v[176:177], s[2:3], 0, v[150:151]
	s_mov_b32 m0, s48
	s_nop 0
	global_load_lds_dwordx4 v[176:177], off
	s_waitcnt vmcnt(8)
	s_waitcnt lgkmcnt(0)
	s_barrier
	s_setprio 1
	s_waitcnt lgkmcnt(0)
	v_mfma_i32_16x16x64_i8 v[228:231], v[160:163], v[196:199], v[126:129]
	v_mfma_i32_16x16x64_i8 v[126:129], v[172:175], v[200:203], v[228:231]
	v_mfma_i32_16x16x64_i8 v[232:235], v[188:191], v[196:199], v[122:125]
	v_mfma_i32_16x16x64_i8 v[236:239], v[160:163], v[204:207], v[110:113]
	v_mfma_i32_16x16x64_i8 v[240:243], v[188:191], v[204:207], v[106:109]
	v_mfma_i32_16x16x64_i8 v[244:247], v[160:163], v[212:215], v[94:97]
	v_mfma_i32_16x16x64_i8 v[248:251], v[188:191], v[212:215], v[90:93]
	v_mfma_i32_16x16x64_i8 v[228:231], v[160:163], v[220:223], v[78:81]
	v_mfma_i32_16x16x64_i8 v[74:77], v[188:191], v[220:223], v[74:77]
	v_mfma_i32_16x16x64_i8 v[122:125], v[192:195], v[200:203], v[232:235]
	v_mfma_i32_16x16x64_i8 v[110:113], v[172:175], v[208:211], v[236:239]
	v_mfma_i32_16x16x64_i8 v[106:109], v[192:195], v[208:211], v[240:243]
	v_mfma_i32_16x16x64_i8 v[94:97], v[172:175], v[216:219], v[244:247]
	v_mfma_i32_16x16x64_i8 v[90:93], v[192:195], v[216:219], v[248:251]
	v_mfma_i32_16x16x64_i8 v[78:81], v[172:175], v[224:227], v[228:231]
	v_mfma_i32_16x16x64_i8 v[74:77], v[192:195], v[224:227], v[74:77]
	s_setprio 0
	s_setprio 1
	v_mfma_i32_16x16x64_i8 v[228:231], v[134:137], v[196:199], v[118:121]
	v_mfma_i32_16x16x64_i8 v[118:121], v[138:141], v[200:203], v[228:231]
	v_mfma_i32_16x16x64_i8 v[232:235], v[142:145], v[196:199], v[114:117]
	v_mfma_i32_16x16x64_i8 v[236:239], v[134:137], v[204:207], v[102:105]
	v_mfma_i32_16x16x64_i8 v[240:243], v[142:145], v[204:207], v[98:101]
	v_mfma_i32_16x16x64_i8 v[244:247], v[134:137], v[212:215], v[86:89]
	v_mfma_i32_16x16x64_i8 v[248:251], v[142:145], v[212:215], v[82:85]
	v_mfma_i32_16x16x64_i8 v[196:199], v[134:137], v[220:223], v[70:73]
	v_mfma_i32_16x16x64_i8 v[66:69], v[142:145], v[220:223], v[66:69]
	v_mfma_i32_16x16x64_i8 v[114:117], v[130:133], v[200:203], v[232:235]
	v_mfma_i32_16x16x64_i8 v[102:105], v[138:141], v[208:211], v[236:239]
	v_mfma_i32_16x16x64_i8 v[98:101], v[130:133], v[208:211], v[240:243]
	v_mfma_i32_16x16x64_i8 v[86:89], v[138:141], v[216:219], v[244:247]
	v_mfma_i32_16x16x64_i8 v[82:85], v[130:133], v[216:219], v[248:251]
	v_mfma_i32_16x16x64_i8 v[70:73], v[138:141], v[224:227], v[196:199]
	v_mfma_i32_16x16x64_i8 v[66:69], v[130:133], v[224:227], v[66:69]
	s_setprio 0
	s_barrier
	s_add_i32 s2, s65, s43
	v_lshl_add_u64 v[164:165], v[164:165], 0, s[18:19]
	s_mov_b32 m0, s2
	ds_read_b128 v[196:199], v187 offset:49152
	ds_read_b128 v[200:203], v187 offset:50176
	ds_read_b128 v[204:207], v187 offset:51200
	ds_read_b128 v[208:211], v187 offset:52224
	ds_read_b128 v[212:215], v187 offset:53248
	ds_read_b128 v[216:219], v187 offset:54272
	ds_read_b128 v[220:223], v187 offset:55296
	ds_read_b128 v[224:227], v187 offset:56320
	global_load_lds_dwordx4 v[164:165], off
	s_add_i32 m0, s2, 0x2000
	s_add_u32 s2, s40, 0x2080
	v_lshl_add_u64 v[164:165], v[166:167], 0, s[18:19]
	s_addc_u32 s3, s41, 0
	s_add_i32 s40, s66, s43
	global_load_lds_dwordx4 v[164:165], off
	v_lshl_add_u64 v[164:165], s[2:3], 0, v[148:149]
	s_mov_b32 m0, s40
	s_nop 0
	global_load_lds_dwordx4 v[164:165], off
	v_lshl_add_u64 v[164:165], s[2:3], 0, v[152:153]
	s_add_i32 m0, s40, 0x2000
	s_nop 0
	global_load_lds_dwordx4 v[164:165], off
	v_lshl_add_u64 v[164:165], v[168:169], 0, s[18:19]
	s_mov_b32 m0, s51
	s_nop 0
	global_load_lds_dwordx4 v[164:165], off
	v_lshl_add_u64 v[164:165], v[170:171], 0, s[18:19]
	s_mov_b32 m0, s52
	s_nop 0
	global_load_lds_dwordx4 v[164:165], off
	s_waitcnt vmcnt(8)
	s_waitcnt lgkmcnt(0)
	s_barrier
; #define PG8_STAGE(bufoff, gbase, voff) do { _Pragma("unroll") for (int _i = 0; _i < 2; ++_i) \
;         __builtin_amdgcn_global_load_lds((const unsigned*)((const char*)(gbase) + (voff)[_i]), (PG8_LAS unsigned*)(lds + (bufoff) + ldsw + _i * 8192), 16, 0, 0); } while (0)
; #define PG8_LDA(dst, b, h) do { _Pragma("unroll") for (int m = 0; m < 4; ++m) _Pragma("unroll") for (int k = 0; k < 2; ++k) dst[m][k] = *(const PG8_LAS bf16x8*)(lds + PG8_SA(b, h) + aoff + m * 2048 + k * 1024); } while (0)
; #define PG8_MMA(ai, bj, At, Bt) do { __builtin_amdgcn_s_setprio(1); _Pragma("unroll") for (int m = 0; m < 4; ++m) _Pragma("unroll") for (int n = 0; n < 2; ++n) _Pragma("unroll") for (int k = 0; k < 2; ++k) \
;         acc[ai][bj][m][n] = Gemm::i8 ? ::mfma16i8_g(Bt[n][k], At[m][k], acc[ai][bj][m][n]) : ::mfma16_g(Bt[n][k], At[m][k], acc[ai][bj][m][n]); __builtin_amdgcn_s_setprio(0); } while (0)
; #define PG8_WAIT_V(n) asm volatile("s_waitcnt vmcnt(" #n ")" ::: "memory")
; #define PG8_WAIT_L(n) asm volatile("s_waitcnt lgkmcnt(" #n ")" ::: "memory")
; #define PG8_BAR __builtin_amdgcn_s_barrier()
; #define PG8_SCHED __builtin_amdgcn_sched_barrier(0)
; template <class Epi, class Sched, class Gemm, bool ALIGN_EPI = false, bool SP2 = false>
; __device__ __forceinline__ void gemm_phase(PG8_LAS unsigned char* lds, const Gemm g, const Sched& S, const Epi& E) {
;     ...
;             PG8_WAIT_V(8); PG8_WAIT_L(0); PG8_BAR; PG8_MMA(0, 0, At, B0); PG8_MMA(0, 1, At, B1); PG8_BAR; PG8_SCHED;
;             PG8_LDA(At, 1, 1); PG8_STAGE(PG8_SB(1, 0), b3, voffB); PG8_STAGE(PG8_SB(1, 1), b3 + hB1, voffB1); PG8_STAGE(PG8_SA(1, 0), a3, voffA);
;             PG8_WAIT_V(8);
;             if constexpr (epi_pre<Epi>::value) { if (last) E.pre(pre, cur, wr, wc, lane); }
;             PG8_WAIT_L(0); PG8_BAR; PG8_MMA(1, 0, At, B0); PG8_MMA(1, 1, At, B1); PG8_BAR; PG8_SCHED;
	s_setprio 1
	s_waitcnt lgkmcnt(0)
	v_mfma_i32_16x16x64_i8 v[164:167], v[160:163], v[196:199], v[62:65]
	v_mfma_i32_16x16x64_i8 v[62:65], v[172:175], v[200:203], v[164:167]
	v_mfma_i32_16x16x64_i8 v[168:171], v[188:191], v[196:199], v[58:61]
	v_mfma_i32_16x16x64_i8 v[228:231], v[160:163], v[204:207], v[46:49]
	v_mfma_i32_16x16x64_i8 v[232:235], v[188:191], v[204:207], v[42:45]
	v_mfma_i32_16x16x64_i8 v[236:239], v[160:163], v[212:215], v[30:33]
	v_mfma_i32_16x16x64_i8 v[240:243], v[188:191], v[212:215], v[26:29]
	v_mfma_i32_16x16x64_i8 v[164:167], v[160:163], v[220:223], v[14:17]
	v_mfma_i32_16x16x64_i8 v[10:13], v[188:191], v[220:223], v[10:13]
	v_mfma_i32_16x16x64_i8 v[58:61], v[192:195], v[200:203], v[168:171]
	v_mfma_i32_16x16x64_i8 v[46:49], v[172:175], v[208:211], v[228:231]
	v_mfma_i32_16x16x64_i8 v[42:45], v[192:195], v[208:211], v[232:235]
	v_mfma_i32_16x16x64_i8 v[30:33], v[172:175], v[216:219], v[236:239]
	v_mfma_i32_16x16x64_i8 v[26:29], v[192:195], v[216:219], v[240:243]
	v_mfma_i32_16x16x64_i8 v[14:17], v[172:175], v[224:227], v[164:167]
	v_mfma_i32_16x16x64_i8 v[10:13], v[192:195], v[224:227], v[10:13]
	s_setprio 0
	s_setprio 1
	v_mfma_i32_16x16x64_i8 v[160:163], v[134:137], v[196:199], v[54:57]
	v_mfma_i32_16x16x64_i8 v[54:57], v[138:141], v[200:203], v[160:163]
	v_mfma_i32_16x16x64_i8 v[164:167], v[142:145], v[196:199], v[50:53]
	v_mfma_i32_16x16x64_i8 v[168:171], v[134:137], v[204:207], v[38:41]
	v_mfma_i32_16x16x64_i8 v[172:175], v[142:145], v[204:207], v[34:37]
	v_mfma_i32_16x16x64_i8 v[188:191], v[134:137], v[212:215], v[22:25]
	v_mfma_i32_16x16x64_i8 v[192:195], v[142:145], v[212:215], v[18:21]
	v_mfma_i32_16x16x64_i8 v[160:163], v[134:137], v[220:223], v[6:9]
	v_mfma_i32_16x16x64_i8 v[2:5], v[142:145], v[220:223], v[2:5]
	v_mfma_i32_16x16x64_i8 v[50:53], v[130:133], v[200:203], v[164:167]
	v_mfma_i32_16x16x64_i8 v[38:41], v[138:141], v[208:211], v[168:171]
	v_mfma_i32_16x16x64_i8 v[34:37], v[130:133], v[208:211], v[172:175]
	v_mfma_i32_16x16x64_i8 v[22:25], v[138:141], v[216:219], v[188:191]
	v_mfma_i32_16x16x64_i8 v[18:21], v[130:133], v[216:219], v[192:195]
	v_mfma_i32_16x16x64_i8 v[6:9], v[138:141], v[224:227], v[160:163]
	v_mfma_i32_16x16x64_i8 v[2:5], v[130:133], v[224:227], v[2:5]
	s_setprio 0
	s_barrier
	s_add_i32 s64, s64, 2
	s_add_u32 s62, s62, 0x100
	s_addc_u32 s63, s63, 0
	s_add_u32 s0, s0, 0x100
	s_addc_u32 s1, s1, 0
	s_cmp_gt_u32 s64, 5
	s_mov_b64 vcc, 0
	s_cbranch_scc0 .LBB0_2552
; #define PG8_BAR __builtin_amdgcn_s_barrier()
;     __device__ __forceinline__ void operator()(const f32x4 (&acc)[2][2][4][2], const Unit& u, int wr, int wc, int fr, int fq) const {
;         asm volatile("" : "+v"(fr), "+v"(fq));
;         const int row0 = u.pm * BM + wr * 64 + fr, col0 = u.pn * BM + wc * 64 + 16 * fq;
;         const int gn = u.pn >> 2, gbase = (gn < 3) ? 3072 + 1024 * gn : 0;
;         f32x4 bv[2][2];
; #pragma unroll
;         for (int bj = 0; bj < 2; ++bj)
; #pragma unroll
;             for (int n = 0; n < 2; ++n) bv[bj][n] = *(const f32x4*)(bias + col0 + 8 * bj + 4 * n) * -1.44269504f;
;         f32x4 wv[2][2];
; #pragma unroll
;         for (int bj = 0; bj < 2; ++bj)
; #pragma unroll
;             for (int n = 0; n < 2; ++n) wv[bj][n] = *(const f32x4*)(SW + col0 + 8 * bj + 4 * n) * -1.44269504f;
;         float rsv[8];
; #pragma unroll
;         for (int i = 0; i < 8; ++i) rsv[i] = SH[row0 + (i >> 2) * HALF + (i & 3) * 16];
; template <class Epi, class Sched, class Gemm, bool ALIGN_EPI = false, bool SP2 = false>
; __device__ __forceinline__ void gemm_phase(PG8_LAS unsigned char* lds, const Gemm g, const Sched& S, const Epi& E) {
;     ...
;         if constexpr (ALIGN_EPI) { if (wr == 0) PG8_BAR; }
	s_lshl_b32 s0, s59, 8
	v_mov_b32_e32 v154, v1
	v_mov_b32_e32 v130, v179
	s_or_b32 s0, s0, s53
	v_cvt_f32_i32_e32 v212, v122
	v_lshl_add_u32 v144, v130, 4, s0
	s_lshl_b32 s0, s38, 8
	v_ashrrev_i32_e32 v145, 31, v144
	s_add_i32 s0, s0, s50
	v_lshlrev_b64 v[142:143], 2, v[144:145]
	v_add_u32_e32 v164, s0, v154
	v_lshl_add_u64 v[160:161], s[14:15], 0, v[142:143]
	v_ashrrev_i32_e32 v165, 31, v164
	global_load_dwordx4 v[130:133], v[160:161], off
	global_load_dwordx4 v[134:137], v[160:161], off offset:16
	global_load_dwordx4 v[138:141], v[160:161], off offset:32
	s_nop 0
	global_load_dwordx4 v[160:163], v[160:161], off offset:48
	v_lshl_add_u64 v[142:143], s[16:17], 0, v[142:143]
	v_lshl_add_u64 v[170:171], v[164:165], 2, s[12:13]
	global_load_dwordx4 v[166:169], v[142:143], off
	global_load_dwordx4 v[194:197], v[142:143], off offset:16
	global_load_dwordx4 v[198:201], v[142:143], off offset:32
	global_load_dwordx4 v[202:205], v[142:143], off offset:48
	global_load_dword v206, v[170:171], off
	global_load_dword v188, v[170:171], off offset:64
	global_load_dword v186, v[170:171], off offset:128
	global_load_dword v184, v[170:171], off offset:192
	global_load_dword v182, v[170:171], off offset:512
	global_load_dword v180, v[170:171], off offset:576
	global_load_dword v178, v[170:171], off offset:640
	global_load_dword v122, v[170:171], off offset:704
	s_ashr_i32 s0, s59, 2
	s_lshl_b32 s1, s0, 10
	v_mov_b64_e32 v[142:143], s[10:11]
	s_add_i32 s2, s1, 0xc00
	v_cvt_f32_i32_e32 v209, v127
	v_cvt_f32_i32_e32 v208, v126
	v_cvt_f32_i32_e32 v215, v125
	v_cvt_f32_i32_e32 v214, v124
	s_cmp_lt_i32 s0, 3
	v_mad_i64_i32 v[124:125], s[0:1], v164, s57, v[142:143]
	s_cselect_b32 s0, s2, 0
	v_cvt_f32_i32_e32 v211, v129
	v_cvt_f32_i32_e32 v210, v128
	s_ashr_i32 s1, s0, 31
	v_cvt_f32_i32_e32 v115, v115
	v_cvt_f32_i32_e32 v114, v114
	v_cvt_f32_i32_e32 v99, v99
	v_cvt_f32_i32_e32 v98, v98
	v_cvt_f32_i32_e32 v83, v83
	v_cvt_f32_i32_e32 v82, v82
	v_cvt_f32_i32_e32 v67, v67
	v_cvt_f32_i32_e32 v66, v66
	v_cvt_f32_i32_e32 v51, v51
	v_cvt_f32_i32_e32 v50, v50
	v_cvt_f32_i32_e32 v35, v35
	v_cvt_f32_i32_e32 v34, v34
	v_cvt_f32_i32_e32 v19, v19
	v_cvt_f32_i32_e32 v18, v18
	v_and_b32_e32 v154, 0x3f0, v144
	v_lshl_add_u64 v[124:125], v[124:125], 0, s[0:1]
	v_cvt_f32_i32_e32 v117, v117
	v_cvt_f32_i32_e32 v116, v116
	v_cvt_f32_i32_e32 v111, v111
	v_cvt_f32_i32_e32 v110, v110
	v_cvt_f32_i32_e32 v101, v101
	v_cvt_f32_i32_e32 v100, v100
	v_cvt_f32_i32_e32 v95, v95
	v_cvt_f32_i32_e32 v94, v94
	v_cvt_f32_i32_e32 v85, v85
	v_cvt_f32_i32_e32 v84, v84
	v_cvt_f32_i32_e32 v79, v79
	v_cvt_f32_i32_e32 v78, v78
	v_cvt_f32_i32_e32 v69, v69
	v_cvt_f32_i32_e32 v68, v68
	v_cvt_f32_i32_e32 v63, v63
	v_cvt_f32_i32_e32 v62, v62
	v_cvt_f32_i32_e32 v53, v53
	v_cvt_f32_i32_e32 v52, v52
	v_cvt_f32_i32_e32 v47, v47
	v_cvt_f32_i32_e32 v46, v46
	v_cvt_f32_i32_e32 v37, v37
	v_cvt_f32_i32_e32 v36, v36
	v_cvt_f32_i32_e32 v31, v31
	v_cvt_f32_i32_e32 v30, v30
	v_cvt_f32_i32_e32 v21, v21
	v_cvt_f32_i32_e32 v20, v20
	v_cvt_f32_i32_e32 v15, v15
	v_cvt_f32_i32_e32 v14, v14
	v_add_u32_e32 v207, 32, v164
	v_lshl_add_u64 v[216:217], v[124:125], 0, v[154:155]
	v_add_u32_e32 v189, 0xa0, v164
	v_cvt_f32_i32_e32 v213, v123
	v_add_u32_e32 v123, 0xb0, v164
	v_cvt_f32_i32_e32 v119, v119
	v_cvt_f32_i32_e32 v118, v118
	v_cvt_f32_i32_e32 v109, v109
	v_cvt_f32_i32_e32 v108, v108
	v_cvt_f32_i32_e32 v103, v103
	v_cvt_f32_i32_e32 v102, v102
	v_cvt_f32_i32_e32 v93, v93
	v_cvt_f32_i32_e32 v121, v121
	v_cvt_f32_i32_e32 v120, v120
	v_cvt_f32_i32_e32 v113, v113
	v_cvt_f32_i32_e32 v112, v112
	v_cvt_f32_i32_e32 v107, v107
	v_cvt_f32_i32_e32 v106, v106
	v_cvt_f32_i32_e32 v105, v105
	v_cvt_f32_i32_e32 v104, v104
	v_cvt_f32_i32_e32 v92, v92
	v_cvt_f32_i32_e32 v87, v87
	v_cvt_f32_i32_e32 v86, v86
	v_cvt_f32_i32_e32 v97, v97
	v_cvt_f32_i32_e32 v96, v96
	v_cvt_f32_i32_e32 v91, v91
	v_cvt_f32_i32_e32 v90, v90
	v_cvt_f32_i32_e32 v89, v89
	v_cvt_f32_i32_e32 v88, v88
	v_cvt_f32_i32_e32 v77, v77
	v_cvt_f32_i32_e32 v76, v76
	v_cvt_f32_i32_e32 v71, v71
	v_cvt_f32_i32_e32 v70, v70
	v_cvt_f32_i32_e32 v81, v81
	v_cvt_f32_i32_e32 v80, v80
	v_cvt_f32_i32_e32 v75, v75
	v_cvt_f32_i32_e32 v74, v74
	v_cvt_f32_i32_e32 v73, v73
	v_cvt_f32_i32_e32 v72, v72
	v_cvt_f32_i32_e32 v61, v61
	v_cvt_f32_i32_e32 v60, v60
	v_cvt_f32_i32_e32 v55, v55
	v_cvt_f32_i32_e32 v54, v54
	v_cvt_f32_i32_e32 v65, v65
	v_cvt_f32_i32_e32 v64, v64
	v_cvt_f32_i32_e32 v59, v59
	v_cvt_f32_i32_e32 v58, v58
	v_cvt_f32_i32_e32 v57, v57
	v_cvt_f32_i32_e32 v56, v56
	v_cvt_f32_i32_e32 v45, v45
	v_cvt_f32_i32_e32 v44, v44
	v_cvt_f32_i32_e32 v39, v39
	v_cvt_f32_i32_e32 v38, v38
	v_cvt_f32_i32_e32 v49, v49
	v_cvt_f32_i32_e32 v48, v48
	v_cvt_f32_i32_e32 v43, v43
	v_cvt_f32_i32_e32 v42, v42
	v_cvt_f32_i32_e32 v41, v41
	v_cvt_f32_i32_e32 v40, v40
	v_cvt_f32_i32_e32 v29, v29
	v_cvt_f32_i32_e32 v28, v28
	v_cvt_f32_i32_e32 v23, v23
	v_cvt_f32_i32_e32 v22, v22
	v_cvt_f32_i32_e32 v33, v33
	v_cvt_f32_i32_e32 v32, v32
	v_cvt_f32_i32_e32 v27, v27
	v_cvt_f32_i32_e32 v26, v26
	v_cvt_f32_i32_e32 v25, v25
	v_cvt_f32_i32_e32 v24, v24
	v_cvt_f32_i32_e32 v7, v7
	v_cvt_f32_i32_e32 v6, v6
	v_cvt_f32_i32_e32 v3, v3
	v_cvt_f32_i32_e32 v2, v2
	v_cvt_f32_i32_e32 v17, v17
	v_cvt_f32_i32_e32 v16, v16
	v_cvt_f32_i32_e32 v11, v11
	v_cvt_f32_i32_e32 v13, v13
	v_cvt_f32_i32_e32 v12, v12
	v_cvt_f32_i32_e32 v10, v10
	v_cvt_f32_i32_e32 v9, v9
	v_cvt_f32_i32_e32 v8, v8
	v_cvt_f32_i32_e32 v5, v5
	v_cvt_f32_i32_e32 v4, v4
	s_and_b64 vcc, exec, s[20:21]
	s_cbranch_vccz .LBB0_2555
	s_barrier

; #define BIDX opqs((int)blockIdx.x)
; #define PG8_LAS __attribute__((address_space(3)))
;     __device__ bool next(int i, Unit& u) const { const bool ok = StaticOrder::next(i >> 2, u); u.sub = i & 3; return ok; }
;     __host__ __device__ bool next(int i, Unit& u) const {
;         const long L = (long)i * G + c; if (L >= nwg) return false;
;         int wgid = (int)L; { const int q = nwg / NXCD, r = nwg % NXCD, xcd = wgid % NXCD, off = wgid / NXCD; wgid = (xcd < r ? xcd * (q + 1) : r * (q + 1) + (xcd - r) * q) + off; }
;         const int nig = WGM * nN, gid = wgid / nig, fm = gid * WGM, gsz = (nM - fm) < WGM ? (nM - fm) : WGM;
;         u.pm = fm + ((wgid % nig) % gsz); u.pn = (wgid % nig) / gsz; u.sub = 0; return true;
; template <int L, int Q>
; __device__ __forceinline__ void layer_phase(unsigned char* lds_raw) {
;     ...
;     } else if constexpr (Q == 4) {
;         typedef pg8::GemmT<DM, 256, 256, 512, 1024 * 256 * 2> GT; GT g{c.P, c.WbT + (size_t)l * 4 * 1024 * 256}; pg8::MergeOrder S; S.init(MT, DM, (int)gridDim.x, BIDX);
;         pg8::EpiMergeChain E{(const unsigned char*)c.Z, c.H, c.FF};
;         pg8::gemm_phase<pg8::EpiMergeChain, pg8::MergeOrder, GT, true, true>((PG8_LAS unsigned char*)lds_raw, g, S, E);
.LBB0_2613:
	s_nop 0
	s_nop 0
	s_nop 0
	s_nop 0
	s_nop 0
	s_nop 0
	s_nop 0
	s_nop 0
	s_nop 0
	s_nop 0
	s_nop 0
	s_nop 0
	s_nop 0
	s_nop 0
	s_nop 0
	s_nop 0
	s_nop 0
	s_nop 0
	s_nop 0
	s_nop 0
	s_nop 0
	s_nop 0
	s_nop 0
	s_nop 0
	s_nop 0
	s_nop 0
	s_nop 0
	s_nop 0
	s_nop 0
	s_nop 0
	s_nop 0
	s_nop 0
	s_nop 0
	s_nop 0
	s_nop 0
	s_nop 0
	s_nop 0
	s_nop 0
	s_nop 0
	s_nop 0
	s_nop 0
	s_nop 0
	s_nop 0
	s_nop 0
	s_nop 0
	s_nop 0
	s_nop 0
	s_nop 0
	s_nop 0
	s_nop 0
	s_nop 0
	s_nop 0
	s_nop 0
	s_nop 0
	s_nop 0
	s_nop 0
	s_nop 0
	s_nop 0
	s_cmp_lt_i32 s86, 10
	s_cselect_b64 s[0:1], -1, 0
	s_cmp_gt_i32 s87, 9
	s_cselect_b64 s[2:3], -1, 0
	s_and_b64 s[0:1], s[0:1], s[2:3]
	s_andn2_b64 vcc, exec, s[0:1]
	s_cbranch_vccnz .LBB0_2710
	v_readlane_b32 s4, v255, 0
	v_readlane_b32 s5, v255, 1
	s_mov_b64 s[0:1], s[4:5]
	s_load_dwordx2 s[2:3], s[0:1], 0x88
	s_add_u32 s8, s4, 0x98
	s_addc_u32 s9, s5, 0
	s_mov_b32 s33, s88
	s_waitcnt vmcnt(0)
	v_mov_b32_e32 v2, v0
	s_cmpk_lt_i32 s33, 0x200
	s_cselect_b64 s[4:5], -1, 0
	s_cmpk_gt_i32 s33, 0x1ff
	s_waitcnt lgkmcnt(0)
	v_readfirstlane_b32 s18, v2
	s_cbranch_scc1 .LBB0_2620
	s_ashr_i32 s0, s33, 31
	s_lshr_b32 s0, s0, 29
	s_add_i32 s10, s33, s0
	s_and_b32 s0, s10, -8
	s_sub_i32 s6, s33, s0
	s_cmp_gt_i32 s6, -1
	s_cbranch_scc0 .LBB0_2617
	s_lshl_b32 s7, s6, 6
	s_ashr_i32 s0, s10, 3
	s_cbranch_execz .LBB0_2618
	s_branch .LBB0_2619

;     __device__ __forceinline__ void operator()(f32x4 (&acc)[2][2][4][2], const Unit& u, int wr, int wc, int fr, int fq) const {
;     ...
;         if constexpr (FINAL) {
; #pragma unroll
;             for (int bj = 0; bj < 2; ++bj)
; #pragma unroll
;                 for (int n = 0; n < 2; ++n) gv[bj][n] = *(const f32x4*)(g + col0 + bj * HALF + 4 * n);
;         } else asm volatile("" : "+v"(gv[0][0]), "+v"(gv[0][1]), "+v"(gv[1][0]), "+v"(gv[1][1]));
; #pragma unroll
;         for (int ai = 0; ai < 2; ++ai)
; #pragma unroll
;             for (int m = 0; m < 4; ++m) {
;                 const int row = row0 + ai * HALF + m * 16;
;                 const float ss = __hip_atomic_load(SS + row, __ATOMIC_RELAXED, __HIP_MEMORY_SCOPE_AGENT);
;                 const float rstd = 1.0f / sqrtf(ss * (1.f / 1024.f) + 1e-6f);
;                 float qs = 0.f;
;                 if constexpr (!FINAL) {
;                     const float am = __uint_as_float(__hip_atomic_load(AM + row, __ATOMIC_RELAXED, __HIP_MEMORY_SCOPE_AGENT));
;                     qs = am > 0.f ? 127.f / am : 0.f;
;                     if (u.pn == 0 && wc == 0 && fq == 0) SH[row] = am * rstd * (1.f / 127.f);
;                 }
; #pragma unroll
;                 for (int bj = 0; bj < 2; ++bj) {
;                     const size_t off = (size_t)row * 1024 + col0 + bj * HALF;
;                     const f32x4 y0 = acc[ai][bj][m][0] * rstd * gv[bj][0], y1 = acc[ai][bj][m][1] * rstd * gv[bj][1];
;                     if constexpr (FINAL) { *(f32x4*)(out + off) = y0; *(f32x4*)(out + off + 4) = y1; }
.LBB0_2766:
	s_or_b64 exec, exec, s[4:5]
	v_lshl_add_u64 v[8:9], s[8:9], 0, v[194:195]
	global_load_dwordx4 v[4:7], v[8:9], off offset:16
	global_load_dwordx4 v[12:15], v[8:9], off
	s_waitcnt lgkmcnt(0)
	global_load_dwordx4 v[0:3], v[8:9], off offset:528
	s_nop 0
	global_load_dwordx4 v[8:11], v[8:9], off offset:512
	s_nop 0
	global_load_dword v84, v[196:197], off sc1
	global_load_dword v85, v[196:197], off offset:64 sc1
	global_load_dword v86, v[196:197], off offset:128 sc1
	global_load_dword v87, v[196:197], off offset:192 sc1
	global_load_dword v88, v[196:197], off offset:512 sc1
	global_load_dword v89, v[196:197], off offset:576 sc1
	global_load_dword v90, v[196:197], off offset:640 sc1
	global_load_dword v91, v[196:197], off offset:704 sc1
	s_waitcnt vmcnt(7)
	v_fmamk_f32 v64, v84, 0x3a800000, v237
	v_mul_f32_e32 v65, 0x4f800000, v64
	v_cmp_gt_f32_e32 vcc, s74, v64
	s_nop 1
	v_cndmask_b32_e32 v64, v64, v65, vcc
	v_sqrt_f32_e32 v65, v64
	s_nop 0
	v_add_u32_e32 v66, -1, v65
	v_add_u32_e32 v67, 1, v65
	v_fma_f32 v68, -v66, v65, v64
	v_fma_f32 v69, -v67, v65, v64
	v_cmp_ge_f32_e64 s[4:5], 0, v68
	s_nop 1
	v_cndmask_b32_e64 v65, v65, v66, s[4:5]
	v_cmp_lt_f32_e64 s[4:5], 0, v69
	s_nop 1
	v_cndmask_b32_e64 v65, v65, v67, s[4:5]
	v_mul_f32_e32 v66, 0x37800000, v65
	v_cndmask_b32_e32 v65, v65, v66, vcc
	v_cmp_class_f32_e32 vcc, v64, v238
	s_nop 1
	v_cndmask_b32_e32 v64, v65, v64, vcc
	v_div_scale_f32 v65, s[2:3], v64, v64, 1.0
	v_rcp_f32_e32 v66, v65
	v_div_scale_f32 v67, vcc, 1.0, v64, 1.0
	v_fma_f32 v68, -v65, v66, 1.0
	v_fmac_f32_e32 v66, v68, v66
	v_mul_f32_e32 v68, v67, v66
	v_fma_f32 v69, -v65, v68, v67
	v_fmac_f32_e32 v68, v69, v66
	v_fma_f32 v65, -v65, v68, v67
	v_div_fmas_f32 v65, v65, v66, v68
	v_div_fixup_f32 v64, v65, v64, 1.0
	v_pk_mul_f32 v[68:69], v[212:213], v[64:65] op_sel_hi:[1,0]
	v_pk_mul_f32 v[66:67], v[210:211], v[64:65] op_sel_hi:[1,0]
	v_pk_mul_f32 v[72:73], v[208:209], v[64:65] op_sel_hi:[1,0]
	v_pk_mul_f32 v[70:71], v[206:207], v[64:65] op_sel_hi:[1,0]
	v_pk_mul_f32 v[76:77], v[220:221], v[64:65] op_sel_hi:[1,0]
	v_pk_mul_f32 v[74:75], v[218:219], v[64:65] op_sel_hi:[1,0]
	v_pk_mul_f32 v[80:81], v[216:217], v[64:65] op_sel_hi:[1,0]
	v_pk_mul_f32 v[78:79], v[214:215], v[64:65] op_sel_hi:[1,0]
	v_pk_mul_f32 v[66:67], v[14:15], v[66:67]
	v_pk_mul_f32 v[64:65], v[12:13], v[68:69]
	v_pk_mul_f32 v[70:71], v[6:7], v[70:71]
	v_pk_mul_f32 v[68:69], v[4:5], v[72:73]
	v_pk_mul_f32 v[74:75], v[10:11], v[74:75]
	v_pk_mul_f32 v[72:73], v[8:9], v[76:77]
	v_pk_mul_f32 v[78:79], v[2:3], v[78:79]
	v_pk_mul_f32 v[76:77], v[0:1], v[80:81]
	global_store_dwordx4 v[204:205], v[64:67], off
	global_store_dwordx4 v[204:205], v[68:71], off offset:16
	global_store_dwordx4 v[204:205], v[72:75], off offset:512
	global_store_dwordx4 v[204:205], v[76:79], off offset:528
	s_waitcnt vmcnt(10)
	v_fmamk_f32 v64, v85, 0x3a800000, v237
	v_mul_f32_e32 v65, 0x4f800000, v64
	v_cmp_gt_f32_e32 vcc, s74, v64
	s_nop 1
	v_cndmask_b32_e32 v66, v64, v65, vcc
	v_sqrt_f32_e32 v67, v66
	v_lshl_add_u64 v[64:65], s[10:11], 0, v[202:203]
	v_lshl_add_u64 v[80:81], v[64:65], 0, v[194:195]
	v_add_u32_e32 v68, -1, v67
	v_add_u32_e32 v69, 1, v67
	v_fma_f32 v70, -v68, v67, v66
	v_fma_f32 v71, -v69, v67, v66
	v_cmp_ge_f32_e64 s[4:5], 0, v70
	s_nop 1
	v_cndmask_b32_e64 v67, v67, v68, s[4:5]
	v_cmp_lt_f32_e64 s[4:5], 0, v71
	s_nop 1
	v_cndmask_b32_e64 v67, v67, v69, s[4:5]
	v_mul_f32_e32 v68, 0x37800000, v67
	v_cndmask_b32_e32 v67, v67, v68, vcc
	v_cmp_class_f32_e32 vcc, v66, v238
	s_nop 1
	v_cndmask_b32_e32 v66, v67, v66, vcc
	v_div_scale_f32 v67, s[2:3], v66, v66, 1.0
	v_rcp_f32_e32 v68, v67
	v_div_scale_f32 v64, vcc, 1.0, v66, 1.0
	v_fma_f32 v65, -v67, v68, 1.0
	v_fmac_f32_e32 v68, v65, v68
	v_mul_f32_e32 v65, v64, v68
	v_fma_f32 v69, -v67, v65, v64
	v_fmac_f32_e32 v65, v69, v68
	v_fma_f32 v64, -v67, v65, v64
	v_div_fmas_f32 v64, v64, v68, v65
	v_div_fixup_f32 v64, v64, v66, 1.0
	v_pk_mul_f32 v[68:69], v[222:223], v[64:65] op_sel_hi:[1,0]
	v_pk_mul_f32 v[66:67], v[174:175], v[64:65] op_sel_hi:[1,0]
	v_pk_mul_f32 v[72:73], v[172:173], v[64:65] op_sel_hi:[1,0]
	v_pk_mul_f32 v[70:71], v[170:171], v[64:65] op_sel_hi:[1,0]
	v_pk_mul_f32 v[76:77], v[164:165], v[64:65] op_sel_hi:[1,0]
	v_pk_mul_f32 v[74:75], v[166:167], v[64:65] op_sel_hi:[1,0]
	v_pk_mul_f32 v[82:83], v[160:161], v[64:65] op_sel_hi:[1,0]
	v_pk_mul_f32 v[78:79], v[162:163], v[64:65] op_sel_hi:[1,0]
	v_pk_mul_f32 v[66:67], v[14:15], v[66:67]
	v_pk_mul_f32 v[64:65], v[12:13], v[68:69]
	v_pk_mul_f32 v[70:71], v[6:7], v[70:71]
	v_pk_mul_f32 v[68:69], v[4:5], v[72:73]
	v_pk_mul_f32 v[74:75], v[10:11], v[74:75]
	v_pk_mul_f32 v[72:73], v[8:9], v[76:77]
	v_pk_mul_f32 v[78:79], v[2:3], v[78:79]
	v_pk_mul_f32 v[76:77], v[0:1], v[82:83]
	global_store_dwordx4 v[80:81], v[64:67], off
	global_store_dwordx4 v[80:81], v[68:71], off offset:16
	global_store_dwordx4 v[80:81], v[72:75], off offset:512
	global_store_dwordx4 v[80:81], v[76:79], off offset:528
	s_waitcnt vmcnt(13)
;     __device__ __forceinline__ void operator()(f32x4 (&acc)[2][2][4][2], const Unit& u, int wr, int wc, int fr, int fq) const {
;     ...
;         for (int ai = 0; ai < 2; ++ai)
; #pragma unroll
;             for (int m = 0; m < 4; ++m) {
;                 const int row = row0 + ai * HALF + m * 16;
;                 const float ss = __hip_atomic_load(SS + row, __ATOMIC_RELAXED, __HIP_MEMORY_SCOPE_AGENT);
;                 const float rstd = 1.0f / sqrtf(ss * (1.f / 1024.f) + 1e-6f);
;                 float qs = 0.f;
;                 if constexpr (!FINAL) {
;                     const float am = __uint_as_float(__hip_atomic_load(AM + row, __ATOMIC_RELAXED, __HIP_MEMORY_SCOPE_AGENT));
;                     qs = am > 0.f ? 127.f / am : 0.f;
;                     if (u.pn == 0 && wc == 0 && fq == 0) SH[row] = am * rstd * (1.f / 127.f);
;                 }
; #pragma unroll
;                 for (int bj = 0; bj < 2; ++bj) {
;                     const size_t off = (size_t)row * 1024 + col0 + bj * HALF;
;                     const f32x4 y0 = acc[ai][bj][m][0] * rstd * gv[bj][0], y1 = acc[ai][bj][m][1] * rstd * gv[bj][1];
;                     if constexpr (FINAL) { *(f32x4*)(out + off) = y0; *(f32x4*)(out + off + 4) = y1; }
	v_fmamk_f32 v64, v86, 0x3a800000, v237
	v_mul_f32_e32 v65, 0x4f800000, v64
	v_cmp_gt_f32_e32 vcc, s74, v64
	s_nop 1
	v_cndmask_b32_e32 v66, v64, v65, vcc
	v_sqrt_f32_e32 v67, v66
	v_lshl_add_u64 v[64:65], s[10:11], 0, v[200:201]
	v_lshl_add_u64 v[80:81], v[64:65], 0, v[194:195]
	v_add_u32_e32 v68, -1, v67
	v_add_u32_e32 v69, 1, v67
	v_fma_f32 v70, -v68, v67, v66
	v_fma_f32 v71, -v69, v67, v66
	v_cmp_ge_f32_e64 s[4:5], 0, v70
	s_nop 1
	v_cndmask_b32_e64 v67, v67, v68, s[4:5]
	v_cmp_lt_f32_e64 s[4:5], 0, v71
	s_nop 1
	v_cndmask_b32_e64 v67, v67, v69, s[4:5]
	v_mul_f32_e32 v68, 0x37800000, v67
	v_cndmask_b32_e32 v67, v67, v68, vcc
	v_cmp_class_f32_e32 vcc, v66, v238
	s_nop 1
	v_cndmask_b32_e32 v66, v67, v66, vcc
	v_div_scale_f32 v67, s[2:3], v66, v66, 1.0
	v_rcp_f32_e32 v68, v67
	v_div_scale_f32 v64, vcc, 1.0, v66, 1.0
	v_fma_f32 v65, -v67, v68, 1.0
	v_fmac_f32_e32 v68, v65, v68
	v_mul_f32_e32 v65, v64, v68
	v_fma_f32 v69, -v67, v65, v64
	v_fmac_f32_e32 v65, v69, v68
	v_fma_f32 v64, -v67, v65, v64
	v_div_fmas_f32 v64, v64, v68, v65
	v_div_fixup_f32 v64, v64, v66, 1.0
	v_pk_mul_f32 v[68:69], v[224:225], v[64:65] op_sel_hi:[1,0]
	v_pk_mul_f32 v[66:67], v[158:159], v[64:65] op_sel_hi:[1,0]
	v_pk_mul_f32 v[72:73], v[156:157], v[64:65] op_sel_hi:[1,0]
	v_pk_mul_f32 v[70:71], v[154:155], v[64:65] op_sel_hi:[1,0]
	v_pk_mul_f32 v[76:77], v[148:149], v[64:65] op_sel_hi:[1,0]
	v_pk_mul_f32 v[74:75], v[150:151], v[64:65] op_sel_hi:[1,0]
	v_pk_mul_f32 v[82:83], v[144:145], v[64:65] op_sel_hi:[1,0]
	v_pk_mul_f32 v[78:79], v[146:147], v[64:65] op_sel_hi:[1,0]
	v_pk_mul_f32 v[66:67], v[14:15], v[66:67]
	v_pk_mul_f32 v[64:65], v[12:13], v[68:69]
	v_pk_mul_f32 v[70:71], v[6:7], v[70:71]
	v_pk_mul_f32 v[68:69], v[4:5], v[72:73]
	v_pk_mul_f32 v[74:75], v[10:11], v[74:75]
	v_pk_mul_f32 v[72:73], v[8:9], v[76:77]
	v_pk_mul_f32 v[78:79], v[2:3], v[78:79]
	v_pk_mul_f32 v[76:77], v[0:1], v[82:83]
	global_store_dwordx4 v[80:81], v[64:67], off
	global_store_dwordx4 v[80:81], v[68:71], off offset:16
	global_store_dwordx4 v[80:81], v[72:75], off offset:512
	global_store_dwordx4 v[80:81], v[76:79], off offset:528
	s_waitcnt vmcnt(16)
	v_fmamk_f32 v64, v87, 0x3a800000, v237
	v_mul_f32_e32 v65, 0x4f800000, v64
	v_cmp_gt_f32_e32 vcc, s74, v64
	s_nop 1
	v_cndmask_b32_e32 v66, v64, v65, vcc
	v_sqrt_f32_e32 v67, v66
	v_lshl_add_u64 v[64:65], s[10:11], 0, v[198:199]
	v_lshl_add_u64 v[80:81], v[64:65], 0, v[194:195]
	v_add_u32_e32 v68, -1, v67
	v_add_u32_e32 v69, 1, v67
	v_fma_f32 v70, -v68, v67, v66
	v_fma_f32 v71, -v69, v67, v66
	v_cmp_ge_f32_e64 s[4:5], 0, v70
	s_nop 1
	v_cndmask_b32_e64 v67, v67, v68, s[4:5]
	v_cmp_lt_f32_e64 s[4:5], 0, v71
	s_nop 1
	v_cndmask_b32_e64 v67, v67, v69, s[4:5]
	v_mul_f32_e32 v68, 0x37800000, v67
	v_cndmask_b32_e32 v67, v67, v68, vcc
	v_cmp_class_f32_e32 vcc, v66, v238
	s_nop 1
	v_cndmask_b32_e32 v66, v67, v66, vcc
	v_div_scale_f32 v67, s[2:3], v66, v66, 1.0
	v_rcp_f32_e32 v68, v67
	v_div_scale_f32 v64, vcc, 1.0, v66, 1.0
	v_fma_f32 v65, -v67, v68, 1.0
	v_fmac_f32_e32 v68, v65, v68
	v_mul_f32_e32 v65, v64, v68
	v_fma_f32 v69, -v67, v65, v64
	v_fmac_f32_e32 v65, v69, v68
	v_fma_f32 v64, -v67, v65, v64
	v_div_fmas_f32 v64, v64, v68, v65
	v_div_fixup_f32 v64, v64, v66, 1.0
	v_pk_mul_f32 v[68:69], v[226:227], v[64:65] op_sel_hi:[1,0]
	v_pk_mul_f32 v[66:67], v[142:143], v[64:65] op_sel_hi:[1,0]
	v_pk_mul_f32 v[72:73], v[140:141], v[64:65] op_sel_hi:[1,0]
	v_pk_mul_f32 v[70:71], v[138:139], v[64:65] op_sel_hi:[1,0]
	v_pk_mul_f32 v[76:77], v[132:133], v[64:65] op_sel_hi:[1,0]
	v_pk_mul_f32 v[74:75], v[134:135], v[64:65] op_sel_hi:[1,0]
	v_pk_mul_f32 v[82:83], v[128:129], v[64:65] op_sel_hi:[1,0]
	v_pk_mul_f32 v[78:79], v[130:131], v[64:65] op_sel_hi:[1,0]
	v_pk_mul_f32 v[66:67], v[14:15], v[66:67]
	v_pk_mul_f32 v[64:65], v[12:13], v[68:69]
	v_pk_mul_f32 v[70:71], v[6:7], v[70:71]
	v_pk_mul_f32 v[68:69], v[4:5], v[72:73]
	v_pk_mul_f32 v[74:75], v[10:11], v[74:75]
	v_pk_mul_f32 v[72:73], v[8:9], v[76:77]
	v_pk_mul_f32 v[78:79], v[2:3], v[78:79]
	v_pk_mul_f32 v[76:77], v[0:1], v[82:83]
	global_store_dwordx4 v[80:81], v[64:67], off
	global_store_dwordx4 v[80:81], v[68:71], off offset:16
	global_store_dwordx4 v[80:81], v[72:75], off offset:512
	global_store_dwordx4 v[80:81], v[76:79], off offset:528
	s_waitcnt vmcnt(19)
	v_fmamk_f32 v64, v88, 0x3a800000, v237
	v_mul_f32_e32 v65, 0x4f800000, v64
	v_cmp_gt_f32_e32 vcc, s74, v64
	s_nop 1
	v_cndmask_b32_e32 v64, v64, v65, vcc
	v_sqrt_f32_e32 v65, v64
	s_nop 0
	v_add_u32_e32 v66, -1, v65
	v_add_u32_e32 v67, 1, v65
	v_fma_f32 v68, -v66, v65, v64
	v_fma_f32 v69, -v67, v65, v64
	v_cmp_ge_f32_e64 s[4:5], 0, v68
	s_nop 1
	v_cndmask_b32_e64 v65, v65, v66, s[4:5]
	v_cmp_lt_f32_e64 s[4:5], 0, v69
	s_nop 1
	v_cndmask_b32_e64 v65, v65, v67, s[4:5]
	v_mul_f32_e32 v66, 0x37800000, v65
	v_cndmask_b32_e32 v65, v65, v66, vcc
	v_cmp_class_f32_e32 vcc, v64, v238
	s_nop 1
	v_cndmask_b32_e32 v64, v65, v64, vcc
	v_div_scale_f32 v65, s[2:3], v64, v64, 1.0
	v_rcp_f32_e32 v66, v65
	v_div_scale_f32 v67, vcc, 1.0, v64, 1.0
	v_fma_f32 v68, -v65, v66, 1.0
	v_fmac_f32_e32 v66, v68, v66
	v_mul_f32_e32 v68, v67, v66
	v_fma_f32 v69, -v65, v68, v67
	v_fmac_f32_e32 v68, v69, v66
	v_fma_f32 v65, -v65, v68, v67
	v_div_fmas_f32 v65, v65, v66, v68
	v_div_fixup_f32 v64, v65, v64, 1.0
	v_pk_mul_f32 v[66:67], v[124:125], v[64:65] op_sel_hi:[1,0]
	v_pk_mul_f32 v[68:69], v[126:127], v[64:65] op_sel_hi:[1,0]
	v_pk_mul_f32 v[70:71], v[120:121], v[64:65] op_sel_hi:[1,0]
	v_pk_mul_f32 v[72:73], v[122:123], v[64:65] op_sel_hi:[1,0]
	v_pk_mul_f32 v[74:75], v[116:117], v[64:65] op_sel_hi:[1,0]
	v_pk_mul_f32 v[76:77], v[62:63], v[64:65] op_sel_hi:[1,0]
	v_pk_mul_f32 v[78:79], v[112:113], v[64:65] op_sel_hi:[1,0]
	v_pk_mul_f32 v[80:81], v[60:61], v[64:65] op_sel_hi:[1,0]
	v_pk_mul_f32 v[62:63], v[14:15], v[68:69]
	v_pk_mul_f32 v[60:61], v[12:13], v[66:67]
	v_pk_mul_f32 v[66:67], v[6:7], v[72:73]
	v_pk_mul_f32 v[64:65], v[4:5], v[70:71]
	v_pk_mul_f32 v[70:71], v[10:11], v[76:77]
	v_pk_mul_f32 v[68:69], v[8:9], v[74:75]
	v_pk_mul_f32 v[74:75], v[2:3], v[80:81]
	v_pk_mul_f32 v[72:73], v[0:1], v[78:79]
	global_store_dwordx4 v[192:193], v[60:63], off
	global_store_dwordx4 v[192:193], v[64:67], off offset:16
	global_store_dwordx4 v[192:193], v[68:71], off offset:512
	global_store_dwordx4 v[192:193], v[72:75], off offset:528
	s_waitcnt vmcnt(22)
; #define PG8_BAR __builtin_amdgcn_s_barrier()
;     __device__ __forceinline__ void operator()(f32x4 (&acc)[2][2][4][2], const Unit& u, int wr, int wc, int fr, int fq) const {
;     ...
;         for (int ai = 0; ai < 2; ++ai)
; #pragma unroll
;             for (int m = 0; m < 4; ++m) {
;                 const int row = row0 + ai * HALF + m * 16;
;                 const float ss = __hip_atomic_load(SS + row, __ATOMIC_RELAXED, __HIP_MEMORY_SCOPE_AGENT);
;                 const float rstd = 1.0f / sqrtf(ss * (1.f / 1024.f) + 1e-6f);
;                 float qs = 0.f;
;                 if constexpr (!FINAL) {
;                     const float am = __uint_as_float(__hip_atomic_load(AM + row, __ATOMIC_RELAXED, __HIP_MEMORY_SCOPE_AGENT));
;                     qs = am > 0.f ? 127.f / am : 0.f;
;                     if (u.pn == 0 && wc == 0 && fq == 0) SH[row] = am * rstd * (1.f / 127.f);
;                 }
; #pragma unroll
;                 for (int bj = 0; bj < 2; ++bj) {
;                     const size_t off = (size_t)row * 1024 + col0 + bj * HALF;
;                     const f32x4 y0 = acc[ai][bj][m][0] * rstd * gv[bj][0], y1 = acc[ai][bj][m][1] * rstd * gv[bj][1];
;                     if constexpr (FINAL) { *(f32x4*)(out + off) = y0; *(f32x4*)(out + off + 4) = y1; }
; template <class Epi, class Sched, class Gemm, bool ALIGN_EPI = false, bool SP2 = false>
; __device__ __forceinline__ void gemm_phase(PG8_LAS unsigned char* lds, const Gemm g, const Sched& S, const Epi& E) {
;     ...
;         if (!has_next) break;
;         if constexpr (!epi_chain<Epi>::value) {
; #pragma unroll
;         for (int a = 0; a < 2; ++a)
; #pragma unroll
;             for (int b = 0; b < 2; ++b)
; #pragma unroll
;                 for (int m = 0; m < 4; ++m)
; #pragma unroll
;                     for (int n = 0; n < 2; ++n) acc[a][b][m][n] = (f32x4){0.f, 0.f, 0.f, 0.f};
;         }
;         cur = nxt; cA = nA; cB = nB; ++ui;
;         if constexpr (ALIGN_EPI) { if (wr == 1) PG8_BAR; }
	v_fmamk_f32 v60, v89, 0x3a800000, v237
	v_mul_f32_e32 v61, 0x4f800000, v60
	v_cmp_gt_f32_e32 vcc, s74, v60
	s_nop 1
	v_cndmask_b32_e32 v60, v60, v61, vcc
	v_sqrt_f32_e32 v61, v60
	s_nop 0
	v_add_u32_e32 v62, -1, v61
	v_add_u32_e32 v63, 1, v61
	v_fma_f32 v64, -v62, v61, v60
	v_fma_f32 v65, -v63, v61, v60
	v_cmp_ge_f32_e64 s[4:5], 0, v64
	s_nop 1
	v_cndmask_b32_e64 v61, v61, v62, s[4:5]
	v_cmp_lt_f32_e64 s[4:5], 0, v65
	s_nop 1
	v_cndmask_b32_e64 v61, v61, v63, s[4:5]
	v_mul_f32_e32 v62, 0x37800000, v61
	v_cndmask_b32_e32 v61, v61, v62, vcc
	v_cmp_class_f32_e32 vcc, v60, v238
	s_nop 1
	v_cndmask_b32_e32 v60, v61, v60, vcc
	v_div_scale_f32 v61, s[2:3], v60, v60, 1.0
	v_rcp_f32_e32 v62, v61
	v_div_scale_f32 v63, vcc, 1.0, v60, 1.0
	v_fma_f32 v64, -v61, v62, 1.0
	v_fmac_f32_e32 v62, v64, v62
	v_mul_f32_e32 v64, v63, v62
	v_fma_f32 v65, -v61, v64, v63
	v_fmac_f32_e32 v64, v65, v62
	v_fma_f32 v61, -v61, v64, v63
	v_div_fmas_f32 v61, v61, v62, v64
	v_div_fixup_f32 v60, v61, v60, 1.0
	v_pk_mul_f32 v[62:63], v[108:109], v[60:61] op_sel_hi:[1,0]
	v_pk_mul_f32 v[58:59], v[58:59], v[60:61] op_sel_hi:[1,0]
	v_pk_mul_f32 v[64:65], v[104:105], v[60:61] op_sel_hi:[1,0]
	v_pk_mul_f32 v[56:57], v[56:57], v[60:61] op_sel_hi:[1,0]
	v_pk_mul_f32 v[66:67], v[52:53], v[60:61] op_sel_hi:[1,0]
	v_pk_mul_f32 v[68:69], v[46:47], v[60:61] op_sel_hi:[1,0]
	v_pk_mul_f32 v[70:71], v[54:55], v[60:61] op_sel_hi:[1,0]
	v_pk_mul_f32 v[60:61], v[44:45], v[60:61] op_sel_hi:[1,0]
	v_pk_mul_f32 v[46:47], v[14:15], v[58:59]
	v_pk_mul_f32 v[44:45], v[12:13], v[62:63]
	v_pk_mul_f32 v[54:55], v[6:7], v[56:57]
	v_pk_mul_f32 v[52:53], v[4:5], v[64:65]
	v_pk_mul_f32 v[58:59], v[10:11], v[68:69]
	v_pk_mul_f32 v[56:57], v[8:9], v[66:67]
	v_pk_mul_f32 v[62:63], v[2:3], v[60:61]
	v_pk_mul_f32 v[60:61], v[0:1], v[70:71]
	global_store_dwordx4 v[168:169], v[44:47], off
	global_store_dwordx4 v[168:169], v[52:55], off offset:16
	global_store_dwordx4 v[168:169], v[56:59], off offset:512
	global_store_dwordx4 v[168:169], v[60:63], off offset:528
	s_waitcnt vmcnt(25)
	v_fmamk_f32 v44, v90, 0x3a800000, v237
	v_mul_f32_e32 v45, 0x4f800000, v44
	v_cmp_gt_f32_e32 vcc, s74, v44
	s_nop 1
	v_cndmask_b32_e32 v44, v44, v45, vcc
	v_sqrt_f32_e32 v45, v44
	s_nop 0
	v_add_u32_e32 v46, -1, v45
	v_add_u32_e32 v47, 1, v45
	v_fma_f32 v52, -v46, v45, v44
	v_fma_f32 v53, -v47, v45, v44
	v_cmp_ge_f32_e64 s[4:5], 0, v52
	s_nop 1
	v_cndmask_b32_e64 v45, v45, v46, s[4:5]
	v_cmp_lt_f32_e64 s[4:5], 0, v53
	s_nop 1
	v_cndmask_b32_e64 v45, v45, v47, s[4:5]
	v_mul_f32_e32 v46, 0x37800000, v45
	v_cndmask_b32_e32 v45, v45, v46, vcc
	v_cmp_class_f32_e32 vcc, v44, v238
	s_nop 1
	v_cndmask_b32_e32 v44, v45, v44, vcc
	v_div_scale_f32 v45, s[2:3], v44, v44, 1.0
	v_rcp_f32_e32 v46, v45
	v_div_scale_f32 v47, vcc, 1.0, v44, 1.0
	v_fma_f32 v52, -v45, v46, 1.0
	v_fmac_f32_e32 v46, v52, v46
	v_mul_f32_e32 v52, v47, v46
	v_fma_f32 v53, -v45, v52, v47
	v_fmac_f32_e32 v52, v53, v46
	v_fma_f32 v45, -v45, v52, v47
	v_div_fmas_f32 v45, v45, v46, v52
	v_div_fixup_f32 v44, v45, v44, 1.0
	v_pk_mul_f32 v[46:47], v[48:49], v[44:45] op_sel_hi:[1,0]
	v_pk_mul_f32 v[42:43], v[42:43], v[44:45] op_sel_hi:[1,0]
	v_pk_mul_f32 v[48:49], v[50:51], v[44:45] op_sel_hi:[1,0]
	v_pk_mul_f32 v[40:41], v[40:41], v[44:45] op_sel_hi:[1,0]
	v_pk_mul_f32 v[50:51], v[36:37], v[44:45] op_sel_hi:[1,0]
	v_pk_mul_f32 v[52:53], v[34:35], v[44:45] op_sel_hi:[1,0]
	v_pk_mul_f32 v[54:55], v[38:39], v[44:45] op_sel_hi:[1,0]
	v_pk_mul_f32 v[44:45], v[32:33], v[44:45] op_sel_hi:[1,0]
	v_pk_mul_f32 v[34:35], v[14:15], v[42:43]
	v_pk_mul_f32 v[32:33], v[12:13], v[46:47]
	v_pk_mul_f32 v[38:39], v[6:7], v[40:41]
	v_pk_mul_f32 v[36:37], v[4:5], v[48:49]
	v_pk_mul_f32 v[42:43], v[10:11], v[52:53]
	v_pk_mul_f32 v[40:41], v[8:9], v[50:51]
	v_pk_mul_f32 v[46:47], v[2:3], v[44:45]
	v_pk_mul_f32 v[44:45], v[0:1], v[54:55]
	global_store_dwordx4 v[152:153], v[32:35], off
	global_store_dwordx4 v[152:153], v[36:39], off offset:16
	global_store_dwordx4 v[152:153], v[40:43], off offset:512
	global_store_dwordx4 v[152:153], v[44:47], off offset:528
	s_waitcnt vmcnt(28)
	v_fmamk_f32 v32, v91, 0x3a800000, v237
	v_mul_f32_e32 v33, 0x4f800000, v32
	v_cmp_gt_f32_e32 vcc, s74, v32
	s_nop 1
	v_cndmask_b32_e32 v32, v32, v33, vcc
	v_sqrt_f32_e32 v33, v32
	s_nop 0
	v_add_u32_e32 v34, -1, v33
	v_add_u32_e32 v35, 1, v33
	v_fma_f32 v36, -v34, v33, v32
	v_fma_f32 v37, -v35, v33, v32
	v_cmp_ge_f32_e64 s[4:5], 0, v36
	s_nop 1
	v_cndmask_b32_e64 v33, v33, v34, s[4:5]
	v_cmp_lt_f32_e64 s[4:5], 0, v37
	s_nop 1
	v_cndmask_b32_e64 v33, v33, v35, s[4:5]
	v_mul_f32_e32 v34, 0x37800000, v33
	v_cndmask_b32_e32 v33, v33, v34, vcc
	v_cmp_class_f32_e32 vcc, v32, v238
	s_nop 1
	v_cndmask_b32_e32 v32, v33, v32, vcc
	v_div_scale_f32 v33, s[2:3], v32, v32, 1.0
	v_rcp_f32_e32 v34, v33
	v_div_scale_f32 v35, vcc, 1.0, v32, 1.0
	v_fma_f32 v36, -v33, v34, 1.0
	v_fmac_f32_e32 v34, v36, v34
	v_mul_f32_e32 v36, v35, v34
	v_fma_f32 v37, -v33, v36, v35
	v_fmac_f32_e32 v36, v37, v34
	v_fma_f32 v33, -v33, v36, v35
	v_div_fmas_f32 v33, v33, v34, v36
	v_div_fixup_f32 v32, v33, v32, 1.0
	v_pk_mul_f32 v[18:19], v[18:19], v[32:33] op_sel_hi:[1,0]
	v_pk_mul_f32 v[16:17], v[16:17], v[32:33] op_sel_hi:[1,0]
	s_andn2_b64 vcc, exec, s[0:1]
	v_pk_mul_f32 v[22:23], v[22:23], v[32:33] op_sel_hi:[1,0]
	v_pk_mul_f32 v[20:21], v[20:21], v[32:33] op_sel_hi:[1,0]
	v_pk_mul_f32 v[26:27], v[26:27], v[32:33] op_sel_hi:[1,0]
	v_pk_mul_f32 v[24:25], v[24:25], v[32:33] op_sel_hi:[1,0]
	v_pk_mul_f32 v[30:31], v[30:31], v[32:33] op_sel_hi:[1,0]
	v_pk_mul_f32 v[28:29], v[28:29], v[32:33] op_sel_hi:[1,0]
	v_pk_mul_f32 v[14:15], v[14:15], v[16:17]
	v_pk_mul_f32 v[12:13], v[12:13], v[18:19]
	s_mov_b64 s[0:1], -1
	v_pk_mul_f32 v[6:7], v[6:7], v[20:21]
	v_pk_mul_f32 v[4:5], v[4:5], v[22:23]
	v_pk_mul_f32 v[10:11], v[10:11], v[24:25]
	v_pk_mul_f32 v[8:9], v[8:9], v[26:27]
	v_pk_mul_f32 v[2:3], v[2:3], v[28:29]
	v_pk_mul_f32 v[0:1], v[0:1], v[30:31]
	global_store_dwordx4 v[136:137], v[12:15], off
	global_store_dwordx4 v[136:137], v[4:7], off offset:16
	global_store_dwordx4 v[136:137], v[8:11], off offset:512
	global_store_dwordx4 v[136:137], v[0:3], off offset:528
	s_cbranch_vccnz .LBB0_2722
	s_andn2_b64 vcc, exec, s[12:13]
	s_cbranch_vccnz .LBB0_2721
	s_barrier
	s_branch .LBB0_2721

; __device__ __forceinline__ unsigned xb_ld(unsigned* p)              { return __hip_atomic_load(p, __ATOMIC_RELAXED, __HIP_MEMORY_SCOPE_AGENT); }
; __device__ __forceinline__ unsigned xb_add(unsigned* p, unsigned v) { return __hip_atomic_fetch_add(p, v, __ATOMIC_RELAXED, __HIP_MEMORY_SCOPE_AGENT); }
; #define XB_SPIN(cond, bar) do { unsigned _sp = 0; while (cond) { __builtin_amdgcn_s_sleep(1); \
;     if ((++_sp & 255u) == 0u) { if (xb_ld(&(bar)[XB_TMO])) break; if (_sp > XB_SPIN_CAP) { atomicAdd(&(bar)[XB_TMO], 1u); break; } } } } while (0)
; __device__ __forceinline__ void xcd_barrier(const XcdBarrier& b) {
;     asm volatile("s_waitcnt vmcnt(0)" ::: "memory");
;     __syncthreads();
;     if (threadIdx.x == 0) {
;         unsigned* bar = b.bar;
;         __builtin_amdgcn_s_waitcnt(0);
;         unsigned nloc = b.st[0], nx = b.st[1];
;         if (nloc == 0u) { xcd_barrier_complete(bar, b.x, nloc, nx); b.st[0] = nloc; b.st[1] = nx; }
;         const unsigned old = xb_add(&bar[XB_XSUB(b.x)], 1u);
;         const unsigned gen = old / nloc;
;         if (old + 1u == (gen + 1u) * nloc) {
;             __builtin_amdgcn_fence(__ATOMIC_RELEASE, "agent");
;             asm volatile("s_waitcnt vmcnt(0)" ::: "memory");
;             const unsigned og = xb_add(&bar[XB_TOP], 1u);
;             const unsigned tg = og / nx;
;             if (og + 1u == (tg + 1u) * nx) xb_add(&bar[XB_TOPGEN], 1u);
;             else XB_SPIN(xb_ld(&bar[XB_TOPGEN]) == tg, bar);
;             __builtin_amdgcn_fence(__ATOMIC_ACQUIRE, "agent");
;             xb_add(&bar[XB_XGEN(b.x)], 1u);
;             asm volatile("s_waitcnt vmcnt(0)" ::: "memory");
;         } else {
;             XB_SPIN(xb_ld(&bar[XB_XGEN(b.x)]) == gen, bar);
;             __builtin_amdgcn_fence(__ATOMIC_ACQUIRE, "agent");
;             asm volatile("s_waitcnt vmcnt(0)" ::: "memory");
;         }
.LBB0_2789:
	s_or_b64 exec, exec, s[6:7]
	v_cvt_f32_u32_e32 v4, v2
	s_waitcnt vmcnt(0)
	v_readfirstlane_b32 s4, v3
	v_sub_u32_e32 v3, 0, v2
	v_rcp_iflag_f32_e32 v4, v4
	v_add_u32_e32 v5, s4, v1
	v_mul_f32_e32 v4, 0x4f7ffffe, v4
	v_cvt_u32_f32_e32 v4, v4
	v_mul_lo_u32 v1, v3, v4
	v_mul_hi_u32 v1, v4, v1
	v_add_u32_e32 v1, v4, v1
	v_mul_hi_u32 v1, v5, v1
	v_mul_lo_u32 v3, v1, v2
	v_sub_u32_e32 v3, v5, v3
	v_add_u32_e32 v4, 1, v1
	v_cmp_ge_u32_e32 vcc, v3, v2
	s_nop 1
	v_cndmask_b32_e32 v1, v1, v4, vcc
	v_sub_u32_e32 v4, v3, v2
	v_cndmask_b32_e32 v3, v3, v4, vcc
	v_add_u32_e32 v4, 1, v1
	v_cmp_ge_u32_e32 vcc, v3, v2
	v_add_u32_e32 v3, 1, v5
	s_nop 0
	v_cndmask_b32_e32 v1, v1, v4, vcc
	v_mul_lo_u32 v4, v2, v1
	v_add_u32_e32 v2, v4, v2
	v_cmp_ne_u32_e32 vcc, v3, v2
	s_and_saveexec_b64 s[4:5], vcc
	s_xor_b64 s[4:5], exec, s[4:5]
	s_cbranch_execz .LBB0_2803
	s_waitcnt lgkmcnt(0)
	v_mov_b32_e32 v0, 0x3100
	global_load_dword v0, v0, s[84:85] offset:1024 sc1
	s_add_u32 s8, s84, 0x3500
	s_addc_u32 s9, s85, 0
	s_waitcnt vmcnt(0)
	v_cmp_eq_u32_e32 vcc, v0, v1
	s_and_saveexec_b64 s[6:7], vcc
	s_cbranch_execz .LBB0_2802
	s_mov_b32 s20, 1
	s_mov_b64 s[10:11], 0
	v_mov_b32_e32 v0, 0
	s_branch .LBB0_2793
